# scan: y/sa products as one accumulation chain each (two fewer packed adds per step)
# speedup vs baseline: 1.0169x; 1.0006x over previous
; #define LAS __attribute__((address_space(3)))
; __device__ __forceinline__ float red8(float x) { x += dpp_mov<0xB1>(x); x += dpp_mov<0x4E>(x); x += dpp_mov<0x141>(x); return x; }
; __device__ __forceinline__ void scan_phase(const KP& P, LAS unsigned char* lds, const int tid, const int bx, const int G) {
;     ...
;         for (int c = 0; c < NCH; ++c) {
;             if (c + 1 < NCH) SC_LOAD(c + 1);
;             const LAS float* cb = buf + (c & 1) * 12288 + kc * 8;
; #pragma unroll 16
;             for (int s = 0; s < 32; ++s) {
;                 const LAS float* p = cb + s * 384;
;                 const f32x4 w0 = *(const LAS f32x4*)(p), w1 = *(const LAS f32x4*)(p + 4);
;                 const f32x4 k0 = *(const LAS f32x4*)(p + 64), k1 = *(const LAS f32x4*)(p + 68);
;                 const f32x4 a0 = *(const LAS f32x4*)(p + 128), a1 = *(const LAS f32x4*)(p + 132);
;                 const f32x4 b0 = *(const LAS f32x4*)(p + 192), b1 = *(const LAS f32x4*)(p + 196);
;                 const f32x4 r0 = *(const LAS f32x4*)(p + 256), r1 = *(const LAS f32x4*)(p + 260);
;                 const float vv = buf[(c & 1) * 12288 + s * 384 + 320 + v];
;                 f32x2 sa2 = S[0] * (f32x2){a0.x, a0.y};
;                 sa2 += S[1] * (f32x2){a0.z, a0.w}; sa2 += S[2] * (f32x2){a1.x, a1.y}; sa2 += S[3] * (f32x2){a1.z, a1.w};
;                 const float sa = red8(sa2.x + sa2.y);
;                 const f32x2 sav = {sa, sa}, vv2 = {vv, vv};
;                 S[0] = S[0] * (f32x2){w0.x, w0.y} + sav * (f32x2){b0.x, b0.y} + vv2 * (f32x2){k0.x, k0.y};
;                 S[1] = S[1] * (f32x2){w0.z, w0.w} + sav * (f32x2){b0.z, b0.w} + vv2 * (f32x2){k0.z, k0.w};
;                 S[2] = S[2] * (f32x2){w1.x, w1.y} + sav * (f32x2){b1.x, b1.y} + vv2 * (f32x2){k1.x, k1.y};
;                 S[3] = S[3] * (f32x2){w1.z, w1.w} + sav * (f32x2){b1.z, b1.w} + vv2 * (f32x2){k1.z, k1.w};
;                 f32x2 y2 = S[0] * (f32x2){r0.x, r0.y};
;                 y2 += S[1] * (f32x2){r0.z, r0.w}; y2 += S[2] * (f32x2){r1.x, r1.y}; y2 += S[3] * (f32x2){r1.z, r1.w};
;                 const float y = red8(y2.x + y2.y);
;                 if (kc == 0) ybuf[s * 64 + v] = y;
.Lscan_compute:
	s_bitcmp1_b32 s3, 0
	s_cselect_b32 s0, 0xc000, 0
	v_lshlrev_b32_e32 v45, 1, v58
	v_or_b32_e32 v44, s0, v56
	v_add_u32_e32 v46, s0, v45
	v_add_u32_e32 v46, 0x500, v46
	v_add_u32_e32 v45, 0x18000, v45
	s_mov_b64 s[0:1], exec
	ds_read_b128 v[148:151], v44 offset:512
	ds_read_b128 v[152:155], v44 offset:528
	ds_read_b128 v[156:159], v44 offset:2048
	ds_read_b128 v[160:163], v44 offset:2064
	ds_read_b128 v[120:123], v44 offset:256
	ds_read_b128 v[124:127], v44 offset:272
	ds_read_b128 v[128:131], v44 offset:768
	ds_read_b128 v[132:135], v44 offset:784
	ds_read_b128 v[136:139], v44 offset:1024
	ds_read_b128 v[140:143], v44 offset:1040
	ds_read_b64 v[144:145], v46 offset:0
	ds_read_b128 v[112:115], v44 offset:47616
	ds_read_b128 v[116:119], v44 offset:47632
	ds_read_b128 v[62:65], v44 offset:3584
	ds_read_b128 v[66:69], v44 offset:3600
	ds_read_b128 v[70:73], v44 offset:1792
	ds_read_b128 v[74:77], v44 offset:1808
	ds_read_b128 v[78:81], v44 offset:2304
	ds_read_b128 v[82:85], v44 offset:2320
	ds_read_b128 v[86:89], v44 offset:2560
	ds_read_b128 v[90:93], v44 offset:2576
	ds_read_b64 v[146:147], v46 offset:1536
	s_waitcnt lgkmcnt(15)
	v_pk_mul_f32 v[50:51], v[96:97], v[148:149] op_sel:[0,0] op_sel_hi:[1,0]
	s_nop 0
	v_pk_fma_f32 v[50:51], v[98:99], v[148:149], v[50:51] op_sel:[0,1,0] op_sel_hi:[1,1,1]
	s_nop 0
	v_pk_fma_f32 v[50:51], v[100:101], v[150:151], v[50:51] op_sel:[0,0,0] op_sel_hi:[1,0,1]
	s_nop 0
	v_pk_fma_f32 v[50:51], v[102:103], v[150:151], v[50:51] op_sel:[0,1,0] op_sel_hi:[1,1,1]
	s_nop 0
	v_pk_fma_f32 v[50:51], v[104:105], v[152:153], v[50:51] op_sel:[0,0,0] op_sel_hi:[1,0,1]
	s_nop 0
	v_pk_fma_f32 v[50:51], v[106:107], v[152:153], v[50:51] op_sel:[0,1,0] op_sel_hi:[1,1,1]
	s_nop 0
	v_pk_fma_f32 v[50:51], v[108:109], v[154:155], v[50:51] op_sel:[0,0,0] op_sel_hi:[1,0,1]
	s_nop 0
	v_pk_fma_f32 v[50:51], v[110:111], v[154:155], v[50:51] op_sel:[0,1,0] op_sel_hi:[1,1,1]
	s_nop 0
	s_waitcnt lgkmcnt(9)
	ds_read_b128 v[168:171], v44 offset:3328
	ds_read_b128 v[172:175], v44 offset:3344
	ds_read_b128 v[176:179], v44 offset:3840
	ds_read_b128 v[180:183], v44 offset:3856
	ds_read_b128 v[184:187], v44 offset:4096
	ds_read_b128 v[188:191], v44 offset:4112
	ds_read_b64 v[192:193], v46 offset:3072
	ds_read_b128 v[148:151], v44 offset:5120
	ds_read_b128 v[152:155], v44 offset:5136
	v_add_f32_dpp v50, v50, v50 quad_perm:[1,0,3,2] row_mask:0xf bank_mask:0xf bound_ctrl:1
	v_add_f32_dpp v51, v51, v51 quad_perm:[1,0,3,2] row_mask:0xf bank_mask:0xf bound_ctrl:1
	v_pk_fma_f32 v[96:97], v[144:145], v[120:121], v[96:97] op_sel:[0,0,0] op_sel_hi:[1,0,1]
	v_pk_fma_f32 v[98:99], v[144:145], v[120:121], v[98:99] op_sel:[0,1,0] op_sel_hi:[1,1,1]
	v_pk_fma_f32 v[100:101], v[144:145], v[122:123], v[100:101] op_sel:[0,0,0] op_sel_hi:[1,0,1]
	v_add_f32_dpp v50, v50, v50 quad_perm:[2,3,0,1] row_mask:0xf bank_mask:0xf bound_ctrl:1
	v_add_f32_dpp v51, v51, v51 quad_perm:[2,3,0,1] row_mask:0xf bank_mask:0xf bound_ctrl:1
	v_pk_fma_f32 v[102:103], v[144:145], v[122:123], v[102:103] op_sel:[0,1,0] op_sel_hi:[1,1,1]
	v_pk_fma_f32 v[104:105], v[144:145], v[124:125], v[104:105] op_sel:[0,0,0] op_sel_hi:[1,0,1]
	v_pk_fma_f32 v[106:107], v[144:145], v[124:125], v[106:107] op_sel:[0,1,0] op_sel_hi:[1,1,1]
	v_add_f32_dpp v50, v50, v50 row_half_mirror row_mask:0xf bank_mask:0xf bound_ctrl:1
	v_add_f32_dpp v51, v51, v51 row_half_mirror row_mask:0xf bank_mask:0xf bound_ctrl:1
	v_pk_fma_f32 v[108:109], v[144:145], v[126:127], v[108:109] op_sel:[0,0,0] op_sel_hi:[1,0,1]
	v_pk_fma_f32 v[110:111], v[144:145], v[126:127], v[110:111] op_sel:[0,1,0] op_sel_hi:[1,1,1]
	s_nop 0
	v_pk_fma_f32 v[96:97], v[50:51], v[128:129], v[96:97] op_sel:[0,0,0] op_sel_hi:[1,0,1]
	v_pk_fma_f32 v[98:99], v[50:51], v[128:129], v[98:99] op_sel:[0,1,0] op_sel_hi:[1,1,1]
	v_pk_fma_f32 v[100:101], v[50:51], v[130:131], v[100:101] op_sel:[0,0,0] op_sel_hi:[1,0,1]
	v_pk_fma_f32 v[102:103], v[50:51], v[130:131], v[102:103] op_sel:[0,1,0] op_sel_hi:[1,1,1]
	v_pk_fma_f32 v[104:105], v[50:51], v[132:133], v[104:105] op_sel:[0,0,0] op_sel_hi:[1,0,1]
	v_pk_fma_f32 v[106:107], v[50:51], v[132:133], v[106:107] op_sel:[0,1,0] op_sel_hi:[1,1,1]
	v_pk_fma_f32 v[108:109], v[50:51], v[134:135], v[108:109] op_sel:[0,0,0] op_sel_hi:[1,0,1]
	v_pk_fma_f32 v[110:111], v[50:51], v[134:135], v[110:111] op_sel:[0,1,0] op_sel_hi:[1,1,1]
	v_pk_mul_f32 v[48:49], v[96:97], v[136:137] op_sel:[0,0] op_sel_hi:[1,0]
	v_pk_mul_f32 v[50:51], v[96:97], v[156:157] op_sel:[0,0] op_sel_hi:[1,0]
	v_pk_fma_f32 v[48:49], v[98:99], v[136:137], v[48:49] op_sel:[0,1,0] op_sel_hi:[1,1,1]
	v_pk_fma_f32 v[50:51], v[98:99], v[156:157], v[50:51] op_sel:[0,1,0] op_sel_hi:[1,1,1]
	v_pk_fma_f32 v[48:49], v[100:101], v[138:139], v[48:49] op_sel:[0,0,0] op_sel_hi:[1,0,1]
	v_pk_fma_f32 v[50:51], v[100:101], v[158:159], v[50:51] op_sel:[0,0,0] op_sel_hi:[1,0,1]
	v_pk_fma_f32 v[48:49], v[102:103], v[138:139], v[48:49] op_sel:[0,1,0] op_sel_hi:[1,1,1]
	v_pk_fma_f32 v[50:51], v[102:103], v[158:159], v[50:51] op_sel:[0,1,0] op_sel_hi:[1,1,1]
	v_pk_fma_f32 v[48:49], v[104:105], v[140:141], v[48:49] op_sel:[0,0,0] op_sel_hi:[1,0,1]
	v_pk_fma_f32 v[50:51], v[104:105], v[160:161], v[50:51] op_sel:[0,0,0] op_sel_hi:[1,0,1]
	v_pk_fma_f32 v[48:49], v[106:107], v[140:141], v[48:49] op_sel:[0,1,0] op_sel_hi:[1,1,1]
	v_pk_fma_f32 v[50:51], v[106:107], v[160:161], v[50:51] op_sel:[0,1,0] op_sel_hi:[1,1,1]
	v_pk_fma_f32 v[48:49], v[108:109], v[142:143], v[48:49] op_sel:[0,0,0] op_sel_hi:[1,0,1]
	v_pk_fma_f32 v[50:51], v[108:109], v[162:163], v[50:51] op_sel:[0,0,0] op_sel_hi:[1,0,1]
	v_pk_fma_f32 v[48:49], v[110:111], v[142:143], v[48:49] op_sel:[0,1,0] op_sel_hi:[1,1,1]
	v_pk_fma_f32 v[50:51], v[110:111], v[162:163], v[50:51] op_sel:[0,1,0] op_sel_hi:[1,1,1]
	s_waitcnt lgkmcnt(9)
; #define LAS __attribute__((address_space(3)))
; __device__ __forceinline__ float red8(float x) { x += dpp_mov<0xB1>(x); x += dpp_mov<0x4E>(x); x += dpp_mov<0x141>(x); return x; }
; __device__ __forceinline__ void scan_phase(const KP& P, LAS unsigned char* lds, const int tid, const int bx, const int G) {
;     ...
;             for (int s = 0; s < 32; ++s) {
;                 const LAS float* p = cb + s * 384;
;                 const f32x4 w0 = *(const LAS f32x4*)(p), w1 = *(const LAS f32x4*)(p + 4);
;                 const f32x4 k0 = *(const LAS f32x4*)(p + 64), k1 = *(const LAS f32x4*)(p + 68);
;                 const f32x4 a0 = *(const LAS f32x4*)(p + 128), a1 = *(const LAS f32x4*)(p + 132);
;                 const f32x4 b0 = *(const LAS f32x4*)(p + 192), b1 = *(const LAS f32x4*)(p + 196);
;                 const f32x4 r0 = *(const LAS f32x4*)(p + 256), r1 = *(const LAS f32x4*)(p + 260);
;                 const float vv = buf[(c & 1) * 12288 + s * 384 + 320 + v];
;                 f32x2 sa2 = S[0] * (f32x2){a0.x, a0.y};
;                 sa2 += S[1] * (f32x2){a0.z, a0.w}; sa2 += S[2] * (f32x2){a1.x, a1.y}; sa2 += S[3] * (f32x2){a1.z, a1.w};
;                 const float sa = red8(sa2.x + sa2.y);
;                 const f32x2 sav = {sa, sa}, vv2 = {vv, vv};
;                 S[0] = S[0] * (f32x2){w0.x, w0.y} + sav * (f32x2){b0.x, b0.y} + vv2 * (f32x2){k0.x, k0.y};
;                 S[1] = S[1] * (f32x2){w0.z, w0.w} + sav * (f32x2){b0.z, b0.w} + vv2 * (f32x2){k0.z, k0.w};
;                 S[2] = S[2] * (f32x2){w1.x, w1.y} + sav * (f32x2){b1.x, b1.y} + vv2 * (f32x2){k1.x, k1.y};
;                 S[3] = S[3] * (f32x2){w1.z, w1.w} + sav * (f32x2){b1.z, b1.w} + vv2 * (f32x2){k1.z, k1.w};
;                 f32x2 y2 = S[0] * (f32x2){r0.x, r0.y};
;                 y2 += S[1] * (f32x2){r0.z, r0.w}; y2 += S[2] * (f32x2){r1.x, r1.y}; y2 += S[3] * (f32x2){r1.z, r1.w};
;                 const float y = red8(y2.x + y2.y);
;                 if (kc == 0) ybuf[s * 64 + v] = y;
	ds_read_b128 v[120:123], v44 offset:4864
	ds_read_b128 v[124:127], v44 offset:4880
	ds_read_b128 v[128:131], v44 offset:5376
	ds_read_b128 v[132:135], v44 offset:5392
	ds_read_b128 v[136:139], v44 offset:5632
	ds_read_b128 v[140:143], v44 offset:5648
	ds_read_b64 v[144:145], v46 offset:4608
	ds_read_b128 v[156:159], v44 offset:6656
	ds_read_b128 v[160:163], v44 offset:6672
	v_add_f32_dpp v48, v48, v48 quad_perm:[1,0,3,2] row_mask:0xf bank_mask:0xf bound_ctrl:1
	v_add_f32_dpp v49, v49, v49 quad_perm:[1,0,3,2] row_mask:0xf bank_mask:0xf bound_ctrl:1
	v_add_f32_dpp v50, v50, v50 quad_perm:[1,0,3,2] row_mask:0xf bank_mask:0xf bound_ctrl:1
	v_add_f32_dpp v51, v51, v51 quad_perm:[1,0,3,2] row_mask:0xf bank_mask:0xf bound_ctrl:1
	v_pk_fma_f32 v[96:97], v[146:147], v[70:71], v[96:97] op_sel:[0,0,0] op_sel_hi:[1,0,1]
	v_pk_fma_f32 v[98:99], v[146:147], v[70:71], v[98:99] op_sel:[0,1,0] op_sel_hi:[1,1,1]
	v_pk_fma_f32 v[100:101], v[146:147], v[72:73], v[100:101] op_sel:[0,0,0] op_sel_hi:[1,0,1]
	v_add_f32_dpp v48, v48, v48 quad_perm:[2,3,0,1] row_mask:0xf bank_mask:0xf bound_ctrl:1
	v_add_f32_dpp v49, v49, v49 quad_perm:[2,3,0,1] row_mask:0xf bank_mask:0xf bound_ctrl:1
	v_add_f32_dpp v50, v50, v50 quad_perm:[2,3,0,1] row_mask:0xf bank_mask:0xf bound_ctrl:1
	v_add_f32_dpp v51, v51, v51 quad_perm:[2,3,0,1] row_mask:0xf bank_mask:0xf bound_ctrl:1
	v_pk_fma_f32 v[102:103], v[146:147], v[72:73], v[102:103] op_sel:[0,1,0] op_sel_hi:[1,1,1]
	v_pk_fma_f32 v[104:105], v[146:147], v[74:75], v[104:105] op_sel:[0,0,0] op_sel_hi:[1,0,1]
	v_pk_fma_f32 v[106:107], v[146:147], v[74:75], v[106:107] op_sel:[0,1,0] op_sel_hi:[1,1,1]
	v_add_f32_dpp v48, v48, v48 row_half_mirror row_mask:0xf bank_mask:0xf bound_ctrl:1
	v_add_f32_dpp v49, v49, v49 row_half_mirror row_mask:0xf bank_mask:0xf bound_ctrl:1
	v_add_f32_dpp v50, v50, v50 row_half_mirror row_mask:0xf bank_mask:0xf bound_ctrl:1
	v_add_f32_dpp v51, v51, v51 row_half_mirror row_mask:0xf bank_mask:0xf bound_ctrl:1
	v_pk_fma_f32 v[108:109], v[146:147], v[76:77], v[108:109] op_sel:[0,0,0] op_sel_hi:[1,0,1]
	s_mov_b64 exec, s[10:11]
	ds_write_b64 v45, v[48:49] offset:0
	s_mov_b64 exec, s[0:1]
	v_pk_fma_f32 v[110:111], v[146:147], v[76:77], v[110:111] op_sel:[0,1,0] op_sel_hi:[1,1,1]
	s_nop 0
	v_pk_fma_f32 v[96:97], v[50:51], v[78:79], v[96:97] op_sel:[0,0,0] op_sel_hi:[1,0,1]
	v_pk_fma_f32 v[98:99], v[50:51], v[78:79], v[98:99] op_sel:[0,1,0] op_sel_hi:[1,1,1]
	v_pk_fma_f32 v[100:101], v[50:51], v[80:81], v[100:101] op_sel:[0,0,0] op_sel_hi:[1,0,1]
	v_pk_fma_f32 v[102:103], v[50:51], v[80:81], v[102:103] op_sel:[0,1,0] op_sel_hi:[1,1,1]
	v_pk_fma_f32 v[104:105], v[50:51], v[82:83], v[104:105] op_sel:[0,0,0] op_sel_hi:[1,0,1]
	v_pk_fma_f32 v[106:107], v[50:51], v[82:83], v[106:107] op_sel:[0,1,0] op_sel_hi:[1,1,1]
	v_pk_fma_f32 v[108:109], v[50:51], v[84:85], v[108:109] op_sel:[0,0,0] op_sel_hi:[1,0,1]
	v_pk_fma_f32 v[110:111], v[50:51], v[84:85], v[110:111] op_sel:[0,1,0] op_sel_hi:[1,1,1]
	v_pk_mul_f32 v[48:49], v[96:97], v[86:87] op_sel:[0,0] op_sel_hi:[1,0]
	v_pk_mul_f32 v[50:51], v[96:97], v[62:63] op_sel:[0,0] op_sel_hi:[1,0]
	v_pk_fma_f32 v[48:49], v[98:99], v[86:87], v[48:49] op_sel:[0,1,0] op_sel_hi:[1,1,1]
	v_pk_fma_f32 v[50:51], v[98:99], v[62:63], v[50:51] op_sel:[0,1,0] op_sel_hi:[1,1,1]
	v_pk_fma_f32 v[48:49], v[100:101], v[88:89], v[48:49] op_sel:[0,0,0] op_sel_hi:[1,0,1]
	v_pk_fma_f32 v[50:51], v[100:101], v[64:65], v[50:51] op_sel:[0,0,0] op_sel_hi:[1,0,1]
	v_pk_fma_f32 v[48:49], v[102:103], v[88:89], v[48:49] op_sel:[0,1,0] op_sel_hi:[1,1,1]
	v_pk_fma_f32 v[50:51], v[102:103], v[64:65], v[50:51] op_sel:[0,1,0] op_sel_hi:[1,1,1]
	v_pk_fma_f32 v[48:49], v[104:105], v[90:91], v[48:49] op_sel:[0,0,0] op_sel_hi:[1,0,1]
	v_pk_fma_f32 v[50:51], v[104:105], v[66:67], v[50:51] op_sel:[0,0,0] op_sel_hi:[1,0,1]
	v_pk_fma_f32 v[48:49], v[106:107], v[90:91], v[48:49] op_sel:[0,1,0] op_sel_hi:[1,1,1]
	v_pk_fma_f32 v[50:51], v[106:107], v[66:67], v[50:51] op_sel:[0,1,0] op_sel_hi:[1,1,1]
	v_pk_fma_f32 v[48:49], v[108:109], v[92:93], v[48:49] op_sel:[0,0,0] op_sel_hi:[1,0,1]
	v_pk_fma_f32 v[50:51], v[108:109], v[68:69], v[50:51] op_sel:[0,0,0] op_sel_hi:[1,0,1]
	v_pk_fma_f32 v[48:49], v[110:111], v[92:93], v[48:49] op_sel:[0,1,0] op_sel_hi:[1,1,1]
	v_pk_fma_f32 v[50:51], v[110:111], v[68:69], v[50:51] op_sel:[0,1,0] op_sel_hi:[1,1,1]
	s_waitcnt lgkmcnt(10)
; #define LAS __attribute__((address_space(3)))
; __device__ __forceinline__ float red8(float x) { x += dpp_mov<0xB1>(x); x += dpp_mov<0x4E>(x); x += dpp_mov<0x141>(x); return x; }
; __device__ __forceinline__ void scan_phase(const KP& P, LAS unsigned char* lds, const int tid, const int bx, const int G) {
;     ...
;             for (int s = 0; s < 32; ++s) {
;                 const LAS float* p = cb + s * 384;
;                 const f32x4 w0 = *(const LAS f32x4*)(p), w1 = *(const LAS f32x4*)(p + 4);
;                 const f32x4 k0 = *(const LAS f32x4*)(p + 64), k1 = *(const LAS f32x4*)(p + 68);
;                 const f32x4 a0 = *(const LAS f32x4*)(p + 128), a1 = *(const LAS f32x4*)(p + 132);
;                 const f32x4 b0 = *(const LAS f32x4*)(p + 192), b1 = *(const LAS f32x4*)(p + 196);
;                 const f32x4 r0 = *(const LAS f32x4*)(p + 256), r1 = *(const LAS f32x4*)(p + 260);
;                 const float vv = buf[(c & 1) * 12288 + s * 384 + 320 + v];
;                 f32x2 sa2 = S[0] * (f32x2){a0.x, a0.y};
;                 sa2 += S[1] * (f32x2){a0.z, a0.w}; sa2 += S[2] * (f32x2){a1.x, a1.y}; sa2 += S[3] * (f32x2){a1.z, a1.w};
;                 const float sa = red8(sa2.x + sa2.y);
;                 const f32x2 sav = {sa, sa}, vv2 = {vv, vv};
;                 S[0] = S[0] * (f32x2){w0.x, w0.y} + sav * (f32x2){b0.x, b0.y} + vv2 * (f32x2){k0.x, k0.y};
;                 S[1] = S[1] * (f32x2){w0.z, w0.w} + sav * (f32x2){b0.z, b0.w} + vv2 * (f32x2){k0.z, k0.w};
;                 S[2] = S[2] * (f32x2){w1.x, w1.y} + sav * (f32x2){b1.x, b1.y} + vv2 * (f32x2){k1.x, k1.y};
;                 S[3] = S[3] * (f32x2){w1.z, w1.w} + sav * (f32x2){b1.z, b1.w} + vv2 * (f32x2){k1.z, k1.w};
;                 f32x2 y2 = S[0] * (f32x2){r0.x, r0.y};
;                 y2 += S[1] * (f32x2){r0.z, r0.w}; y2 += S[2] * (f32x2){r1.x, r1.y}; y2 += S[3] * (f32x2){r1.z, r1.w};
;                 const float y = red8(y2.x + y2.y);
;                 if (kc == 0) ybuf[s * 64 + v] = y;
	ds_read_b128 v[70:73], v44 offset:6400
	ds_read_b128 v[74:77], v44 offset:6416
	ds_read_b128 v[78:81], v44 offset:6912
	ds_read_b128 v[82:85], v44 offset:6928
	ds_read_b128 v[86:89], v44 offset:7168
	ds_read_b128 v[90:93], v44 offset:7184
	ds_read_b64 v[146:147], v46 offset:6144
	ds_read_b128 v[62:65], v44 offset:8192
	ds_read_b128 v[66:69], v44 offset:8208
	v_add_f32_dpp v48, v48, v48 quad_perm:[1,0,3,2] row_mask:0xf bank_mask:0xf bound_ctrl:1
	v_add_f32_dpp v49, v49, v49 quad_perm:[1,0,3,2] row_mask:0xf bank_mask:0xf bound_ctrl:1
	v_add_f32_dpp v50, v50, v50 quad_perm:[1,0,3,2] row_mask:0xf bank_mask:0xf bound_ctrl:1
	v_add_f32_dpp v51, v51, v51 quad_perm:[1,0,3,2] row_mask:0xf bank_mask:0xf bound_ctrl:1
	v_pk_fma_f32 v[96:97], v[192:193], v[168:169], v[96:97] op_sel:[0,0,0] op_sel_hi:[1,0,1]
	v_pk_fma_f32 v[98:99], v[192:193], v[168:169], v[98:99] op_sel:[0,1,0] op_sel_hi:[1,1,1]
	v_pk_fma_f32 v[100:101], v[192:193], v[170:171], v[100:101] op_sel:[0,0,0] op_sel_hi:[1,0,1]
	v_add_f32_dpp v48, v48, v48 quad_perm:[2,3,0,1] row_mask:0xf bank_mask:0xf bound_ctrl:1
	v_add_f32_dpp v49, v49, v49 quad_perm:[2,3,0,1] row_mask:0xf bank_mask:0xf bound_ctrl:1
	v_add_f32_dpp v50, v50, v50 quad_perm:[2,3,0,1] row_mask:0xf bank_mask:0xf bound_ctrl:1
	v_add_f32_dpp v51, v51, v51 quad_perm:[2,3,0,1] row_mask:0xf bank_mask:0xf bound_ctrl:1
	v_pk_fma_f32 v[102:103], v[192:193], v[170:171], v[102:103] op_sel:[0,1,0] op_sel_hi:[1,1,1]
	v_pk_fma_f32 v[104:105], v[192:193], v[172:173], v[104:105] op_sel:[0,0,0] op_sel_hi:[1,0,1]
	v_pk_fma_f32 v[106:107], v[192:193], v[172:173], v[106:107] op_sel:[0,1,0] op_sel_hi:[1,1,1]
	v_add_f32_dpp v48, v48, v48 row_half_mirror row_mask:0xf bank_mask:0xf bound_ctrl:1
	v_add_f32_dpp v49, v49, v49 row_half_mirror row_mask:0xf bank_mask:0xf bound_ctrl:1
	v_add_f32_dpp v50, v50, v50 row_half_mirror row_mask:0xf bank_mask:0xf bound_ctrl:1
	v_add_f32_dpp v51, v51, v51 row_half_mirror row_mask:0xf bank_mask:0xf bound_ctrl:1
	v_pk_fma_f32 v[108:109], v[192:193], v[174:175], v[108:109] op_sel:[0,0,0] op_sel_hi:[1,0,1]
	s_mov_b64 exec, s[10:11]
	ds_write_b64 v45, v[48:49] offset:256
	s_mov_b64 exec, s[0:1]
	v_pk_fma_f32 v[110:111], v[192:193], v[174:175], v[110:111] op_sel:[0,1,0] op_sel_hi:[1,1,1]
	s_nop 0
	v_pk_fma_f32 v[96:97], v[50:51], v[176:177], v[96:97] op_sel:[0,0,0] op_sel_hi:[1,0,1]
	v_pk_fma_f32 v[98:99], v[50:51], v[176:177], v[98:99] op_sel:[0,1,0] op_sel_hi:[1,1,1]
	v_pk_fma_f32 v[100:101], v[50:51], v[178:179], v[100:101] op_sel:[0,0,0] op_sel_hi:[1,0,1]
	v_pk_fma_f32 v[102:103], v[50:51], v[178:179], v[102:103] op_sel:[0,1,0] op_sel_hi:[1,1,1]
	v_pk_fma_f32 v[104:105], v[50:51], v[180:181], v[104:105] op_sel:[0,0,0] op_sel_hi:[1,0,1]
	v_pk_fma_f32 v[106:107], v[50:51], v[180:181], v[106:107] op_sel:[0,1,0] op_sel_hi:[1,1,1]
	v_pk_fma_f32 v[108:109], v[50:51], v[182:183], v[108:109] op_sel:[0,0,0] op_sel_hi:[1,0,1]
	v_pk_fma_f32 v[110:111], v[50:51], v[182:183], v[110:111] op_sel:[0,1,0] op_sel_hi:[1,1,1]
	v_pk_mul_f32 v[48:49], v[96:97], v[184:185] op_sel:[0,0] op_sel_hi:[1,0]
	v_pk_mul_f32 v[50:51], v[96:97], v[148:149] op_sel:[0,0] op_sel_hi:[1,0]
	v_pk_fma_f32 v[48:49], v[98:99], v[184:185], v[48:49] op_sel:[0,1,0] op_sel_hi:[1,1,1]
	v_pk_fma_f32 v[50:51], v[98:99], v[148:149], v[50:51] op_sel:[0,1,0] op_sel_hi:[1,1,1]
	v_pk_fma_f32 v[48:49], v[100:101], v[186:187], v[48:49] op_sel:[0,0,0] op_sel_hi:[1,0,1]
	v_pk_fma_f32 v[50:51], v[100:101], v[150:151], v[50:51] op_sel:[0,0,0] op_sel_hi:[1,0,1]
	v_pk_fma_f32 v[48:49], v[102:103], v[186:187], v[48:49] op_sel:[0,1,0] op_sel_hi:[1,1,1]
	v_pk_fma_f32 v[50:51], v[102:103], v[150:151], v[50:51] op_sel:[0,1,0] op_sel_hi:[1,1,1]
	v_pk_fma_f32 v[48:49], v[104:105], v[188:189], v[48:49] op_sel:[0,0,0] op_sel_hi:[1,0,1]
	v_pk_fma_f32 v[50:51], v[104:105], v[152:153], v[50:51] op_sel:[0,0,0] op_sel_hi:[1,0,1]
	v_pk_fma_f32 v[48:49], v[106:107], v[188:189], v[48:49] op_sel:[0,1,0] op_sel_hi:[1,1,1]
	v_pk_fma_f32 v[50:51], v[106:107], v[152:153], v[50:51] op_sel:[0,1,0] op_sel_hi:[1,1,1]
	v_pk_fma_f32 v[48:49], v[108:109], v[190:191], v[48:49] op_sel:[0,0,0] op_sel_hi:[1,0,1]
	v_pk_fma_f32 v[50:51], v[108:109], v[154:155], v[50:51] op_sel:[0,0,0] op_sel_hi:[1,0,1]
	v_pk_fma_f32 v[48:49], v[110:111], v[190:191], v[48:49] op_sel:[0,1,0] op_sel_hi:[1,1,1]
	v_pk_fma_f32 v[50:51], v[110:111], v[154:155], v[50:51] op_sel:[0,1,0] op_sel_hi:[1,1,1]
	s_waitcnt lgkmcnt(11)
; #define LAS __attribute__((address_space(3)))
; __device__ __forceinline__ float red8(float x) { x += dpp_mov<0xB1>(x); x += dpp_mov<0x4E>(x); x += dpp_mov<0x141>(x); return x; }
; __device__ __forceinline__ void scan_phase(const KP& P, LAS unsigned char* lds, const int tid, const int bx, const int G) {
;     ...
;             for (int s = 0; s < 32; ++s) {
;                 const LAS float* p = cb + s * 384;
;                 const f32x4 w0 = *(const LAS f32x4*)(p), w1 = *(const LAS f32x4*)(p + 4);
;                 const f32x4 k0 = *(const LAS f32x4*)(p + 64), k1 = *(const LAS f32x4*)(p + 68);
;                 const f32x4 a0 = *(const LAS f32x4*)(p + 128), a1 = *(const LAS f32x4*)(p + 132);
;                 const f32x4 b0 = *(const LAS f32x4*)(p + 192), b1 = *(const LAS f32x4*)(p + 196);
;                 const f32x4 r0 = *(const LAS f32x4*)(p + 256), r1 = *(const LAS f32x4*)(p + 260);
;                 const float vv = buf[(c & 1) * 12288 + s * 384 + 320 + v];
;                 f32x2 sa2 = S[0] * (f32x2){a0.x, a0.y};
;                 sa2 += S[1] * (f32x2){a0.z, a0.w}; sa2 += S[2] * (f32x2){a1.x, a1.y}; sa2 += S[3] * (f32x2){a1.z, a1.w};
;                 const float sa = red8(sa2.x + sa2.y);
;                 const f32x2 sav = {sa, sa}, vv2 = {vv, vv};
;                 S[0] = S[0] * (f32x2){w0.x, w0.y} + sav * (f32x2){b0.x, b0.y} + vv2 * (f32x2){k0.x, k0.y};
;                 S[1] = S[1] * (f32x2){w0.z, w0.w} + sav * (f32x2){b0.z, b0.w} + vv2 * (f32x2){k0.z, k0.w};
;                 S[2] = S[2] * (f32x2){w1.x, w1.y} + sav * (f32x2){b1.x, b1.y} + vv2 * (f32x2){k1.x, k1.y};
;                 S[3] = S[3] * (f32x2){w1.z, w1.w} + sav * (f32x2){b1.z, b1.w} + vv2 * (f32x2){k1.z, k1.w};
;                 f32x2 y2 = S[0] * (f32x2){r0.x, r0.y};
;                 y2 += S[1] * (f32x2){r0.z, r0.w}; y2 += S[2] * (f32x2){r1.x, r1.y}; y2 += S[3] * (f32x2){r1.z, r1.w};
;                 const float y = red8(y2.x + y2.y);
;                 if (kc == 0) ybuf[s * 64 + v] = y;
	ds_read_b128 v[168:171], v44 offset:7936
	ds_read_b128 v[172:175], v44 offset:7952
	ds_read_b128 v[176:179], v44 offset:8448
	ds_read_b128 v[180:183], v44 offset:8464
	ds_read_b128 v[184:187], v44 offset:8704
	ds_read_b128 v[188:191], v44 offset:8720
	ds_read_b64 v[192:193], v46 offset:7680
	ds_read_b128 v[148:151], v44 offset:9728
	ds_read_b128 v[152:155], v44 offset:9744
	v_add_f32_dpp v48, v48, v48 quad_perm:[1,0,3,2] row_mask:0xf bank_mask:0xf bound_ctrl:1
	v_add_f32_dpp v49, v49, v49 quad_perm:[1,0,3,2] row_mask:0xf bank_mask:0xf bound_ctrl:1
	v_add_f32_dpp v50, v50, v50 quad_perm:[1,0,3,2] row_mask:0xf bank_mask:0xf bound_ctrl:1
	v_add_f32_dpp v51, v51, v51 quad_perm:[1,0,3,2] row_mask:0xf bank_mask:0xf bound_ctrl:1
	v_pk_fma_f32 v[96:97], v[144:145], v[120:121], v[96:97] op_sel:[0,0,0] op_sel_hi:[1,0,1]
	v_pk_fma_f32 v[98:99], v[144:145], v[120:121], v[98:99] op_sel:[0,1,0] op_sel_hi:[1,1,1]
	v_pk_fma_f32 v[100:101], v[144:145], v[122:123], v[100:101] op_sel:[0,0,0] op_sel_hi:[1,0,1]
	v_add_f32_dpp v48, v48, v48 quad_perm:[2,3,0,1] row_mask:0xf bank_mask:0xf bound_ctrl:1
	v_add_f32_dpp v49, v49, v49 quad_perm:[2,3,0,1] row_mask:0xf bank_mask:0xf bound_ctrl:1
	v_add_f32_dpp v50, v50, v50 quad_perm:[2,3,0,1] row_mask:0xf bank_mask:0xf bound_ctrl:1
	v_add_f32_dpp v51, v51, v51 quad_perm:[2,3,0,1] row_mask:0xf bank_mask:0xf bound_ctrl:1
	v_pk_fma_f32 v[102:103], v[144:145], v[122:123], v[102:103] op_sel:[0,1,0] op_sel_hi:[1,1,1]
	v_pk_fma_f32 v[104:105], v[144:145], v[124:125], v[104:105] op_sel:[0,0,0] op_sel_hi:[1,0,1]
	v_pk_fma_f32 v[106:107], v[144:145], v[124:125], v[106:107] op_sel:[0,1,0] op_sel_hi:[1,1,1]
	v_add_f32_dpp v48, v48, v48 row_half_mirror row_mask:0xf bank_mask:0xf bound_ctrl:1
	v_add_f32_dpp v49, v49, v49 row_half_mirror row_mask:0xf bank_mask:0xf bound_ctrl:1
	v_add_f32_dpp v50, v50, v50 row_half_mirror row_mask:0xf bank_mask:0xf bound_ctrl:1
	v_add_f32_dpp v51, v51, v51 row_half_mirror row_mask:0xf bank_mask:0xf bound_ctrl:1
	v_pk_fma_f32 v[108:109], v[144:145], v[126:127], v[108:109] op_sel:[0,0,0] op_sel_hi:[1,0,1]
	s_mov_b64 exec, s[10:11]
	ds_write_b64 v45, v[48:49] offset:512
	s_mov_b64 exec, s[0:1]
	v_pk_fma_f32 v[110:111], v[144:145], v[126:127], v[110:111] op_sel:[0,1,0] op_sel_hi:[1,1,1]
	s_nop 0
	v_pk_fma_f32 v[96:97], v[50:51], v[128:129], v[96:97] op_sel:[0,0,0] op_sel_hi:[1,0,1]
	v_pk_fma_f32 v[98:99], v[50:51], v[128:129], v[98:99] op_sel:[0,1,0] op_sel_hi:[1,1,1]
	v_pk_fma_f32 v[100:101], v[50:51], v[130:131], v[100:101] op_sel:[0,0,0] op_sel_hi:[1,0,1]
	v_pk_fma_f32 v[102:103], v[50:51], v[130:131], v[102:103] op_sel:[0,1,0] op_sel_hi:[1,1,1]
	v_pk_fma_f32 v[104:105], v[50:51], v[132:133], v[104:105] op_sel:[0,0,0] op_sel_hi:[1,0,1]
	v_pk_fma_f32 v[106:107], v[50:51], v[132:133], v[106:107] op_sel:[0,1,0] op_sel_hi:[1,1,1]
	v_pk_fma_f32 v[108:109], v[50:51], v[134:135], v[108:109] op_sel:[0,0,0] op_sel_hi:[1,0,1]
	v_pk_fma_f32 v[110:111], v[50:51], v[134:135], v[110:111] op_sel:[0,1,0] op_sel_hi:[1,1,1]
	v_pk_mul_f32 v[48:49], v[96:97], v[136:137] op_sel:[0,0] op_sel_hi:[1,0]
	v_pk_mul_f32 v[50:51], v[96:97], v[156:157] op_sel:[0,0] op_sel_hi:[1,0]
	v_pk_fma_f32 v[48:49], v[98:99], v[136:137], v[48:49] op_sel:[0,1,0] op_sel_hi:[1,1,1]
	v_pk_fma_f32 v[50:51], v[98:99], v[156:157], v[50:51] op_sel:[0,1,0] op_sel_hi:[1,1,1]
	v_pk_fma_f32 v[48:49], v[100:101], v[138:139], v[48:49] op_sel:[0,0,0] op_sel_hi:[1,0,1]
	v_pk_fma_f32 v[50:51], v[100:101], v[158:159], v[50:51] op_sel:[0,0,0] op_sel_hi:[1,0,1]
	v_pk_fma_f32 v[48:49], v[102:103], v[138:139], v[48:49] op_sel:[0,1,0] op_sel_hi:[1,1,1]
	v_pk_fma_f32 v[50:51], v[102:103], v[158:159], v[50:51] op_sel:[0,1,0] op_sel_hi:[1,1,1]
	v_pk_fma_f32 v[48:49], v[104:105], v[140:141], v[48:49] op_sel:[0,0,0] op_sel_hi:[1,0,1]
	v_pk_fma_f32 v[50:51], v[104:105], v[160:161], v[50:51] op_sel:[0,0,0] op_sel_hi:[1,0,1]
	v_pk_fma_f32 v[48:49], v[106:107], v[140:141], v[48:49] op_sel:[0,1,0] op_sel_hi:[1,1,1]
	v_pk_fma_f32 v[50:51], v[106:107], v[160:161], v[50:51] op_sel:[0,1,0] op_sel_hi:[1,1,1]
	v_pk_fma_f32 v[48:49], v[108:109], v[142:143], v[48:49] op_sel:[0,0,0] op_sel_hi:[1,0,1]
	v_pk_fma_f32 v[50:51], v[108:109], v[162:163], v[50:51] op_sel:[0,0,0] op_sel_hi:[1,0,1]
	v_pk_fma_f32 v[48:49], v[110:111], v[142:143], v[48:49] op_sel:[0,1,0] op_sel_hi:[1,1,1]
	v_pk_fma_f32 v[50:51], v[110:111], v[162:163], v[50:51] op_sel:[0,1,0] op_sel_hi:[1,1,1]
	s_waitcnt lgkmcnt(11)
; #define LAS __attribute__((address_space(3)))
; __device__ __forceinline__ float red8(float x) { x += dpp_mov<0xB1>(x); x += dpp_mov<0x4E>(x); x += dpp_mov<0x141>(x); return x; }
; __device__ __forceinline__ void scan_phase(const KP& P, LAS unsigned char* lds, const int tid, const int bx, const int G) {
;     ...
;             for (int s = 0; s < 32; ++s) {
;                 const LAS float* p = cb + s * 384;
;                 const f32x4 w0 = *(const LAS f32x4*)(p), w1 = *(const LAS f32x4*)(p + 4);
;                 const f32x4 k0 = *(const LAS f32x4*)(p + 64), k1 = *(const LAS f32x4*)(p + 68);
;                 const f32x4 a0 = *(const LAS f32x4*)(p + 128), a1 = *(const LAS f32x4*)(p + 132);
;                 const f32x4 b0 = *(const LAS f32x4*)(p + 192), b1 = *(const LAS f32x4*)(p + 196);
;                 const f32x4 r0 = *(const LAS f32x4*)(p + 256), r1 = *(const LAS f32x4*)(p + 260);
;                 const float vv = buf[(c & 1) * 12288 + s * 384 + 320 + v];
;                 f32x2 sa2 = S[0] * (f32x2){a0.x, a0.y};
;                 sa2 += S[1] * (f32x2){a0.z, a0.w}; sa2 += S[2] * (f32x2){a1.x, a1.y}; sa2 += S[3] * (f32x2){a1.z, a1.w};
;                 const float sa = red8(sa2.x + sa2.y);
;                 const f32x2 sav = {sa, sa}, vv2 = {vv, vv};
;                 S[0] = S[0] * (f32x2){w0.x, w0.y} + sav * (f32x2){b0.x, b0.y} + vv2 * (f32x2){k0.x, k0.y};
;                 S[1] = S[1] * (f32x2){w0.z, w0.w} + sav * (f32x2){b0.z, b0.w} + vv2 * (f32x2){k0.z, k0.w};
;                 S[2] = S[2] * (f32x2){w1.x, w1.y} + sav * (f32x2){b1.x, b1.y} + vv2 * (f32x2){k1.x, k1.y};
;                 S[3] = S[3] * (f32x2){w1.z, w1.w} + sav * (f32x2){b1.z, b1.w} + vv2 * (f32x2){k1.z, k1.w};
;                 f32x2 y2 = S[0] * (f32x2){r0.x, r0.y};
;                 y2 += S[1] * (f32x2){r0.z, r0.w}; y2 += S[2] * (f32x2){r1.x, r1.y}; y2 += S[3] * (f32x2){r1.z, r1.w};
;                 const float y = red8(y2.x + y2.y);
;                 if (kc == 0) ybuf[s * 64 + v] = y;
	ds_read_b128 v[120:123], v44 offset:9472
	ds_read_b128 v[124:127], v44 offset:9488
	ds_read_b128 v[128:131], v44 offset:9984
	ds_read_b128 v[132:135], v44 offset:10000
	ds_read_b128 v[136:139], v44 offset:10240
	ds_read_b128 v[140:143], v44 offset:10256
	ds_read_b64 v[144:145], v46 offset:9216
	ds_read_b128 v[156:159], v44 offset:11264
	ds_read_b128 v[160:163], v44 offset:11280
	v_add_f32_dpp v48, v48, v48 quad_perm:[1,0,3,2] row_mask:0xf bank_mask:0xf bound_ctrl:1
	v_add_f32_dpp v49, v49, v49 quad_perm:[1,0,3,2] row_mask:0xf bank_mask:0xf bound_ctrl:1
	v_add_f32_dpp v50, v50, v50 quad_perm:[1,0,3,2] row_mask:0xf bank_mask:0xf bound_ctrl:1
	v_add_f32_dpp v51, v51, v51 quad_perm:[1,0,3,2] row_mask:0xf bank_mask:0xf bound_ctrl:1
	v_pk_fma_f32 v[96:97], v[146:147], v[70:71], v[96:97] op_sel:[0,0,0] op_sel_hi:[1,0,1]
	v_pk_fma_f32 v[98:99], v[146:147], v[70:71], v[98:99] op_sel:[0,1,0] op_sel_hi:[1,1,1]
	v_pk_fma_f32 v[100:101], v[146:147], v[72:73], v[100:101] op_sel:[0,0,0] op_sel_hi:[1,0,1]
	v_add_f32_dpp v48, v48, v48 quad_perm:[2,3,0,1] row_mask:0xf bank_mask:0xf bound_ctrl:1
	v_add_f32_dpp v49, v49, v49 quad_perm:[2,3,0,1] row_mask:0xf bank_mask:0xf bound_ctrl:1
	v_add_f32_dpp v50, v50, v50 quad_perm:[2,3,0,1] row_mask:0xf bank_mask:0xf bound_ctrl:1
	v_add_f32_dpp v51, v51, v51 quad_perm:[2,3,0,1] row_mask:0xf bank_mask:0xf bound_ctrl:1
	v_pk_fma_f32 v[102:103], v[146:147], v[72:73], v[102:103] op_sel:[0,1,0] op_sel_hi:[1,1,1]
	v_pk_fma_f32 v[104:105], v[146:147], v[74:75], v[104:105] op_sel:[0,0,0] op_sel_hi:[1,0,1]
	v_pk_fma_f32 v[106:107], v[146:147], v[74:75], v[106:107] op_sel:[0,1,0] op_sel_hi:[1,1,1]
	v_add_f32_dpp v48, v48, v48 row_half_mirror row_mask:0xf bank_mask:0xf bound_ctrl:1
	v_add_f32_dpp v49, v49, v49 row_half_mirror row_mask:0xf bank_mask:0xf bound_ctrl:1
	v_add_f32_dpp v50, v50, v50 row_half_mirror row_mask:0xf bank_mask:0xf bound_ctrl:1
	v_add_f32_dpp v51, v51, v51 row_half_mirror row_mask:0xf bank_mask:0xf bound_ctrl:1
	v_pk_fma_f32 v[108:109], v[146:147], v[76:77], v[108:109] op_sel:[0,0,0] op_sel_hi:[1,0,1]
	s_mov_b64 exec, s[10:11]
	ds_write_b64 v45, v[48:49] offset:768
	s_mov_b64 exec, s[0:1]
	v_pk_fma_f32 v[110:111], v[146:147], v[76:77], v[110:111] op_sel:[0,1,0] op_sel_hi:[1,1,1]
	s_nop 0
	v_pk_fma_f32 v[96:97], v[50:51], v[78:79], v[96:97] op_sel:[0,0,0] op_sel_hi:[1,0,1]
	v_pk_fma_f32 v[98:99], v[50:51], v[78:79], v[98:99] op_sel:[0,1,0] op_sel_hi:[1,1,1]
	v_pk_fma_f32 v[100:101], v[50:51], v[80:81], v[100:101] op_sel:[0,0,0] op_sel_hi:[1,0,1]
	v_pk_fma_f32 v[102:103], v[50:51], v[80:81], v[102:103] op_sel:[0,1,0] op_sel_hi:[1,1,1]
	v_pk_fma_f32 v[104:105], v[50:51], v[82:83], v[104:105] op_sel:[0,0,0] op_sel_hi:[1,0,1]
	v_pk_fma_f32 v[106:107], v[50:51], v[82:83], v[106:107] op_sel:[0,1,0] op_sel_hi:[1,1,1]
	v_pk_fma_f32 v[108:109], v[50:51], v[84:85], v[108:109] op_sel:[0,0,0] op_sel_hi:[1,0,1]
	v_pk_fma_f32 v[110:111], v[50:51], v[84:85], v[110:111] op_sel:[0,1,0] op_sel_hi:[1,1,1]
	v_pk_mul_f32 v[48:49], v[96:97], v[86:87] op_sel:[0,0] op_sel_hi:[1,0]
	v_pk_mul_f32 v[50:51], v[96:97], v[62:63] op_sel:[0,0] op_sel_hi:[1,0]
	v_pk_fma_f32 v[48:49], v[98:99], v[86:87], v[48:49] op_sel:[0,1,0] op_sel_hi:[1,1,1]
	v_pk_fma_f32 v[50:51], v[98:99], v[62:63], v[50:51] op_sel:[0,1,0] op_sel_hi:[1,1,1]
	v_pk_fma_f32 v[48:49], v[100:101], v[88:89], v[48:49] op_sel:[0,0,0] op_sel_hi:[1,0,1]
	v_pk_fma_f32 v[50:51], v[100:101], v[64:65], v[50:51] op_sel:[0,0,0] op_sel_hi:[1,0,1]
	v_pk_fma_f32 v[48:49], v[102:103], v[88:89], v[48:49] op_sel:[0,1,0] op_sel_hi:[1,1,1]
	v_pk_fma_f32 v[50:51], v[102:103], v[64:65], v[50:51] op_sel:[0,1,0] op_sel_hi:[1,1,1]
	v_pk_fma_f32 v[48:49], v[104:105], v[90:91], v[48:49] op_sel:[0,0,0] op_sel_hi:[1,0,1]
	v_pk_fma_f32 v[50:51], v[104:105], v[66:67], v[50:51] op_sel:[0,0,0] op_sel_hi:[1,0,1]
	v_pk_fma_f32 v[48:49], v[106:107], v[90:91], v[48:49] op_sel:[0,1,0] op_sel_hi:[1,1,1]
	v_pk_fma_f32 v[50:51], v[106:107], v[66:67], v[50:51] op_sel:[0,1,0] op_sel_hi:[1,1,1]
	v_pk_fma_f32 v[48:49], v[108:109], v[92:93], v[48:49] op_sel:[0,0,0] op_sel_hi:[1,0,1]
	v_pk_fma_f32 v[50:51], v[108:109], v[68:69], v[50:51] op_sel:[0,0,0] op_sel_hi:[1,0,1]
	v_pk_fma_f32 v[48:49], v[110:111], v[92:93], v[48:49] op_sel:[0,1,0] op_sel_hi:[1,1,1]
	v_pk_fma_f32 v[50:51], v[110:111], v[68:69], v[50:51] op_sel:[0,1,0] op_sel_hi:[1,1,1]
	s_waitcnt lgkmcnt(11)
; #define LAS __attribute__((address_space(3)))
; __device__ __forceinline__ float red8(float x) { x += dpp_mov<0xB1>(x); x += dpp_mov<0x4E>(x); x += dpp_mov<0x141>(x); return x; }
; __device__ __forceinline__ void scan_phase(const KP& P, LAS unsigned char* lds, const int tid, const int bx, const int G) {
;     ...
;             for (int s = 0; s < 32; ++s) {
;                 const LAS float* p = cb + s * 384;
;                 const f32x4 w0 = *(const LAS f32x4*)(p), w1 = *(const LAS f32x4*)(p + 4);
;                 const f32x4 k0 = *(const LAS f32x4*)(p + 64), k1 = *(const LAS f32x4*)(p + 68);
;                 const f32x4 a0 = *(const LAS f32x4*)(p + 128), a1 = *(const LAS f32x4*)(p + 132);
;                 const f32x4 b0 = *(const LAS f32x4*)(p + 192), b1 = *(const LAS f32x4*)(p + 196);
;                 const f32x4 r0 = *(const LAS f32x4*)(p + 256), r1 = *(const LAS f32x4*)(p + 260);
;                 const float vv = buf[(c & 1) * 12288 + s * 384 + 320 + v];
;                 f32x2 sa2 = S[0] * (f32x2){a0.x, a0.y};
;                 sa2 += S[1] * (f32x2){a0.z, a0.w}; sa2 += S[2] * (f32x2){a1.x, a1.y}; sa2 += S[3] * (f32x2){a1.z, a1.w};
;                 const float sa = red8(sa2.x + sa2.y);
;                 const f32x2 sav = {sa, sa}, vv2 = {vv, vv};
;                 S[0] = S[0] * (f32x2){w0.x, w0.y} + sav * (f32x2){b0.x, b0.y} + vv2 * (f32x2){k0.x, k0.y};
;                 S[1] = S[1] * (f32x2){w0.z, w0.w} + sav * (f32x2){b0.z, b0.w} + vv2 * (f32x2){k0.z, k0.w};
;                 S[2] = S[2] * (f32x2){w1.x, w1.y} + sav * (f32x2){b1.x, b1.y} + vv2 * (f32x2){k1.x, k1.y};
;                 S[3] = S[3] * (f32x2){w1.z, w1.w} + sav * (f32x2){b1.z, b1.w} + vv2 * (f32x2){k1.z, k1.w};
;                 f32x2 y2 = S[0] * (f32x2){r0.x, r0.y};
;                 y2 += S[1] * (f32x2){r0.z, r0.w}; y2 += S[2] * (f32x2){r1.x, r1.y}; y2 += S[3] * (f32x2){r1.z, r1.w};
;                 const float y = red8(y2.x + y2.y);
;                 if (kc == 0) ybuf[s * 64 + v] = y;
	ds_read_b128 v[70:73], v44 offset:11008
	ds_read_b128 v[74:77], v44 offset:11024
	ds_read_b128 v[78:81], v44 offset:11520
	ds_read_b128 v[82:85], v44 offset:11536
	ds_read_b128 v[86:89], v44 offset:11776
	ds_read_b128 v[90:93], v44 offset:11792
	ds_read_b64 v[146:147], v46 offset:10752
	ds_read_b128 v[62:65], v44 offset:12800
	ds_read_b128 v[66:69], v44 offset:12816
	v_add_f32_dpp v48, v48, v48 quad_perm:[1,0,3,2] row_mask:0xf bank_mask:0xf bound_ctrl:1
	v_add_f32_dpp v49, v49, v49 quad_perm:[1,0,3,2] row_mask:0xf bank_mask:0xf bound_ctrl:1
	v_add_f32_dpp v50, v50, v50 quad_perm:[1,0,3,2] row_mask:0xf bank_mask:0xf bound_ctrl:1
	v_add_f32_dpp v51, v51, v51 quad_perm:[1,0,3,2] row_mask:0xf bank_mask:0xf bound_ctrl:1
	v_pk_fma_f32 v[96:97], v[192:193], v[168:169], v[96:97] op_sel:[0,0,0] op_sel_hi:[1,0,1]
	v_pk_fma_f32 v[98:99], v[192:193], v[168:169], v[98:99] op_sel:[0,1,0] op_sel_hi:[1,1,1]
	v_pk_fma_f32 v[100:101], v[192:193], v[170:171], v[100:101] op_sel:[0,0,0] op_sel_hi:[1,0,1]
	v_add_f32_dpp v48, v48, v48 quad_perm:[2,3,0,1] row_mask:0xf bank_mask:0xf bound_ctrl:1
	v_add_f32_dpp v49, v49, v49 quad_perm:[2,3,0,1] row_mask:0xf bank_mask:0xf bound_ctrl:1
	v_add_f32_dpp v50, v50, v50 quad_perm:[2,3,0,1] row_mask:0xf bank_mask:0xf bound_ctrl:1
	v_add_f32_dpp v51, v51, v51 quad_perm:[2,3,0,1] row_mask:0xf bank_mask:0xf bound_ctrl:1
	v_pk_fma_f32 v[102:103], v[192:193], v[170:171], v[102:103] op_sel:[0,1,0] op_sel_hi:[1,1,1]
	v_pk_fma_f32 v[104:105], v[192:193], v[172:173], v[104:105] op_sel:[0,0,0] op_sel_hi:[1,0,1]
	v_pk_fma_f32 v[106:107], v[192:193], v[172:173], v[106:107] op_sel:[0,1,0] op_sel_hi:[1,1,1]
	v_add_f32_dpp v48, v48, v48 row_half_mirror row_mask:0xf bank_mask:0xf bound_ctrl:1
	v_add_f32_dpp v49, v49, v49 row_half_mirror row_mask:0xf bank_mask:0xf bound_ctrl:1
	v_add_f32_dpp v50, v50, v50 row_half_mirror row_mask:0xf bank_mask:0xf bound_ctrl:1
	v_add_f32_dpp v51, v51, v51 row_half_mirror row_mask:0xf bank_mask:0xf bound_ctrl:1
	v_pk_fma_f32 v[108:109], v[192:193], v[174:175], v[108:109] op_sel:[0,0,0] op_sel_hi:[1,0,1]
	s_mov_b64 exec, s[10:11]
	ds_write_b64 v45, v[48:49] offset:1024
	s_mov_b64 exec, s[0:1]
	v_pk_fma_f32 v[110:111], v[192:193], v[174:175], v[110:111] op_sel:[0,1,0] op_sel_hi:[1,1,1]
	s_nop 0
	v_pk_fma_f32 v[96:97], v[50:51], v[176:177], v[96:97] op_sel:[0,0,0] op_sel_hi:[1,0,1]
	v_pk_fma_f32 v[98:99], v[50:51], v[176:177], v[98:99] op_sel:[0,1,0] op_sel_hi:[1,1,1]
	v_pk_fma_f32 v[100:101], v[50:51], v[178:179], v[100:101] op_sel:[0,0,0] op_sel_hi:[1,0,1]
	v_pk_fma_f32 v[102:103], v[50:51], v[178:179], v[102:103] op_sel:[0,1,0] op_sel_hi:[1,1,1]
	v_pk_fma_f32 v[104:105], v[50:51], v[180:181], v[104:105] op_sel:[0,0,0] op_sel_hi:[1,0,1]
	v_pk_fma_f32 v[106:107], v[50:51], v[180:181], v[106:107] op_sel:[0,1,0] op_sel_hi:[1,1,1]
	v_pk_fma_f32 v[108:109], v[50:51], v[182:183], v[108:109] op_sel:[0,0,0] op_sel_hi:[1,0,1]
	v_pk_fma_f32 v[110:111], v[50:51], v[182:183], v[110:111] op_sel:[0,1,0] op_sel_hi:[1,1,1]
	v_pk_mul_f32 v[48:49], v[96:97], v[184:185] op_sel:[0,0] op_sel_hi:[1,0]
	v_pk_mul_f32 v[50:51], v[96:97], v[148:149] op_sel:[0,0] op_sel_hi:[1,0]
	v_pk_fma_f32 v[48:49], v[98:99], v[184:185], v[48:49] op_sel:[0,1,0] op_sel_hi:[1,1,1]
	v_pk_fma_f32 v[50:51], v[98:99], v[148:149], v[50:51] op_sel:[0,1,0] op_sel_hi:[1,1,1]
	v_pk_fma_f32 v[48:49], v[100:101], v[186:187], v[48:49] op_sel:[0,0,0] op_sel_hi:[1,0,1]
	v_pk_fma_f32 v[50:51], v[100:101], v[150:151], v[50:51] op_sel:[0,0,0] op_sel_hi:[1,0,1]
	v_pk_fma_f32 v[48:49], v[102:103], v[186:187], v[48:49] op_sel:[0,1,0] op_sel_hi:[1,1,1]
	v_pk_fma_f32 v[50:51], v[102:103], v[150:151], v[50:51] op_sel:[0,1,0] op_sel_hi:[1,1,1]
	v_pk_fma_f32 v[48:49], v[104:105], v[188:189], v[48:49] op_sel:[0,0,0] op_sel_hi:[1,0,1]
	v_pk_fma_f32 v[50:51], v[104:105], v[152:153], v[50:51] op_sel:[0,0,0] op_sel_hi:[1,0,1]
	v_pk_fma_f32 v[48:49], v[106:107], v[188:189], v[48:49] op_sel:[0,1,0] op_sel_hi:[1,1,1]
	v_pk_fma_f32 v[50:51], v[106:107], v[152:153], v[50:51] op_sel:[0,1,0] op_sel_hi:[1,1,1]
	v_pk_fma_f32 v[48:49], v[108:109], v[190:191], v[48:49] op_sel:[0,0,0] op_sel_hi:[1,0,1]
	v_pk_fma_f32 v[50:51], v[108:109], v[154:155], v[50:51] op_sel:[0,0,0] op_sel_hi:[1,0,1]
	v_pk_fma_f32 v[48:49], v[110:111], v[190:191], v[48:49] op_sel:[0,1,0] op_sel_hi:[1,1,1]
	v_pk_fma_f32 v[50:51], v[110:111], v[154:155], v[50:51] op_sel:[0,1,0] op_sel_hi:[1,1,1]
	s_waitcnt lgkmcnt(11)
; #define LAS __attribute__((address_space(3)))
; __device__ __forceinline__ float red8(float x) { x += dpp_mov<0xB1>(x); x += dpp_mov<0x4E>(x); x += dpp_mov<0x141>(x); return x; }
; __device__ __forceinline__ void scan_phase(const KP& P, LAS unsigned char* lds, const int tid, const int bx, const int G) {
;     ...
;             for (int s = 0; s < 32; ++s) {
;                 const LAS float* p = cb + s * 384;
;                 const f32x4 w0 = *(const LAS f32x4*)(p), w1 = *(const LAS f32x4*)(p + 4);
;                 const f32x4 k0 = *(const LAS f32x4*)(p + 64), k1 = *(const LAS f32x4*)(p + 68);
;                 const f32x4 a0 = *(const LAS f32x4*)(p + 128), a1 = *(const LAS f32x4*)(p + 132);
;                 const f32x4 b0 = *(const LAS f32x4*)(p + 192), b1 = *(const LAS f32x4*)(p + 196);
;                 const f32x4 r0 = *(const LAS f32x4*)(p + 256), r1 = *(const LAS f32x4*)(p + 260);
;                 const float vv = buf[(c & 1) * 12288 + s * 384 + 320 + v];
;                 f32x2 sa2 = S[0] * (f32x2){a0.x, a0.y};
;                 sa2 += S[1] * (f32x2){a0.z, a0.w}; sa2 += S[2] * (f32x2){a1.x, a1.y}; sa2 += S[3] * (f32x2){a1.z, a1.w};
;                 const float sa = red8(sa2.x + sa2.y);
;                 const f32x2 sav = {sa, sa}, vv2 = {vv, vv};
;                 S[0] = S[0] * (f32x2){w0.x, w0.y} + sav * (f32x2){b0.x, b0.y} + vv2 * (f32x2){k0.x, k0.y};
;                 S[1] = S[1] * (f32x2){w0.z, w0.w} + sav * (f32x2){b0.z, b0.w} + vv2 * (f32x2){k0.z, k0.w};
;                 S[2] = S[2] * (f32x2){w1.x, w1.y} + sav * (f32x2){b1.x, b1.y} + vv2 * (f32x2){k1.x, k1.y};
;                 S[3] = S[3] * (f32x2){w1.z, w1.w} + sav * (f32x2){b1.z, b1.w} + vv2 * (f32x2){k1.z, k1.w};
;                 f32x2 y2 = S[0] * (f32x2){r0.x, r0.y};
;                 y2 += S[1] * (f32x2){r0.z, r0.w}; y2 += S[2] * (f32x2){r1.x, r1.y}; y2 += S[3] * (f32x2){r1.z, r1.w};
;                 const float y = red8(y2.x + y2.y);
;                 if (kc == 0) ybuf[s * 64 + v] = y;
	ds_read_b128 v[168:171], v44 offset:12544
	ds_read_b128 v[172:175], v44 offset:12560
	ds_read_b128 v[176:179], v44 offset:13056
	ds_read_b128 v[180:183], v44 offset:13072
	ds_read_b128 v[184:187], v44 offset:13312
	ds_read_b128 v[188:191], v44 offset:13328
	ds_read_b64 v[192:193], v46 offset:12288
	ds_read_b128 v[148:151], v44 offset:14336
	ds_read_b128 v[152:155], v44 offset:14352
	v_add_f32_dpp v48, v48, v48 quad_perm:[1,0,3,2] row_mask:0xf bank_mask:0xf bound_ctrl:1
	v_add_f32_dpp v49, v49, v49 quad_perm:[1,0,3,2] row_mask:0xf bank_mask:0xf bound_ctrl:1
	v_add_f32_dpp v50, v50, v50 quad_perm:[1,0,3,2] row_mask:0xf bank_mask:0xf bound_ctrl:1
	v_add_f32_dpp v51, v51, v51 quad_perm:[1,0,3,2] row_mask:0xf bank_mask:0xf bound_ctrl:1
	v_pk_fma_f32 v[96:97], v[144:145], v[120:121], v[96:97] op_sel:[0,0,0] op_sel_hi:[1,0,1]
	v_pk_fma_f32 v[98:99], v[144:145], v[120:121], v[98:99] op_sel:[0,1,0] op_sel_hi:[1,1,1]
	v_pk_fma_f32 v[100:101], v[144:145], v[122:123], v[100:101] op_sel:[0,0,0] op_sel_hi:[1,0,1]
	v_add_f32_dpp v48, v48, v48 quad_perm:[2,3,0,1] row_mask:0xf bank_mask:0xf bound_ctrl:1
	v_add_f32_dpp v49, v49, v49 quad_perm:[2,3,0,1] row_mask:0xf bank_mask:0xf bound_ctrl:1
	v_add_f32_dpp v50, v50, v50 quad_perm:[2,3,0,1] row_mask:0xf bank_mask:0xf bound_ctrl:1
	v_add_f32_dpp v51, v51, v51 quad_perm:[2,3,0,1] row_mask:0xf bank_mask:0xf bound_ctrl:1
	v_pk_fma_f32 v[102:103], v[144:145], v[122:123], v[102:103] op_sel:[0,1,0] op_sel_hi:[1,1,1]
	v_pk_fma_f32 v[104:105], v[144:145], v[124:125], v[104:105] op_sel:[0,0,0] op_sel_hi:[1,0,1]
	v_pk_fma_f32 v[106:107], v[144:145], v[124:125], v[106:107] op_sel:[0,1,0] op_sel_hi:[1,1,1]
	v_add_f32_dpp v48, v48, v48 row_half_mirror row_mask:0xf bank_mask:0xf bound_ctrl:1
	v_add_f32_dpp v49, v49, v49 row_half_mirror row_mask:0xf bank_mask:0xf bound_ctrl:1
	v_add_f32_dpp v50, v50, v50 row_half_mirror row_mask:0xf bank_mask:0xf bound_ctrl:1
	v_add_f32_dpp v51, v51, v51 row_half_mirror row_mask:0xf bank_mask:0xf bound_ctrl:1
	v_pk_fma_f32 v[108:109], v[144:145], v[126:127], v[108:109] op_sel:[0,0,0] op_sel_hi:[1,0,1]
	s_mov_b64 exec, s[10:11]
	ds_write_b64 v45, v[48:49] offset:1280
	s_mov_b64 exec, s[0:1]
	v_pk_fma_f32 v[110:111], v[144:145], v[126:127], v[110:111] op_sel:[0,1,0] op_sel_hi:[1,1,1]
	s_nop 0
	v_pk_fma_f32 v[96:97], v[50:51], v[128:129], v[96:97] op_sel:[0,0,0] op_sel_hi:[1,0,1]
	v_pk_fma_f32 v[98:99], v[50:51], v[128:129], v[98:99] op_sel:[0,1,0] op_sel_hi:[1,1,1]
	v_pk_fma_f32 v[100:101], v[50:51], v[130:131], v[100:101] op_sel:[0,0,0] op_sel_hi:[1,0,1]
	v_pk_fma_f32 v[102:103], v[50:51], v[130:131], v[102:103] op_sel:[0,1,0] op_sel_hi:[1,1,1]
	v_pk_fma_f32 v[104:105], v[50:51], v[132:133], v[104:105] op_sel:[0,0,0] op_sel_hi:[1,0,1]
	v_pk_fma_f32 v[106:107], v[50:51], v[132:133], v[106:107] op_sel:[0,1,0] op_sel_hi:[1,1,1]
	v_pk_fma_f32 v[108:109], v[50:51], v[134:135], v[108:109] op_sel:[0,0,0] op_sel_hi:[1,0,1]
	v_pk_fma_f32 v[110:111], v[50:51], v[134:135], v[110:111] op_sel:[0,1,0] op_sel_hi:[1,1,1]
	v_pk_mul_f32 v[48:49], v[96:97], v[136:137] op_sel:[0,0] op_sel_hi:[1,0]
	v_pk_mul_f32 v[50:51], v[96:97], v[156:157] op_sel:[0,0] op_sel_hi:[1,0]
	v_pk_fma_f32 v[48:49], v[98:99], v[136:137], v[48:49] op_sel:[0,1,0] op_sel_hi:[1,1,1]
	v_pk_fma_f32 v[50:51], v[98:99], v[156:157], v[50:51] op_sel:[0,1,0] op_sel_hi:[1,1,1]
	v_pk_fma_f32 v[48:49], v[100:101], v[138:139], v[48:49] op_sel:[0,0,0] op_sel_hi:[1,0,1]
	v_pk_fma_f32 v[50:51], v[100:101], v[158:159], v[50:51] op_sel:[0,0,0] op_sel_hi:[1,0,1]
	v_pk_fma_f32 v[48:49], v[102:103], v[138:139], v[48:49] op_sel:[0,1,0] op_sel_hi:[1,1,1]
	v_pk_fma_f32 v[50:51], v[102:103], v[158:159], v[50:51] op_sel:[0,1,0] op_sel_hi:[1,1,1]
	v_pk_fma_f32 v[48:49], v[104:105], v[140:141], v[48:49] op_sel:[0,0,0] op_sel_hi:[1,0,1]
	v_pk_fma_f32 v[50:51], v[104:105], v[160:161], v[50:51] op_sel:[0,0,0] op_sel_hi:[1,0,1]
	v_pk_fma_f32 v[48:49], v[106:107], v[140:141], v[48:49] op_sel:[0,1,0] op_sel_hi:[1,1,1]
	v_pk_fma_f32 v[50:51], v[106:107], v[160:161], v[50:51] op_sel:[0,1,0] op_sel_hi:[1,1,1]
	v_pk_fma_f32 v[48:49], v[108:109], v[142:143], v[48:49] op_sel:[0,0,0] op_sel_hi:[1,0,1]
	v_pk_fma_f32 v[50:51], v[108:109], v[162:163], v[50:51] op_sel:[0,0,0] op_sel_hi:[1,0,1]
	v_pk_fma_f32 v[48:49], v[110:111], v[142:143], v[48:49] op_sel:[0,1,0] op_sel_hi:[1,1,1]
	v_pk_fma_f32 v[50:51], v[110:111], v[162:163], v[50:51] op_sel:[0,1,0] op_sel_hi:[1,1,1]
	s_waitcnt lgkmcnt(11)
; #define LAS __attribute__((address_space(3)))
; __device__ __forceinline__ float red8(float x) { x += dpp_mov<0xB1>(x); x += dpp_mov<0x4E>(x); x += dpp_mov<0x141>(x); return x; }
; __device__ __forceinline__ void scan_phase(const KP& P, LAS unsigned char* lds, const int tid, const int bx, const int G) {
;     ...
;             for (int s = 0; s < 32; ++s) {
;                 const LAS float* p = cb + s * 384;
;                 const f32x4 w0 = *(const LAS f32x4*)(p), w1 = *(const LAS f32x4*)(p + 4);
;                 const f32x4 k0 = *(const LAS f32x4*)(p + 64), k1 = *(const LAS f32x4*)(p + 68);
;                 const f32x4 a0 = *(const LAS f32x4*)(p + 128), a1 = *(const LAS f32x4*)(p + 132);
;                 const f32x4 b0 = *(const LAS f32x4*)(p + 192), b1 = *(const LAS f32x4*)(p + 196);
;                 const f32x4 r0 = *(const LAS f32x4*)(p + 256), r1 = *(const LAS f32x4*)(p + 260);
;                 const float vv = buf[(c & 1) * 12288 + s * 384 + 320 + v];
;                 f32x2 sa2 = S[0] * (f32x2){a0.x, a0.y};
;                 sa2 += S[1] * (f32x2){a0.z, a0.w}; sa2 += S[2] * (f32x2){a1.x, a1.y}; sa2 += S[3] * (f32x2){a1.z, a1.w};
;                 const float sa = red8(sa2.x + sa2.y);
;                 const f32x2 sav = {sa, sa}, vv2 = {vv, vv};
;                 S[0] = S[0] * (f32x2){w0.x, w0.y} + sav * (f32x2){b0.x, b0.y} + vv2 * (f32x2){k0.x, k0.y};
;                 S[1] = S[1] * (f32x2){w0.z, w0.w} + sav * (f32x2){b0.z, b0.w} + vv2 * (f32x2){k0.z, k0.w};
;                 S[2] = S[2] * (f32x2){w1.x, w1.y} + sav * (f32x2){b1.x, b1.y} + vv2 * (f32x2){k1.x, k1.y};
;                 S[3] = S[3] * (f32x2){w1.z, w1.w} + sav * (f32x2){b1.z, b1.w} + vv2 * (f32x2){k1.z, k1.w};
;                 f32x2 y2 = S[0] * (f32x2){r0.x, r0.y};
;                 y2 += S[1] * (f32x2){r0.z, r0.w}; y2 += S[2] * (f32x2){r1.x, r1.y}; y2 += S[3] * (f32x2){r1.z, r1.w};
;                 const float y = red8(y2.x + y2.y);
;                 if (kc == 0) ybuf[s * 64 + v] = y;
	ds_read_b128 v[120:123], v44 offset:14080
	ds_read_b128 v[124:127], v44 offset:14096
	ds_read_b128 v[128:131], v44 offset:14592
	ds_read_b128 v[132:135], v44 offset:14608
	ds_read_b128 v[136:139], v44 offset:14848
	ds_read_b128 v[140:143], v44 offset:14864
	ds_read_b64 v[144:145], v46 offset:13824
	ds_read_b128 v[156:159], v44 offset:15872
	ds_read_b128 v[160:163], v44 offset:15888
	v_add_f32_dpp v48, v48, v48 quad_perm:[1,0,3,2] row_mask:0xf bank_mask:0xf bound_ctrl:1
	v_add_f32_dpp v49, v49, v49 quad_perm:[1,0,3,2] row_mask:0xf bank_mask:0xf bound_ctrl:1
	v_add_f32_dpp v50, v50, v50 quad_perm:[1,0,3,2] row_mask:0xf bank_mask:0xf bound_ctrl:1
	v_add_f32_dpp v51, v51, v51 quad_perm:[1,0,3,2] row_mask:0xf bank_mask:0xf bound_ctrl:1
	v_pk_fma_f32 v[96:97], v[146:147], v[70:71], v[96:97] op_sel:[0,0,0] op_sel_hi:[1,0,1]
	v_pk_fma_f32 v[98:99], v[146:147], v[70:71], v[98:99] op_sel:[0,1,0] op_sel_hi:[1,1,1]
	v_pk_fma_f32 v[100:101], v[146:147], v[72:73], v[100:101] op_sel:[0,0,0] op_sel_hi:[1,0,1]
	v_add_f32_dpp v48, v48, v48 quad_perm:[2,3,0,1] row_mask:0xf bank_mask:0xf bound_ctrl:1
	v_add_f32_dpp v49, v49, v49 quad_perm:[2,3,0,1] row_mask:0xf bank_mask:0xf bound_ctrl:1
	v_add_f32_dpp v50, v50, v50 quad_perm:[2,3,0,1] row_mask:0xf bank_mask:0xf bound_ctrl:1
	v_add_f32_dpp v51, v51, v51 quad_perm:[2,3,0,1] row_mask:0xf bank_mask:0xf bound_ctrl:1
	v_pk_fma_f32 v[102:103], v[146:147], v[72:73], v[102:103] op_sel:[0,1,0] op_sel_hi:[1,1,1]
	v_pk_fma_f32 v[104:105], v[146:147], v[74:75], v[104:105] op_sel:[0,0,0] op_sel_hi:[1,0,1]
	v_pk_fma_f32 v[106:107], v[146:147], v[74:75], v[106:107] op_sel:[0,1,0] op_sel_hi:[1,1,1]
	v_add_f32_dpp v48, v48, v48 row_half_mirror row_mask:0xf bank_mask:0xf bound_ctrl:1
	v_add_f32_dpp v49, v49, v49 row_half_mirror row_mask:0xf bank_mask:0xf bound_ctrl:1
	v_add_f32_dpp v50, v50, v50 row_half_mirror row_mask:0xf bank_mask:0xf bound_ctrl:1
	v_add_f32_dpp v51, v51, v51 row_half_mirror row_mask:0xf bank_mask:0xf bound_ctrl:1
	v_pk_fma_f32 v[108:109], v[146:147], v[76:77], v[108:109] op_sel:[0,0,0] op_sel_hi:[1,0,1]
	s_mov_b64 exec, s[10:11]
	ds_write_b64 v45, v[48:49] offset:1536
	s_mov_b64 exec, s[0:1]
	v_pk_fma_f32 v[110:111], v[146:147], v[76:77], v[110:111] op_sel:[0,1,0] op_sel_hi:[1,1,1]
	s_nop 0
	v_pk_fma_f32 v[96:97], v[50:51], v[78:79], v[96:97] op_sel:[0,0,0] op_sel_hi:[1,0,1]
	v_pk_fma_f32 v[98:99], v[50:51], v[78:79], v[98:99] op_sel:[0,1,0] op_sel_hi:[1,1,1]
	v_pk_fma_f32 v[100:101], v[50:51], v[80:81], v[100:101] op_sel:[0,0,0] op_sel_hi:[1,0,1]
	v_pk_fma_f32 v[102:103], v[50:51], v[80:81], v[102:103] op_sel:[0,1,0] op_sel_hi:[1,1,1]
	v_pk_fma_f32 v[104:105], v[50:51], v[82:83], v[104:105] op_sel:[0,0,0] op_sel_hi:[1,0,1]
	v_pk_fma_f32 v[106:107], v[50:51], v[82:83], v[106:107] op_sel:[0,1,0] op_sel_hi:[1,1,1]
	v_pk_fma_f32 v[108:109], v[50:51], v[84:85], v[108:109] op_sel:[0,0,0] op_sel_hi:[1,0,1]
	v_pk_fma_f32 v[110:111], v[50:51], v[84:85], v[110:111] op_sel:[0,1,0] op_sel_hi:[1,1,1]
	v_pk_mul_f32 v[48:49], v[96:97], v[86:87] op_sel:[0,0] op_sel_hi:[1,0]
	v_pk_mul_f32 v[50:51], v[96:97], v[62:63] op_sel:[0,0] op_sel_hi:[1,0]
	v_pk_fma_f32 v[48:49], v[98:99], v[86:87], v[48:49] op_sel:[0,1,0] op_sel_hi:[1,1,1]
	v_pk_fma_f32 v[50:51], v[98:99], v[62:63], v[50:51] op_sel:[0,1,0] op_sel_hi:[1,1,1]
	v_pk_fma_f32 v[48:49], v[100:101], v[88:89], v[48:49] op_sel:[0,0,0] op_sel_hi:[1,0,1]
	v_pk_fma_f32 v[50:51], v[100:101], v[64:65], v[50:51] op_sel:[0,0,0] op_sel_hi:[1,0,1]
	v_pk_fma_f32 v[48:49], v[102:103], v[88:89], v[48:49] op_sel:[0,1,0] op_sel_hi:[1,1,1]
	v_pk_fma_f32 v[50:51], v[102:103], v[64:65], v[50:51] op_sel:[0,1,0] op_sel_hi:[1,1,1]
	v_pk_fma_f32 v[48:49], v[104:105], v[90:91], v[48:49] op_sel:[0,0,0] op_sel_hi:[1,0,1]
	v_pk_fma_f32 v[50:51], v[104:105], v[66:67], v[50:51] op_sel:[0,0,0] op_sel_hi:[1,0,1]
	v_pk_fma_f32 v[48:49], v[106:107], v[90:91], v[48:49] op_sel:[0,1,0] op_sel_hi:[1,1,1]
	v_pk_fma_f32 v[50:51], v[106:107], v[66:67], v[50:51] op_sel:[0,1,0] op_sel_hi:[1,1,1]
	v_pk_fma_f32 v[48:49], v[108:109], v[92:93], v[48:49] op_sel:[0,0,0] op_sel_hi:[1,0,1]
	v_pk_fma_f32 v[50:51], v[108:109], v[68:69], v[50:51] op_sel:[0,0,0] op_sel_hi:[1,0,1]
	v_pk_fma_f32 v[48:49], v[110:111], v[92:93], v[48:49] op_sel:[0,1,0] op_sel_hi:[1,1,1]
	v_pk_fma_f32 v[50:51], v[110:111], v[68:69], v[50:51] op_sel:[0,1,0] op_sel_hi:[1,1,1]
	s_waitcnt lgkmcnt(11)
; #define LAS __attribute__((address_space(3)))
; __device__ __forceinline__ float red8(float x) { x += dpp_mov<0xB1>(x); x += dpp_mov<0x4E>(x); x += dpp_mov<0x141>(x); return x; }
; __device__ __forceinline__ void scan_phase(const KP& P, LAS unsigned char* lds, const int tid, const int bx, const int G) {
;     ...
;             for (int s = 0; s < 32; ++s) {
;                 const LAS float* p = cb + s * 384;
;                 const f32x4 w0 = *(const LAS f32x4*)(p), w1 = *(const LAS f32x4*)(p + 4);
;                 const f32x4 k0 = *(const LAS f32x4*)(p + 64), k1 = *(const LAS f32x4*)(p + 68);
;                 const f32x4 a0 = *(const LAS f32x4*)(p + 128), a1 = *(const LAS f32x4*)(p + 132);
;                 const f32x4 b0 = *(const LAS f32x4*)(p + 192), b1 = *(const LAS f32x4*)(p + 196);
;                 const f32x4 r0 = *(const LAS f32x4*)(p + 256), r1 = *(const LAS f32x4*)(p + 260);
;                 const float vv = buf[(c & 1) * 12288 + s * 384 + 320 + v];
;                 f32x2 sa2 = S[0] * (f32x2){a0.x, a0.y};
;                 sa2 += S[1] * (f32x2){a0.z, a0.w}; sa2 += S[2] * (f32x2){a1.x, a1.y}; sa2 += S[3] * (f32x2){a1.z, a1.w};
;                 const float sa = red8(sa2.x + sa2.y);
;                 const f32x2 sav = {sa, sa}, vv2 = {vv, vv};
;                 S[0] = S[0] * (f32x2){w0.x, w0.y} + sav * (f32x2){b0.x, b0.y} + vv2 * (f32x2){k0.x, k0.y};
;                 S[1] = S[1] * (f32x2){w0.z, w0.w} + sav * (f32x2){b0.z, b0.w} + vv2 * (f32x2){k0.z, k0.w};
;                 S[2] = S[2] * (f32x2){w1.x, w1.y} + sav * (f32x2){b1.x, b1.y} + vv2 * (f32x2){k1.x, k1.y};
;                 S[3] = S[3] * (f32x2){w1.z, w1.w} + sav * (f32x2){b1.z, b1.w} + vv2 * (f32x2){k1.z, k1.w};
;                 f32x2 y2 = S[0] * (f32x2){r0.x, r0.y};
;                 y2 += S[1] * (f32x2){r0.z, r0.w}; y2 += S[2] * (f32x2){r1.x, r1.y}; y2 += S[3] * (f32x2){r1.z, r1.w};
;                 const float y = red8(y2.x + y2.y);
;                 if (kc == 0) ybuf[s * 64 + v] = y;
	ds_read_b128 v[70:73], v44 offset:15616
	ds_read_b128 v[74:77], v44 offset:15632
	ds_read_b128 v[78:81], v44 offset:16128
	ds_read_b128 v[82:85], v44 offset:16144
	ds_read_b128 v[86:89], v44 offset:16384
	ds_read_b128 v[90:93], v44 offset:16400
	ds_read_b64 v[146:147], v46 offset:15360
	ds_read_b128 v[62:65], v44 offset:17408
	ds_read_b128 v[66:69], v44 offset:17424
	v_add_f32_dpp v48, v48, v48 quad_perm:[1,0,3,2] row_mask:0xf bank_mask:0xf bound_ctrl:1
	v_add_f32_dpp v49, v49, v49 quad_perm:[1,0,3,2] row_mask:0xf bank_mask:0xf bound_ctrl:1
	v_add_f32_dpp v50, v50, v50 quad_perm:[1,0,3,2] row_mask:0xf bank_mask:0xf bound_ctrl:1
	v_add_f32_dpp v51, v51, v51 quad_perm:[1,0,3,2] row_mask:0xf bank_mask:0xf bound_ctrl:1
	v_pk_fma_f32 v[96:97], v[192:193], v[168:169], v[96:97] op_sel:[0,0,0] op_sel_hi:[1,0,1]
	v_pk_fma_f32 v[98:99], v[192:193], v[168:169], v[98:99] op_sel:[0,1,0] op_sel_hi:[1,1,1]
	v_pk_fma_f32 v[100:101], v[192:193], v[170:171], v[100:101] op_sel:[0,0,0] op_sel_hi:[1,0,1]
	v_add_f32_dpp v48, v48, v48 quad_perm:[2,3,0,1] row_mask:0xf bank_mask:0xf bound_ctrl:1
	v_add_f32_dpp v49, v49, v49 quad_perm:[2,3,0,1] row_mask:0xf bank_mask:0xf bound_ctrl:1
	v_add_f32_dpp v50, v50, v50 quad_perm:[2,3,0,1] row_mask:0xf bank_mask:0xf bound_ctrl:1
	v_add_f32_dpp v51, v51, v51 quad_perm:[2,3,0,1] row_mask:0xf bank_mask:0xf bound_ctrl:1
	v_pk_fma_f32 v[102:103], v[192:193], v[170:171], v[102:103] op_sel:[0,1,0] op_sel_hi:[1,1,1]
	v_pk_fma_f32 v[104:105], v[192:193], v[172:173], v[104:105] op_sel:[0,0,0] op_sel_hi:[1,0,1]
	v_pk_fma_f32 v[106:107], v[192:193], v[172:173], v[106:107] op_sel:[0,1,0] op_sel_hi:[1,1,1]
	v_add_f32_dpp v48, v48, v48 row_half_mirror row_mask:0xf bank_mask:0xf bound_ctrl:1
	v_add_f32_dpp v49, v49, v49 row_half_mirror row_mask:0xf bank_mask:0xf bound_ctrl:1
	v_add_f32_dpp v50, v50, v50 row_half_mirror row_mask:0xf bank_mask:0xf bound_ctrl:1
	v_add_f32_dpp v51, v51, v51 row_half_mirror row_mask:0xf bank_mask:0xf bound_ctrl:1
	v_pk_fma_f32 v[108:109], v[192:193], v[174:175], v[108:109] op_sel:[0,0,0] op_sel_hi:[1,0,1]
	s_mov_b64 exec, s[10:11]
	ds_write_b64 v45, v[48:49] offset:1792
	s_mov_b64 exec, s[0:1]
	v_pk_fma_f32 v[110:111], v[192:193], v[174:175], v[110:111] op_sel:[0,1,0] op_sel_hi:[1,1,1]
	s_nop 0
	v_pk_fma_f32 v[96:97], v[50:51], v[176:177], v[96:97] op_sel:[0,0,0] op_sel_hi:[1,0,1]
	v_pk_fma_f32 v[98:99], v[50:51], v[176:177], v[98:99] op_sel:[0,1,0] op_sel_hi:[1,1,1]
	v_pk_fma_f32 v[100:101], v[50:51], v[178:179], v[100:101] op_sel:[0,0,0] op_sel_hi:[1,0,1]
	v_pk_fma_f32 v[102:103], v[50:51], v[178:179], v[102:103] op_sel:[0,1,0] op_sel_hi:[1,1,1]
	v_pk_fma_f32 v[104:105], v[50:51], v[180:181], v[104:105] op_sel:[0,0,0] op_sel_hi:[1,0,1]
	v_pk_fma_f32 v[106:107], v[50:51], v[180:181], v[106:107] op_sel:[0,1,0] op_sel_hi:[1,1,1]
	v_pk_fma_f32 v[108:109], v[50:51], v[182:183], v[108:109] op_sel:[0,0,0] op_sel_hi:[1,0,1]
	v_pk_fma_f32 v[110:111], v[50:51], v[182:183], v[110:111] op_sel:[0,1,0] op_sel_hi:[1,1,1]
	v_pk_mul_f32 v[48:49], v[96:97], v[184:185] op_sel:[0,0] op_sel_hi:[1,0]
	v_pk_mul_f32 v[50:51], v[96:97], v[148:149] op_sel:[0,0] op_sel_hi:[1,0]
	v_pk_fma_f32 v[48:49], v[98:99], v[184:185], v[48:49] op_sel:[0,1,0] op_sel_hi:[1,1,1]
	v_pk_fma_f32 v[50:51], v[98:99], v[148:149], v[50:51] op_sel:[0,1,0] op_sel_hi:[1,1,1]
	v_pk_fma_f32 v[48:49], v[100:101], v[186:187], v[48:49] op_sel:[0,0,0] op_sel_hi:[1,0,1]
	v_pk_fma_f32 v[50:51], v[100:101], v[150:151], v[50:51] op_sel:[0,0,0] op_sel_hi:[1,0,1]
	v_pk_fma_f32 v[48:49], v[102:103], v[186:187], v[48:49] op_sel:[0,1,0] op_sel_hi:[1,1,1]
	v_pk_fma_f32 v[50:51], v[102:103], v[150:151], v[50:51] op_sel:[0,1,0] op_sel_hi:[1,1,1]
	v_pk_fma_f32 v[48:49], v[104:105], v[188:189], v[48:49] op_sel:[0,0,0] op_sel_hi:[1,0,1]
	v_pk_fma_f32 v[50:51], v[104:105], v[152:153], v[50:51] op_sel:[0,0,0] op_sel_hi:[1,0,1]
	v_pk_fma_f32 v[48:49], v[106:107], v[188:189], v[48:49] op_sel:[0,1,0] op_sel_hi:[1,1,1]
	v_pk_fma_f32 v[50:51], v[106:107], v[152:153], v[50:51] op_sel:[0,1,0] op_sel_hi:[1,1,1]
	v_pk_fma_f32 v[48:49], v[108:109], v[190:191], v[48:49] op_sel:[0,0,0] op_sel_hi:[1,0,1]
	v_pk_fma_f32 v[50:51], v[108:109], v[154:155], v[50:51] op_sel:[0,0,0] op_sel_hi:[1,0,1]
	v_pk_fma_f32 v[48:49], v[110:111], v[190:191], v[48:49] op_sel:[0,1,0] op_sel_hi:[1,1,1]
	v_pk_fma_f32 v[50:51], v[110:111], v[154:155], v[50:51] op_sel:[0,1,0] op_sel_hi:[1,1,1]
	s_waitcnt lgkmcnt(11)
; #define LAS __attribute__((address_space(3)))
; __device__ __forceinline__ float red8(float x) { x += dpp_mov<0xB1>(x); x += dpp_mov<0x4E>(x); x += dpp_mov<0x141>(x); return x; }
; __device__ __forceinline__ void scan_phase(const KP& P, LAS unsigned char* lds, const int tid, const int bx, const int G) {
;     ...
;             for (int s = 0; s < 32; ++s) {
;                 const LAS float* p = cb + s * 384;
;                 const f32x4 w0 = *(const LAS f32x4*)(p), w1 = *(const LAS f32x4*)(p + 4);
;                 const f32x4 k0 = *(const LAS f32x4*)(p + 64), k1 = *(const LAS f32x4*)(p + 68);
;                 const f32x4 a0 = *(const LAS f32x4*)(p + 128), a1 = *(const LAS f32x4*)(p + 132);
;                 const f32x4 b0 = *(const LAS f32x4*)(p + 192), b1 = *(const LAS f32x4*)(p + 196);
;                 const f32x4 r0 = *(const LAS f32x4*)(p + 256), r1 = *(const LAS f32x4*)(p + 260);
;                 const float vv = buf[(c & 1) * 12288 + s * 384 + 320 + v];
;                 f32x2 sa2 = S[0] * (f32x2){a0.x, a0.y};
;                 sa2 += S[1] * (f32x2){a0.z, a0.w}; sa2 += S[2] * (f32x2){a1.x, a1.y}; sa2 += S[3] * (f32x2){a1.z, a1.w};
;                 const float sa = red8(sa2.x + sa2.y);
;                 const f32x2 sav = {sa, sa}, vv2 = {vv, vv};
;                 S[0] = S[0] * (f32x2){w0.x, w0.y} + sav * (f32x2){b0.x, b0.y} + vv2 * (f32x2){k0.x, k0.y};
;                 S[1] = S[1] * (f32x2){w0.z, w0.w} + sav * (f32x2){b0.z, b0.w} + vv2 * (f32x2){k0.z, k0.w};
;                 S[2] = S[2] * (f32x2){w1.x, w1.y} + sav * (f32x2){b1.x, b1.y} + vv2 * (f32x2){k1.x, k1.y};
;                 S[3] = S[3] * (f32x2){w1.z, w1.w} + sav * (f32x2){b1.z, b1.w} + vv2 * (f32x2){k1.z, k1.w};
;                 f32x2 y2 = S[0] * (f32x2){r0.x, r0.y};
;                 y2 += S[1] * (f32x2){r0.z, r0.w}; y2 += S[2] * (f32x2){r1.x, r1.y}; y2 += S[3] * (f32x2){r1.z, r1.w};
;                 const float y = red8(y2.x + y2.y);
;                 if (kc == 0) ybuf[s * 64 + v] = y;
	ds_read_b128 v[168:171], v44 offset:17152
	ds_read_b128 v[172:175], v44 offset:17168
	ds_read_b128 v[176:179], v44 offset:17664
	ds_read_b128 v[180:183], v44 offset:17680
	ds_read_b128 v[184:187], v44 offset:17920
	ds_read_b128 v[188:191], v44 offset:17936
	ds_read_b64 v[192:193], v46 offset:16896
	ds_read_b128 v[148:151], v44 offset:18944
	ds_read_b128 v[152:155], v44 offset:18960
	v_add_f32_dpp v48, v48, v48 quad_perm:[1,0,3,2] row_mask:0xf bank_mask:0xf bound_ctrl:1
	v_add_f32_dpp v49, v49, v49 quad_perm:[1,0,3,2] row_mask:0xf bank_mask:0xf bound_ctrl:1
	v_add_f32_dpp v50, v50, v50 quad_perm:[1,0,3,2] row_mask:0xf bank_mask:0xf bound_ctrl:1
	v_add_f32_dpp v51, v51, v51 quad_perm:[1,0,3,2] row_mask:0xf bank_mask:0xf bound_ctrl:1
	v_pk_fma_f32 v[96:97], v[144:145], v[120:121], v[96:97] op_sel:[0,0,0] op_sel_hi:[1,0,1]
	v_pk_fma_f32 v[98:99], v[144:145], v[120:121], v[98:99] op_sel:[0,1,0] op_sel_hi:[1,1,1]
	v_pk_fma_f32 v[100:101], v[144:145], v[122:123], v[100:101] op_sel:[0,0,0] op_sel_hi:[1,0,1]
	v_add_f32_dpp v48, v48, v48 quad_perm:[2,3,0,1] row_mask:0xf bank_mask:0xf bound_ctrl:1
	v_add_f32_dpp v49, v49, v49 quad_perm:[2,3,0,1] row_mask:0xf bank_mask:0xf bound_ctrl:1
	v_add_f32_dpp v50, v50, v50 quad_perm:[2,3,0,1] row_mask:0xf bank_mask:0xf bound_ctrl:1
	v_add_f32_dpp v51, v51, v51 quad_perm:[2,3,0,1] row_mask:0xf bank_mask:0xf bound_ctrl:1
	v_pk_fma_f32 v[102:103], v[144:145], v[122:123], v[102:103] op_sel:[0,1,0] op_sel_hi:[1,1,1]
	v_pk_fma_f32 v[104:105], v[144:145], v[124:125], v[104:105] op_sel:[0,0,0] op_sel_hi:[1,0,1]
	v_pk_fma_f32 v[106:107], v[144:145], v[124:125], v[106:107] op_sel:[0,1,0] op_sel_hi:[1,1,1]
	v_add_f32_dpp v48, v48, v48 row_half_mirror row_mask:0xf bank_mask:0xf bound_ctrl:1
	v_add_f32_dpp v49, v49, v49 row_half_mirror row_mask:0xf bank_mask:0xf bound_ctrl:1
	v_add_f32_dpp v50, v50, v50 row_half_mirror row_mask:0xf bank_mask:0xf bound_ctrl:1
	v_add_f32_dpp v51, v51, v51 row_half_mirror row_mask:0xf bank_mask:0xf bound_ctrl:1
	v_pk_fma_f32 v[108:109], v[144:145], v[126:127], v[108:109] op_sel:[0,0,0] op_sel_hi:[1,0,1]
	s_mov_b64 exec, s[10:11]
	ds_write_b64 v45, v[48:49] offset:2048
	s_mov_b64 exec, s[0:1]
	v_pk_fma_f32 v[110:111], v[144:145], v[126:127], v[110:111] op_sel:[0,1,0] op_sel_hi:[1,1,1]
	s_nop 0
	v_pk_fma_f32 v[96:97], v[50:51], v[128:129], v[96:97] op_sel:[0,0,0] op_sel_hi:[1,0,1]
	v_pk_fma_f32 v[98:99], v[50:51], v[128:129], v[98:99] op_sel:[0,1,0] op_sel_hi:[1,1,1]
	v_pk_fma_f32 v[100:101], v[50:51], v[130:131], v[100:101] op_sel:[0,0,0] op_sel_hi:[1,0,1]
	v_pk_fma_f32 v[102:103], v[50:51], v[130:131], v[102:103] op_sel:[0,1,0] op_sel_hi:[1,1,1]
	v_pk_fma_f32 v[104:105], v[50:51], v[132:133], v[104:105] op_sel:[0,0,0] op_sel_hi:[1,0,1]
	v_pk_fma_f32 v[106:107], v[50:51], v[132:133], v[106:107] op_sel:[0,1,0] op_sel_hi:[1,1,1]
	v_pk_fma_f32 v[108:109], v[50:51], v[134:135], v[108:109] op_sel:[0,0,0] op_sel_hi:[1,0,1]
	v_pk_fma_f32 v[110:111], v[50:51], v[134:135], v[110:111] op_sel:[0,1,0] op_sel_hi:[1,1,1]
	v_pk_mul_f32 v[48:49], v[96:97], v[136:137] op_sel:[0,0] op_sel_hi:[1,0]
	v_pk_mul_f32 v[50:51], v[96:97], v[156:157] op_sel:[0,0] op_sel_hi:[1,0]
	v_pk_fma_f32 v[48:49], v[98:99], v[136:137], v[48:49] op_sel:[0,1,0] op_sel_hi:[1,1,1]
	v_pk_fma_f32 v[50:51], v[98:99], v[156:157], v[50:51] op_sel:[0,1,0] op_sel_hi:[1,1,1]
	v_pk_fma_f32 v[48:49], v[100:101], v[138:139], v[48:49] op_sel:[0,0,0] op_sel_hi:[1,0,1]
	v_pk_fma_f32 v[50:51], v[100:101], v[158:159], v[50:51] op_sel:[0,0,0] op_sel_hi:[1,0,1]
	v_pk_fma_f32 v[48:49], v[102:103], v[138:139], v[48:49] op_sel:[0,1,0] op_sel_hi:[1,1,1]
	v_pk_fma_f32 v[50:51], v[102:103], v[158:159], v[50:51] op_sel:[0,1,0] op_sel_hi:[1,1,1]
	v_pk_fma_f32 v[48:49], v[104:105], v[140:141], v[48:49] op_sel:[0,0,0] op_sel_hi:[1,0,1]
	v_pk_fma_f32 v[50:51], v[104:105], v[160:161], v[50:51] op_sel:[0,0,0] op_sel_hi:[1,0,1]
	v_pk_fma_f32 v[48:49], v[106:107], v[140:141], v[48:49] op_sel:[0,1,0] op_sel_hi:[1,1,1]
	v_pk_fma_f32 v[50:51], v[106:107], v[160:161], v[50:51] op_sel:[0,1,0] op_sel_hi:[1,1,1]
	v_pk_fma_f32 v[48:49], v[108:109], v[142:143], v[48:49] op_sel:[0,0,0] op_sel_hi:[1,0,1]
	v_pk_fma_f32 v[50:51], v[108:109], v[162:163], v[50:51] op_sel:[0,0,0] op_sel_hi:[1,0,1]
	v_pk_fma_f32 v[48:49], v[110:111], v[142:143], v[48:49] op_sel:[0,1,0] op_sel_hi:[1,1,1]
	v_pk_fma_f32 v[50:51], v[110:111], v[162:163], v[50:51] op_sel:[0,1,0] op_sel_hi:[1,1,1]
	s_waitcnt lgkmcnt(11)
; #define LAS __attribute__((address_space(3)))
; __device__ __forceinline__ float red8(float x) { x += dpp_mov<0xB1>(x); x += dpp_mov<0x4E>(x); x += dpp_mov<0x141>(x); return x; }
; __device__ __forceinline__ void scan_phase(const KP& P, LAS unsigned char* lds, const int tid, const int bx, const int G) {
;     ...
;             for (int s = 0; s < 32; ++s) {
;                 const LAS float* p = cb + s * 384;
;                 const f32x4 w0 = *(const LAS f32x4*)(p), w1 = *(const LAS f32x4*)(p + 4);
;                 const f32x4 k0 = *(const LAS f32x4*)(p + 64), k1 = *(const LAS f32x4*)(p + 68);
;                 const f32x4 a0 = *(const LAS f32x4*)(p + 128), a1 = *(const LAS f32x4*)(p + 132);
;                 const f32x4 b0 = *(const LAS f32x4*)(p + 192), b1 = *(const LAS f32x4*)(p + 196);
;                 const f32x4 r0 = *(const LAS f32x4*)(p + 256), r1 = *(const LAS f32x4*)(p + 260);
;                 const float vv = buf[(c & 1) * 12288 + s * 384 + 320 + v];
;                 f32x2 sa2 = S[0] * (f32x2){a0.x, a0.y};
;                 sa2 += S[1] * (f32x2){a0.z, a0.w}; sa2 += S[2] * (f32x2){a1.x, a1.y}; sa2 += S[3] * (f32x2){a1.z, a1.w};
;                 const float sa = red8(sa2.x + sa2.y);
;                 const f32x2 sav = {sa, sa}, vv2 = {vv, vv};
;                 S[0] = S[0] * (f32x2){w0.x, w0.y} + sav * (f32x2){b0.x, b0.y} + vv2 * (f32x2){k0.x, k0.y};
;                 S[1] = S[1] * (f32x2){w0.z, w0.w} + sav * (f32x2){b0.z, b0.w} + vv2 * (f32x2){k0.z, k0.w};
;                 S[2] = S[2] * (f32x2){w1.x, w1.y} + sav * (f32x2){b1.x, b1.y} + vv2 * (f32x2){k1.x, k1.y};
;                 S[3] = S[3] * (f32x2){w1.z, w1.w} + sav * (f32x2){b1.z, b1.w} + vv2 * (f32x2){k1.z, k1.w};
;                 f32x2 y2 = S[0] * (f32x2){r0.x, r0.y};
;                 y2 += S[1] * (f32x2){r0.z, r0.w}; y2 += S[2] * (f32x2){r1.x, r1.y}; y2 += S[3] * (f32x2){r1.z, r1.w};
;                 const float y = red8(y2.x + y2.y);
;                 if (kc == 0) ybuf[s * 64 + v] = y;
	ds_read_b128 v[120:123], v44 offset:18688
	ds_read_b128 v[124:127], v44 offset:18704
	ds_read_b128 v[128:131], v44 offset:19200
	ds_read_b128 v[132:135], v44 offset:19216
	ds_read_b128 v[136:139], v44 offset:19456
	ds_read_b128 v[140:143], v44 offset:19472
	ds_read_b64 v[144:145], v46 offset:18432
	ds_read_b128 v[156:159], v44 offset:20480
	ds_read_b128 v[160:163], v44 offset:20496
	v_add_f32_dpp v48, v48, v48 quad_perm:[1,0,3,2] row_mask:0xf bank_mask:0xf bound_ctrl:1
	v_add_f32_dpp v49, v49, v49 quad_perm:[1,0,3,2] row_mask:0xf bank_mask:0xf bound_ctrl:1
	v_add_f32_dpp v50, v50, v50 quad_perm:[1,0,3,2] row_mask:0xf bank_mask:0xf bound_ctrl:1
	v_add_f32_dpp v51, v51, v51 quad_perm:[1,0,3,2] row_mask:0xf bank_mask:0xf bound_ctrl:1
	v_pk_fma_f32 v[96:97], v[146:147], v[70:71], v[96:97] op_sel:[0,0,0] op_sel_hi:[1,0,1]
	v_pk_fma_f32 v[98:99], v[146:147], v[70:71], v[98:99] op_sel:[0,1,0] op_sel_hi:[1,1,1]
	v_pk_fma_f32 v[100:101], v[146:147], v[72:73], v[100:101] op_sel:[0,0,0] op_sel_hi:[1,0,1]
	v_add_f32_dpp v48, v48, v48 quad_perm:[2,3,0,1] row_mask:0xf bank_mask:0xf bound_ctrl:1
	v_add_f32_dpp v49, v49, v49 quad_perm:[2,3,0,1] row_mask:0xf bank_mask:0xf bound_ctrl:1
	v_add_f32_dpp v50, v50, v50 quad_perm:[2,3,0,1] row_mask:0xf bank_mask:0xf bound_ctrl:1
	v_add_f32_dpp v51, v51, v51 quad_perm:[2,3,0,1] row_mask:0xf bank_mask:0xf bound_ctrl:1
	v_pk_fma_f32 v[102:103], v[146:147], v[72:73], v[102:103] op_sel:[0,1,0] op_sel_hi:[1,1,1]
	v_pk_fma_f32 v[104:105], v[146:147], v[74:75], v[104:105] op_sel:[0,0,0] op_sel_hi:[1,0,1]
	v_pk_fma_f32 v[106:107], v[146:147], v[74:75], v[106:107] op_sel:[0,1,0] op_sel_hi:[1,1,1]
	v_add_f32_dpp v48, v48, v48 row_half_mirror row_mask:0xf bank_mask:0xf bound_ctrl:1
	v_add_f32_dpp v49, v49, v49 row_half_mirror row_mask:0xf bank_mask:0xf bound_ctrl:1
	v_add_f32_dpp v50, v50, v50 row_half_mirror row_mask:0xf bank_mask:0xf bound_ctrl:1
	v_add_f32_dpp v51, v51, v51 row_half_mirror row_mask:0xf bank_mask:0xf bound_ctrl:1
	v_pk_fma_f32 v[108:109], v[146:147], v[76:77], v[108:109] op_sel:[0,0,0] op_sel_hi:[1,0,1]
	s_mov_b64 exec, s[10:11]
	ds_write_b64 v45, v[48:49] offset:2304
	s_mov_b64 exec, s[0:1]
	v_pk_fma_f32 v[110:111], v[146:147], v[76:77], v[110:111] op_sel:[0,1,0] op_sel_hi:[1,1,1]
	s_nop 0
	v_pk_fma_f32 v[96:97], v[50:51], v[78:79], v[96:97] op_sel:[0,0,0] op_sel_hi:[1,0,1]
	v_pk_fma_f32 v[98:99], v[50:51], v[78:79], v[98:99] op_sel:[0,1,0] op_sel_hi:[1,1,1]
	v_pk_fma_f32 v[100:101], v[50:51], v[80:81], v[100:101] op_sel:[0,0,0] op_sel_hi:[1,0,1]
	v_pk_fma_f32 v[102:103], v[50:51], v[80:81], v[102:103] op_sel:[0,1,0] op_sel_hi:[1,1,1]
	v_pk_fma_f32 v[104:105], v[50:51], v[82:83], v[104:105] op_sel:[0,0,0] op_sel_hi:[1,0,1]
	v_pk_fma_f32 v[106:107], v[50:51], v[82:83], v[106:107] op_sel:[0,1,0] op_sel_hi:[1,1,1]
	v_pk_fma_f32 v[108:109], v[50:51], v[84:85], v[108:109] op_sel:[0,0,0] op_sel_hi:[1,0,1]
	v_pk_fma_f32 v[110:111], v[50:51], v[84:85], v[110:111] op_sel:[0,1,0] op_sel_hi:[1,1,1]
	v_pk_mul_f32 v[48:49], v[96:97], v[86:87] op_sel:[0,0] op_sel_hi:[1,0]
	v_pk_mul_f32 v[50:51], v[96:97], v[62:63] op_sel:[0,0] op_sel_hi:[1,0]
	v_pk_fma_f32 v[48:49], v[98:99], v[86:87], v[48:49] op_sel:[0,1,0] op_sel_hi:[1,1,1]
	v_pk_fma_f32 v[50:51], v[98:99], v[62:63], v[50:51] op_sel:[0,1,0] op_sel_hi:[1,1,1]
	v_pk_fma_f32 v[48:49], v[100:101], v[88:89], v[48:49] op_sel:[0,0,0] op_sel_hi:[1,0,1]
	v_pk_fma_f32 v[50:51], v[100:101], v[64:65], v[50:51] op_sel:[0,0,0] op_sel_hi:[1,0,1]
	v_pk_fma_f32 v[48:49], v[102:103], v[88:89], v[48:49] op_sel:[0,1,0] op_sel_hi:[1,1,1]
	v_pk_fma_f32 v[50:51], v[102:103], v[64:65], v[50:51] op_sel:[0,1,0] op_sel_hi:[1,1,1]
	v_pk_fma_f32 v[48:49], v[104:105], v[90:91], v[48:49] op_sel:[0,0,0] op_sel_hi:[1,0,1]
	v_pk_fma_f32 v[50:51], v[104:105], v[66:67], v[50:51] op_sel:[0,0,0] op_sel_hi:[1,0,1]
	v_pk_fma_f32 v[48:49], v[106:107], v[90:91], v[48:49] op_sel:[0,1,0] op_sel_hi:[1,1,1]
	v_pk_fma_f32 v[50:51], v[106:107], v[66:67], v[50:51] op_sel:[0,1,0] op_sel_hi:[1,1,1]
	v_pk_fma_f32 v[48:49], v[108:109], v[92:93], v[48:49] op_sel:[0,0,0] op_sel_hi:[1,0,1]
	v_pk_fma_f32 v[50:51], v[108:109], v[68:69], v[50:51] op_sel:[0,0,0] op_sel_hi:[1,0,1]
	v_pk_fma_f32 v[48:49], v[110:111], v[92:93], v[48:49] op_sel:[0,1,0] op_sel_hi:[1,1,1]
	v_pk_fma_f32 v[50:51], v[110:111], v[68:69], v[50:51] op_sel:[0,1,0] op_sel_hi:[1,1,1]
	s_waitcnt lgkmcnt(11)
; #define LAS __attribute__((address_space(3)))
; __device__ __forceinline__ float red8(float x) { x += dpp_mov<0xB1>(x); x += dpp_mov<0x4E>(x); x += dpp_mov<0x141>(x); return x; }
; __device__ __forceinline__ void scan_phase(const KP& P, LAS unsigned char* lds, const int tid, const int bx, const int G) {
;     ...
;             for (int s = 0; s < 32; ++s) {
;                 const LAS float* p = cb + s * 384;
;                 const f32x4 w0 = *(const LAS f32x4*)(p), w1 = *(const LAS f32x4*)(p + 4);
;                 const f32x4 k0 = *(const LAS f32x4*)(p + 64), k1 = *(const LAS f32x4*)(p + 68);
;                 const f32x4 a0 = *(const LAS f32x4*)(p + 128), a1 = *(const LAS f32x4*)(p + 132);
;                 const f32x4 b0 = *(const LAS f32x4*)(p + 192), b1 = *(const LAS f32x4*)(p + 196);
;                 const f32x4 r0 = *(const LAS f32x4*)(p + 256), r1 = *(const LAS f32x4*)(p + 260);
;                 const float vv = buf[(c & 1) * 12288 + s * 384 + 320 + v];
;                 f32x2 sa2 = S[0] * (f32x2){a0.x, a0.y};
;                 sa2 += S[1] * (f32x2){a0.z, a0.w}; sa2 += S[2] * (f32x2){a1.x, a1.y}; sa2 += S[3] * (f32x2){a1.z, a1.w};
;                 const float sa = red8(sa2.x + sa2.y);
;                 const f32x2 sav = {sa, sa}, vv2 = {vv, vv};
;                 S[0] = S[0] * (f32x2){w0.x, w0.y} + sav * (f32x2){b0.x, b0.y} + vv2 * (f32x2){k0.x, k0.y};
;                 S[1] = S[1] * (f32x2){w0.z, w0.w} + sav * (f32x2){b0.z, b0.w} + vv2 * (f32x2){k0.z, k0.w};
;                 S[2] = S[2] * (f32x2){w1.x, w1.y} + sav * (f32x2){b1.x, b1.y} + vv2 * (f32x2){k1.x, k1.y};
;                 S[3] = S[3] * (f32x2){w1.z, w1.w} + sav * (f32x2){b1.z, b1.w} + vv2 * (f32x2){k1.z, k1.w};
;                 f32x2 y2 = S[0] * (f32x2){r0.x, r0.y};
;                 y2 += S[1] * (f32x2){r0.z, r0.w}; y2 += S[2] * (f32x2){r1.x, r1.y}; y2 += S[3] * (f32x2){r1.z, r1.w};
;                 const float y = red8(y2.x + y2.y);
;                 if (kc == 0) ybuf[s * 64 + v] = y;
	ds_read_b128 v[70:73], v44 offset:20224
	ds_read_b128 v[74:77], v44 offset:20240
	ds_read_b128 v[78:81], v44 offset:20736
	ds_read_b128 v[82:85], v44 offset:20752
	ds_read_b128 v[86:89], v44 offset:20992
	ds_read_b128 v[90:93], v44 offset:21008
	ds_read_b64 v[146:147], v46 offset:19968
	ds_read_b128 v[62:65], v44 offset:22016
	ds_read_b128 v[66:69], v44 offset:22032
	v_add_f32_dpp v48, v48, v48 quad_perm:[1,0,3,2] row_mask:0xf bank_mask:0xf bound_ctrl:1
	v_add_f32_dpp v49, v49, v49 quad_perm:[1,0,3,2] row_mask:0xf bank_mask:0xf bound_ctrl:1
	v_add_f32_dpp v50, v50, v50 quad_perm:[1,0,3,2] row_mask:0xf bank_mask:0xf bound_ctrl:1
	v_add_f32_dpp v51, v51, v51 quad_perm:[1,0,3,2] row_mask:0xf bank_mask:0xf bound_ctrl:1
	v_pk_fma_f32 v[96:97], v[192:193], v[168:169], v[96:97] op_sel:[0,0,0] op_sel_hi:[1,0,1]
	v_pk_fma_f32 v[98:99], v[192:193], v[168:169], v[98:99] op_sel:[0,1,0] op_sel_hi:[1,1,1]
	v_pk_fma_f32 v[100:101], v[192:193], v[170:171], v[100:101] op_sel:[0,0,0] op_sel_hi:[1,0,1]
	v_add_f32_dpp v48, v48, v48 quad_perm:[2,3,0,1] row_mask:0xf bank_mask:0xf bound_ctrl:1
	v_add_f32_dpp v49, v49, v49 quad_perm:[2,3,0,1] row_mask:0xf bank_mask:0xf bound_ctrl:1
	v_add_f32_dpp v50, v50, v50 quad_perm:[2,3,0,1] row_mask:0xf bank_mask:0xf bound_ctrl:1
	v_add_f32_dpp v51, v51, v51 quad_perm:[2,3,0,1] row_mask:0xf bank_mask:0xf bound_ctrl:1
	v_pk_fma_f32 v[102:103], v[192:193], v[170:171], v[102:103] op_sel:[0,1,0] op_sel_hi:[1,1,1]
	v_pk_fma_f32 v[104:105], v[192:193], v[172:173], v[104:105] op_sel:[0,0,0] op_sel_hi:[1,0,1]
	v_pk_fma_f32 v[106:107], v[192:193], v[172:173], v[106:107] op_sel:[0,1,0] op_sel_hi:[1,1,1]
	v_add_f32_dpp v48, v48, v48 row_half_mirror row_mask:0xf bank_mask:0xf bound_ctrl:1
	v_add_f32_dpp v49, v49, v49 row_half_mirror row_mask:0xf bank_mask:0xf bound_ctrl:1
	v_add_f32_dpp v50, v50, v50 row_half_mirror row_mask:0xf bank_mask:0xf bound_ctrl:1
	v_add_f32_dpp v51, v51, v51 row_half_mirror row_mask:0xf bank_mask:0xf bound_ctrl:1
	v_pk_fma_f32 v[108:109], v[192:193], v[174:175], v[108:109] op_sel:[0,0,0] op_sel_hi:[1,0,1]
	s_mov_b64 exec, s[10:11]
	ds_write_b64 v45, v[48:49] offset:2560
	s_mov_b64 exec, s[0:1]
	v_pk_fma_f32 v[110:111], v[192:193], v[174:175], v[110:111] op_sel:[0,1,0] op_sel_hi:[1,1,1]
	s_nop 0
	v_pk_fma_f32 v[96:97], v[50:51], v[176:177], v[96:97] op_sel:[0,0,0] op_sel_hi:[1,0,1]
	v_pk_fma_f32 v[98:99], v[50:51], v[176:177], v[98:99] op_sel:[0,1,0] op_sel_hi:[1,1,1]
	v_pk_fma_f32 v[100:101], v[50:51], v[178:179], v[100:101] op_sel:[0,0,0] op_sel_hi:[1,0,1]
	v_pk_fma_f32 v[102:103], v[50:51], v[178:179], v[102:103] op_sel:[0,1,0] op_sel_hi:[1,1,1]
	v_pk_fma_f32 v[104:105], v[50:51], v[180:181], v[104:105] op_sel:[0,0,0] op_sel_hi:[1,0,1]
	v_pk_fma_f32 v[106:107], v[50:51], v[180:181], v[106:107] op_sel:[0,1,0] op_sel_hi:[1,1,1]
	v_pk_fma_f32 v[108:109], v[50:51], v[182:183], v[108:109] op_sel:[0,0,0] op_sel_hi:[1,0,1]
	v_pk_fma_f32 v[110:111], v[50:51], v[182:183], v[110:111] op_sel:[0,1,0] op_sel_hi:[1,1,1]
	v_pk_mul_f32 v[48:49], v[96:97], v[184:185] op_sel:[0,0] op_sel_hi:[1,0]
	v_pk_mul_f32 v[50:51], v[96:97], v[148:149] op_sel:[0,0] op_sel_hi:[1,0]
	v_pk_fma_f32 v[48:49], v[98:99], v[184:185], v[48:49] op_sel:[0,1,0] op_sel_hi:[1,1,1]
	v_pk_fma_f32 v[50:51], v[98:99], v[148:149], v[50:51] op_sel:[0,1,0] op_sel_hi:[1,1,1]
	v_pk_fma_f32 v[48:49], v[100:101], v[186:187], v[48:49] op_sel:[0,0,0] op_sel_hi:[1,0,1]
	v_pk_fma_f32 v[50:51], v[100:101], v[150:151], v[50:51] op_sel:[0,0,0] op_sel_hi:[1,0,1]
	v_pk_fma_f32 v[48:49], v[102:103], v[186:187], v[48:49] op_sel:[0,1,0] op_sel_hi:[1,1,1]
	v_pk_fma_f32 v[50:51], v[102:103], v[150:151], v[50:51] op_sel:[0,1,0] op_sel_hi:[1,1,1]
	v_pk_fma_f32 v[48:49], v[104:105], v[188:189], v[48:49] op_sel:[0,0,0] op_sel_hi:[1,0,1]
	v_pk_fma_f32 v[50:51], v[104:105], v[152:153], v[50:51] op_sel:[0,0,0] op_sel_hi:[1,0,1]
	v_pk_fma_f32 v[48:49], v[106:107], v[188:189], v[48:49] op_sel:[0,1,0] op_sel_hi:[1,1,1]
	v_pk_fma_f32 v[50:51], v[106:107], v[152:153], v[50:51] op_sel:[0,1,0] op_sel_hi:[1,1,1]
	v_pk_fma_f32 v[48:49], v[108:109], v[190:191], v[48:49] op_sel:[0,0,0] op_sel_hi:[1,0,1]
	v_pk_fma_f32 v[50:51], v[108:109], v[154:155], v[50:51] op_sel:[0,0,0] op_sel_hi:[1,0,1]
	v_pk_fma_f32 v[48:49], v[110:111], v[190:191], v[48:49] op_sel:[0,1,0] op_sel_hi:[1,1,1]
	v_pk_fma_f32 v[50:51], v[110:111], v[154:155], v[50:51] op_sel:[0,1,0] op_sel_hi:[1,1,1]
	s_waitcnt lgkmcnt(11)
; #define LAS __attribute__((address_space(3)))
; __device__ __forceinline__ float red8(float x) { x += dpp_mov<0xB1>(x); x += dpp_mov<0x4E>(x); x += dpp_mov<0x141>(x); return x; }
; __device__ __forceinline__ void scan_phase(const KP& P, LAS unsigned char* lds, const int tid, const int bx, const int G) {
;     ...
;             for (int s = 0; s < 32; ++s) {
;                 const LAS float* p = cb + s * 384;
;                 const f32x4 w0 = *(const LAS f32x4*)(p), w1 = *(const LAS f32x4*)(p + 4);
;                 const f32x4 k0 = *(const LAS f32x4*)(p + 64), k1 = *(const LAS f32x4*)(p + 68);
;                 const f32x4 a0 = *(const LAS f32x4*)(p + 128), a1 = *(const LAS f32x4*)(p + 132);
;                 const f32x4 b0 = *(const LAS f32x4*)(p + 192), b1 = *(const LAS f32x4*)(p + 196);
;                 const f32x4 r0 = *(const LAS f32x4*)(p + 256), r1 = *(const LAS f32x4*)(p + 260);
;                 const float vv = buf[(c & 1) * 12288 + s * 384 + 320 + v];
;                 f32x2 sa2 = S[0] * (f32x2){a0.x, a0.y};
;                 sa2 += S[1] * (f32x2){a0.z, a0.w}; sa2 += S[2] * (f32x2){a1.x, a1.y}; sa2 += S[3] * (f32x2){a1.z, a1.w};
;                 const float sa = red8(sa2.x + sa2.y);
;                 const f32x2 sav = {sa, sa}, vv2 = {vv, vv};
;                 S[0] = S[0] * (f32x2){w0.x, w0.y} + sav * (f32x2){b0.x, b0.y} + vv2 * (f32x2){k0.x, k0.y};
;                 S[1] = S[1] * (f32x2){w0.z, w0.w} + sav * (f32x2){b0.z, b0.w} + vv2 * (f32x2){k0.z, k0.w};
;                 S[2] = S[2] * (f32x2){w1.x, w1.y} + sav * (f32x2){b1.x, b1.y} + vv2 * (f32x2){k1.x, k1.y};
;                 S[3] = S[3] * (f32x2){w1.z, w1.w} + sav * (f32x2){b1.z, b1.w} + vv2 * (f32x2){k1.z, k1.w};
;                 f32x2 y2 = S[0] * (f32x2){r0.x, r0.y};
;                 y2 += S[1] * (f32x2){r0.z, r0.w}; y2 += S[2] * (f32x2){r1.x, r1.y}; y2 += S[3] * (f32x2){r1.z, r1.w};
;                 const float y = red8(y2.x + y2.y);
;                 if (kc == 0) ybuf[s * 64 + v] = y;
	ds_read_b128 v[168:171], v44 offset:21760
	ds_read_b128 v[172:175], v44 offset:21776
	ds_read_b128 v[176:179], v44 offset:22272
	ds_read_b128 v[180:183], v44 offset:22288
	ds_read_b128 v[184:187], v44 offset:22528
	ds_read_b128 v[188:191], v44 offset:22544
	ds_read_b64 v[192:193], v46 offset:21504
	ds_read_b128 v[148:151], v44 offset:23552
	ds_read_b128 v[152:155], v44 offset:23568
	v_add_f32_dpp v48, v48, v48 quad_perm:[1,0,3,2] row_mask:0xf bank_mask:0xf bound_ctrl:1
	v_add_f32_dpp v49, v49, v49 quad_perm:[1,0,3,2] row_mask:0xf bank_mask:0xf bound_ctrl:1
	v_add_f32_dpp v50, v50, v50 quad_perm:[1,0,3,2] row_mask:0xf bank_mask:0xf bound_ctrl:1
	v_add_f32_dpp v51, v51, v51 quad_perm:[1,0,3,2] row_mask:0xf bank_mask:0xf bound_ctrl:1
	v_pk_fma_f32 v[96:97], v[144:145], v[120:121], v[96:97] op_sel:[0,0,0] op_sel_hi:[1,0,1]
	v_pk_fma_f32 v[98:99], v[144:145], v[120:121], v[98:99] op_sel:[0,1,0] op_sel_hi:[1,1,1]
	v_pk_fma_f32 v[100:101], v[144:145], v[122:123], v[100:101] op_sel:[0,0,0] op_sel_hi:[1,0,1]
	v_add_f32_dpp v48, v48, v48 quad_perm:[2,3,0,1] row_mask:0xf bank_mask:0xf bound_ctrl:1
	v_add_f32_dpp v49, v49, v49 quad_perm:[2,3,0,1] row_mask:0xf bank_mask:0xf bound_ctrl:1
	v_add_f32_dpp v50, v50, v50 quad_perm:[2,3,0,1] row_mask:0xf bank_mask:0xf bound_ctrl:1
	v_add_f32_dpp v51, v51, v51 quad_perm:[2,3,0,1] row_mask:0xf bank_mask:0xf bound_ctrl:1
	v_pk_fma_f32 v[102:103], v[144:145], v[122:123], v[102:103] op_sel:[0,1,0] op_sel_hi:[1,1,1]
	v_pk_fma_f32 v[104:105], v[144:145], v[124:125], v[104:105] op_sel:[0,0,0] op_sel_hi:[1,0,1]
	v_pk_fma_f32 v[106:107], v[144:145], v[124:125], v[106:107] op_sel:[0,1,0] op_sel_hi:[1,1,1]
	v_add_f32_dpp v48, v48, v48 row_half_mirror row_mask:0xf bank_mask:0xf bound_ctrl:1
	v_add_f32_dpp v49, v49, v49 row_half_mirror row_mask:0xf bank_mask:0xf bound_ctrl:1
	v_add_f32_dpp v50, v50, v50 row_half_mirror row_mask:0xf bank_mask:0xf bound_ctrl:1
	v_add_f32_dpp v51, v51, v51 row_half_mirror row_mask:0xf bank_mask:0xf bound_ctrl:1
	v_pk_fma_f32 v[108:109], v[144:145], v[126:127], v[108:109] op_sel:[0,0,0] op_sel_hi:[1,0,1]
	s_mov_b64 exec, s[10:11]
	ds_write_b64 v45, v[48:49] offset:2816
	s_mov_b64 exec, s[0:1]
	v_pk_fma_f32 v[110:111], v[144:145], v[126:127], v[110:111] op_sel:[0,1,0] op_sel_hi:[1,1,1]
	s_nop 0
	v_pk_fma_f32 v[96:97], v[50:51], v[128:129], v[96:97] op_sel:[0,0,0] op_sel_hi:[1,0,1]
	v_pk_fma_f32 v[98:99], v[50:51], v[128:129], v[98:99] op_sel:[0,1,0] op_sel_hi:[1,1,1]
	v_pk_fma_f32 v[100:101], v[50:51], v[130:131], v[100:101] op_sel:[0,0,0] op_sel_hi:[1,0,1]
	v_pk_fma_f32 v[102:103], v[50:51], v[130:131], v[102:103] op_sel:[0,1,0] op_sel_hi:[1,1,1]
	v_pk_fma_f32 v[104:105], v[50:51], v[132:133], v[104:105] op_sel:[0,0,0] op_sel_hi:[1,0,1]
	v_pk_fma_f32 v[106:107], v[50:51], v[132:133], v[106:107] op_sel:[0,1,0] op_sel_hi:[1,1,1]
	v_pk_fma_f32 v[108:109], v[50:51], v[134:135], v[108:109] op_sel:[0,0,0] op_sel_hi:[1,0,1]
	v_pk_fma_f32 v[110:111], v[50:51], v[134:135], v[110:111] op_sel:[0,1,0] op_sel_hi:[1,1,1]
	v_pk_mul_f32 v[48:49], v[96:97], v[136:137] op_sel:[0,0] op_sel_hi:[1,0]
	v_pk_mul_f32 v[50:51], v[96:97], v[156:157] op_sel:[0,0] op_sel_hi:[1,0]
	v_pk_fma_f32 v[48:49], v[98:99], v[136:137], v[48:49] op_sel:[0,1,0] op_sel_hi:[1,1,1]
	v_pk_fma_f32 v[50:51], v[98:99], v[156:157], v[50:51] op_sel:[0,1,0] op_sel_hi:[1,1,1]
	v_pk_fma_f32 v[48:49], v[100:101], v[138:139], v[48:49] op_sel:[0,0,0] op_sel_hi:[1,0,1]
	v_pk_fma_f32 v[50:51], v[100:101], v[158:159], v[50:51] op_sel:[0,0,0] op_sel_hi:[1,0,1]
	v_pk_fma_f32 v[48:49], v[102:103], v[138:139], v[48:49] op_sel:[0,1,0] op_sel_hi:[1,1,1]
	v_pk_fma_f32 v[50:51], v[102:103], v[158:159], v[50:51] op_sel:[0,1,0] op_sel_hi:[1,1,1]
	v_pk_fma_f32 v[48:49], v[104:105], v[140:141], v[48:49] op_sel:[0,0,0] op_sel_hi:[1,0,1]
	v_pk_fma_f32 v[50:51], v[104:105], v[160:161], v[50:51] op_sel:[0,0,0] op_sel_hi:[1,0,1]
	v_pk_fma_f32 v[48:49], v[106:107], v[140:141], v[48:49] op_sel:[0,1,0] op_sel_hi:[1,1,1]
	v_pk_fma_f32 v[50:51], v[106:107], v[160:161], v[50:51] op_sel:[0,1,0] op_sel_hi:[1,1,1]
	v_pk_fma_f32 v[48:49], v[108:109], v[142:143], v[48:49] op_sel:[0,0,0] op_sel_hi:[1,0,1]
	v_pk_fma_f32 v[50:51], v[108:109], v[162:163], v[50:51] op_sel:[0,0,0] op_sel_hi:[1,0,1]
	v_pk_fma_f32 v[48:49], v[110:111], v[142:143], v[48:49] op_sel:[0,1,0] op_sel_hi:[1,1,1]
	v_pk_fma_f32 v[50:51], v[110:111], v[162:163], v[50:51] op_sel:[0,1,0] op_sel_hi:[1,1,1]
	s_waitcnt lgkmcnt(11)
; #define LAS __attribute__((address_space(3)))
; __device__ __forceinline__ float red8(float x) { x += dpp_mov<0xB1>(x); x += dpp_mov<0x4E>(x); x += dpp_mov<0x141>(x); return x; }
; __device__ __forceinline__ void scan_phase(const KP& P, LAS unsigned char* lds, const int tid, const int bx, const int G) {
;     ...
;             for (int s = 0; s < 32; ++s) {
;                 const LAS float* p = cb + s * 384;
;                 const f32x4 w0 = *(const LAS f32x4*)(p), w1 = *(const LAS f32x4*)(p + 4);
;                 const f32x4 k0 = *(const LAS f32x4*)(p + 64), k1 = *(const LAS f32x4*)(p + 68);
;                 const f32x4 a0 = *(const LAS f32x4*)(p + 128), a1 = *(const LAS f32x4*)(p + 132);
;                 const f32x4 b0 = *(const LAS f32x4*)(p + 192), b1 = *(const LAS f32x4*)(p + 196);
;                 const f32x4 r0 = *(const LAS f32x4*)(p + 256), r1 = *(const LAS f32x4*)(p + 260);
;                 const float vv = buf[(c & 1) * 12288 + s * 384 + 320 + v];
;                 f32x2 sa2 = S[0] * (f32x2){a0.x, a0.y};
;                 sa2 += S[1] * (f32x2){a0.z, a0.w}; sa2 += S[2] * (f32x2){a1.x, a1.y}; sa2 += S[3] * (f32x2){a1.z, a1.w};
;                 const float sa = red8(sa2.x + sa2.y);
;                 const f32x2 sav = {sa, sa}, vv2 = {vv, vv};
;                 S[0] = S[0] * (f32x2){w0.x, w0.y} + sav * (f32x2){b0.x, b0.y} + vv2 * (f32x2){k0.x, k0.y};
;                 S[1] = S[1] * (f32x2){w0.z, w0.w} + sav * (f32x2){b0.z, b0.w} + vv2 * (f32x2){k0.z, k0.w};
;                 S[2] = S[2] * (f32x2){w1.x, w1.y} + sav * (f32x2){b1.x, b1.y} + vv2 * (f32x2){k1.x, k1.y};
;                 S[3] = S[3] * (f32x2){w1.z, w1.w} + sav * (f32x2){b1.z, b1.w} + vv2 * (f32x2){k1.z, k1.w};
;                 f32x2 y2 = S[0] * (f32x2){r0.x, r0.y};
;                 y2 += S[1] * (f32x2){r0.z, r0.w}; y2 += S[2] * (f32x2){r1.x, r1.y}; y2 += S[3] * (f32x2){r1.z, r1.w};
;                 const float y = red8(y2.x + y2.y);
;                 if (kc == 0) ybuf[s * 64 + v] = y;
	ds_read_b128 v[120:123], v44 offset:23296
	ds_read_b128 v[124:127], v44 offset:23312
	ds_read_b128 v[128:131], v44 offset:23808
	ds_read_b128 v[132:135], v44 offset:23824
	ds_read_b128 v[136:139], v44 offset:24064
	ds_read_b128 v[140:143], v44 offset:24080
	ds_read_b64 v[144:145], v46 offset:23040
	ds_read_b128 v[156:159], v44 offset:25088
	ds_read_b128 v[160:163], v44 offset:25104
	v_add_f32_dpp v48, v48, v48 quad_perm:[1,0,3,2] row_mask:0xf bank_mask:0xf bound_ctrl:1
	v_add_f32_dpp v49, v49, v49 quad_perm:[1,0,3,2] row_mask:0xf bank_mask:0xf bound_ctrl:1
	v_add_f32_dpp v50, v50, v50 quad_perm:[1,0,3,2] row_mask:0xf bank_mask:0xf bound_ctrl:1
	v_add_f32_dpp v51, v51, v51 quad_perm:[1,0,3,2] row_mask:0xf bank_mask:0xf bound_ctrl:1
	v_pk_fma_f32 v[96:97], v[146:147], v[70:71], v[96:97] op_sel:[0,0,0] op_sel_hi:[1,0,1]
	v_pk_fma_f32 v[98:99], v[146:147], v[70:71], v[98:99] op_sel:[0,1,0] op_sel_hi:[1,1,1]
	v_pk_fma_f32 v[100:101], v[146:147], v[72:73], v[100:101] op_sel:[0,0,0] op_sel_hi:[1,0,1]
	v_add_f32_dpp v48, v48, v48 quad_perm:[2,3,0,1] row_mask:0xf bank_mask:0xf bound_ctrl:1
	v_add_f32_dpp v49, v49, v49 quad_perm:[2,3,0,1] row_mask:0xf bank_mask:0xf bound_ctrl:1
	v_add_f32_dpp v50, v50, v50 quad_perm:[2,3,0,1] row_mask:0xf bank_mask:0xf bound_ctrl:1
	v_add_f32_dpp v51, v51, v51 quad_perm:[2,3,0,1] row_mask:0xf bank_mask:0xf bound_ctrl:1
	v_pk_fma_f32 v[102:103], v[146:147], v[72:73], v[102:103] op_sel:[0,1,0] op_sel_hi:[1,1,1]
	v_pk_fma_f32 v[104:105], v[146:147], v[74:75], v[104:105] op_sel:[0,0,0] op_sel_hi:[1,0,1]
	v_pk_fma_f32 v[106:107], v[146:147], v[74:75], v[106:107] op_sel:[0,1,0] op_sel_hi:[1,1,1]
	v_add_f32_dpp v48, v48, v48 row_half_mirror row_mask:0xf bank_mask:0xf bound_ctrl:1
	v_add_f32_dpp v49, v49, v49 row_half_mirror row_mask:0xf bank_mask:0xf bound_ctrl:1
	v_add_f32_dpp v50, v50, v50 row_half_mirror row_mask:0xf bank_mask:0xf bound_ctrl:1
	v_add_f32_dpp v51, v51, v51 row_half_mirror row_mask:0xf bank_mask:0xf bound_ctrl:1
	v_pk_fma_f32 v[108:109], v[146:147], v[76:77], v[108:109] op_sel:[0,0,0] op_sel_hi:[1,0,1]
	s_mov_b64 exec, s[10:11]
	ds_write_b64 v45, v[48:49] offset:3072
	s_mov_b64 exec, s[0:1]
	v_pk_fma_f32 v[110:111], v[146:147], v[76:77], v[110:111] op_sel:[0,1,0] op_sel_hi:[1,1,1]
	s_nop 0
	v_pk_fma_f32 v[96:97], v[50:51], v[78:79], v[96:97] op_sel:[0,0,0] op_sel_hi:[1,0,1]
	v_pk_fma_f32 v[98:99], v[50:51], v[78:79], v[98:99] op_sel:[0,1,0] op_sel_hi:[1,1,1]
	v_pk_fma_f32 v[100:101], v[50:51], v[80:81], v[100:101] op_sel:[0,0,0] op_sel_hi:[1,0,1]
	v_pk_fma_f32 v[102:103], v[50:51], v[80:81], v[102:103] op_sel:[0,1,0] op_sel_hi:[1,1,1]
	v_pk_fma_f32 v[104:105], v[50:51], v[82:83], v[104:105] op_sel:[0,0,0] op_sel_hi:[1,0,1]
	v_pk_fma_f32 v[106:107], v[50:51], v[82:83], v[106:107] op_sel:[0,1,0] op_sel_hi:[1,1,1]
	v_pk_fma_f32 v[108:109], v[50:51], v[84:85], v[108:109] op_sel:[0,0,0] op_sel_hi:[1,0,1]
	v_pk_fma_f32 v[110:111], v[50:51], v[84:85], v[110:111] op_sel:[0,1,0] op_sel_hi:[1,1,1]
	v_pk_mul_f32 v[48:49], v[96:97], v[86:87] op_sel:[0,0] op_sel_hi:[1,0]
	v_pk_mul_f32 v[50:51], v[96:97], v[62:63] op_sel:[0,0] op_sel_hi:[1,0]
	v_pk_fma_f32 v[48:49], v[98:99], v[86:87], v[48:49] op_sel:[0,1,0] op_sel_hi:[1,1,1]
	v_pk_fma_f32 v[50:51], v[98:99], v[62:63], v[50:51] op_sel:[0,1,0] op_sel_hi:[1,1,1]
	v_pk_fma_f32 v[48:49], v[100:101], v[88:89], v[48:49] op_sel:[0,0,0] op_sel_hi:[1,0,1]
	v_pk_fma_f32 v[50:51], v[100:101], v[64:65], v[50:51] op_sel:[0,0,0] op_sel_hi:[1,0,1]
	v_pk_fma_f32 v[48:49], v[102:103], v[88:89], v[48:49] op_sel:[0,1,0] op_sel_hi:[1,1,1]
	v_pk_fma_f32 v[50:51], v[102:103], v[64:65], v[50:51] op_sel:[0,1,0] op_sel_hi:[1,1,1]
	v_pk_fma_f32 v[48:49], v[104:105], v[90:91], v[48:49] op_sel:[0,0,0] op_sel_hi:[1,0,1]
	v_pk_fma_f32 v[50:51], v[104:105], v[66:67], v[50:51] op_sel:[0,0,0] op_sel_hi:[1,0,1]
	v_pk_fma_f32 v[48:49], v[106:107], v[90:91], v[48:49] op_sel:[0,1,0] op_sel_hi:[1,1,1]
	v_pk_fma_f32 v[50:51], v[106:107], v[66:67], v[50:51] op_sel:[0,1,0] op_sel_hi:[1,1,1]
	v_pk_fma_f32 v[48:49], v[108:109], v[92:93], v[48:49] op_sel:[0,0,0] op_sel_hi:[1,0,1]
	v_pk_fma_f32 v[50:51], v[108:109], v[68:69], v[50:51] op_sel:[0,0,0] op_sel_hi:[1,0,1]
	v_pk_fma_f32 v[48:49], v[110:111], v[92:93], v[48:49] op_sel:[0,1,0] op_sel_hi:[1,1,1]
	v_pk_fma_f32 v[50:51], v[110:111], v[68:69], v[50:51] op_sel:[0,1,0] op_sel_hi:[1,1,1]
	s_waitcnt lgkmcnt(11)
; #define LAS __attribute__((address_space(3)))
; __device__ __forceinline__ float red8(float x) { x += dpp_mov<0xB1>(x); x += dpp_mov<0x4E>(x); x += dpp_mov<0x141>(x); return x; }
; __device__ __forceinline__ void scan_phase(const KP& P, LAS unsigned char* lds, const int tid, const int bx, const int G) {
;     ...
;             for (int s = 0; s < 32; ++s) {
;                 const LAS float* p = cb + s * 384;
;                 const f32x4 w0 = *(const LAS f32x4*)(p), w1 = *(const LAS f32x4*)(p + 4);
;                 const f32x4 k0 = *(const LAS f32x4*)(p + 64), k1 = *(const LAS f32x4*)(p + 68);
;                 const f32x4 a0 = *(const LAS f32x4*)(p + 128), a1 = *(const LAS f32x4*)(p + 132);
;                 const f32x4 b0 = *(const LAS f32x4*)(p + 192), b1 = *(const LAS f32x4*)(p + 196);
;                 const f32x4 r0 = *(const LAS f32x4*)(p + 256), r1 = *(const LAS f32x4*)(p + 260);
;                 const float vv = buf[(c & 1) * 12288 + s * 384 + 320 + v];
;                 f32x2 sa2 = S[0] * (f32x2){a0.x, a0.y};
;                 sa2 += S[1] * (f32x2){a0.z, a0.w}; sa2 += S[2] * (f32x2){a1.x, a1.y}; sa2 += S[3] * (f32x2){a1.z, a1.w};
;                 const float sa = red8(sa2.x + sa2.y);
;                 const f32x2 sav = {sa, sa}, vv2 = {vv, vv};
;                 S[0] = S[0] * (f32x2){w0.x, w0.y} + sav * (f32x2){b0.x, b0.y} + vv2 * (f32x2){k0.x, k0.y};
;                 S[1] = S[1] * (f32x2){w0.z, w0.w} + sav * (f32x2){b0.z, b0.w} + vv2 * (f32x2){k0.z, k0.w};
;                 S[2] = S[2] * (f32x2){w1.x, w1.y} + sav * (f32x2){b1.x, b1.y} + vv2 * (f32x2){k1.x, k1.y};
;                 S[3] = S[3] * (f32x2){w1.z, w1.w} + sav * (f32x2){b1.z, b1.w} + vv2 * (f32x2){k1.z, k1.w};
;                 f32x2 y2 = S[0] * (f32x2){r0.x, r0.y};
;                 y2 += S[1] * (f32x2){r0.z, r0.w}; y2 += S[2] * (f32x2){r1.x, r1.y}; y2 += S[3] * (f32x2){r1.z, r1.w};
;                 const float y = red8(y2.x + y2.y);
;                 if (kc == 0) ybuf[s * 64 + v] = y;
	ds_read_b128 v[70:73], v44 offset:24832
	ds_read_b128 v[74:77], v44 offset:24848
	ds_read_b128 v[78:81], v44 offset:25344
	ds_read_b128 v[82:85], v44 offset:25360
	ds_read_b128 v[86:89], v44 offset:25600
	ds_read_b128 v[90:93], v44 offset:25616
	ds_read_b64 v[146:147], v46 offset:24576
	ds_read_b128 v[62:65], v44 offset:26624
	ds_read_b128 v[66:69], v44 offset:26640
	v_add_f32_dpp v48, v48, v48 quad_perm:[1,0,3,2] row_mask:0xf bank_mask:0xf bound_ctrl:1
	v_add_f32_dpp v49, v49, v49 quad_perm:[1,0,3,2] row_mask:0xf bank_mask:0xf bound_ctrl:1
	v_add_f32_dpp v50, v50, v50 quad_perm:[1,0,3,2] row_mask:0xf bank_mask:0xf bound_ctrl:1
	v_add_f32_dpp v51, v51, v51 quad_perm:[1,0,3,2] row_mask:0xf bank_mask:0xf bound_ctrl:1
	v_pk_fma_f32 v[96:97], v[192:193], v[168:169], v[96:97] op_sel:[0,0,0] op_sel_hi:[1,0,1]
	v_pk_fma_f32 v[98:99], v[192:193], v[168:169], v[98:99] op_sel:[0,1,0] op_sel_hi:[1,1,1]
	v_pk_fma_f32 v[100:101], v[192:193], v[170:171], v[100:101] op_sel:[0,0,0] op_sel_hi:[1,0,1]
	v_add_f32_dpp v48, v48, v48 quad_perm:[2,3,0,1] row_mask:0xf bank_mask:0xf bound_ctrl:1
	v_add_f32_dpp v49, v49, v49 quad_perm:[2,3,0,1] row_mask:0xf bank_mask:0xf bound_ctrl:1
	v_add_f32_dpp v50, v50, v50 quad_perm:[2,3,0,1] row_mask:0xf bank_mask:0xf bound_ctrl:1
	v_add_f32_dpp v51, v51, v51 quad_perm:[2,3,0,1] row_mask:0xf bank_mask:0xf bound_ctrl:1
	v_pk_fma_f32 v[102:103], v[192:193], v[170:171], v[102:103] op_sel:[0,1,0] op_sel_hi:[1,1,1]
	v_pk_fma_f32 v[104:105], v[192:193], v[172:173], v[104:105] op_sel:[0,0,0] op_sel_hi:[1,0,1]
	v_pk_fma_f32 v[106:107], v[192:193], v[172:173], v[106:107] op_sel:[0,1,0] op_sel_hi:[1,1,1]
	v_add_f32_dpp v48, v48, v48 row_half_mirror row_mask:0xf bank_mask:0xf bound_ctrl:1
	v_add_f32_dpp v49, v49, v49 row_half_mirror row_mask:0xf bank_mask:0xf bound_ctrl:1
	v_add_f32_dpp v50, v50, v50 row_half_mirror row_mask:0xf bank_mask:0xf bound_ctrl:1
	v_add_f32_dpp v51, v51, v51 row_half_mirror row_mask:0xf bank_mask:0xf bound_ctrl:1
	v_pk_fma_f32 v[108:109], v[192:193], v[174:175], v[108:109] op_sel:[0,0,0] op_sel_hi:[1,0,1]
	s_mov_b64 exec, s[10:11]
	ds_write_b64 v45, v[48:49] offset:3328
	s_mov_b64 exec, s[0:1]
	v_pk_fma_f32 v[110:111], v[192:193], v[174:175], v[110:111] op_sel:[0,1,0] op_sel_hi:[1,1,1]
	s_nop 0
	v_pk_fma_f32 v[96:97], v[50:51], v[176:177], v[96:97] op_sel:[0,0,0] op_sel_hi:[1,0,1]
	v_pk_fma_f32 v[98:99], v[50:51], v[176:177], v[98:99] op_sel:[0,1,0] op_sel_hi:[1,1,1]
	v_pk_fma_f32 v[100:101], v[50:51], v[178:179], v[100:101] op_sel:[0,0,0] op_sel_hi:[1,0,1]
	v_pk_fma_f32 v[102:103], v[50:51], v[178:179], v[102:103] op_sel:[0,1,0] op_sel_hi:[1,1,1]
	v_pk_fma_f32 v[104:105], v[50:51], v[180:181], v[104:105] op_sel:[0,0,0] op_sel_hi:[1,0,1]
	v_pk_fma_f32 v[106:107], v[50:51], v[180:181], v[106:107] op_sel:[0,1,0] op_sel_hi:[1,1,1]
	v_pk_fma_f32 v[108:109], v[50:51], v[182:183], v[108:109] op_sel:[0,0,0] op_sel_hi:[1,0,1]
	v_pk_fma_f32 v[110:111], v[50:51], v[182:183], v[110:111] op_sel:[0,1,0] op_sel_hi:[1,1,1]
	v_pk_mul_f32 v[48:49], v[96:97], v[184:185] op_sel:[0,0] op_sel_hi:[1,0]
	v_pk_mul_f32 v[50:51], v[96:97], v[148:149] op_sel:[0,0] op_sel_hi:[1,0]
	v_pk_fma_f32 v[48:49], v[98:99], v[184:185], v[48:49] op_sel:[0,1,0] op_sel_hi:[1,1,1]
	v_pk_fma_f32 v[50:51], v[98:99], v[148:149], v[50:51] op_sel:[0,1,0] op_sel_hi:[1,1,1]
	v_pk_fma_f32 v[48:49], v[100:101], v[186:187], v[48:49] op_sel:[0,0,0] op_sel_hi:[1,0,1]
	v_pk_fma_f32 v[50:51], v[100:101], v[150:151], v[50:51] op_sel:[0,0,0] op_sel_hi:[1,0,1]
	v_pk_fma_f32 v[48:49], v[102:103], v[186:187], v[48:49] op_sel:[0,1,0] op_sel_hi:[1,1,1]
	v_pk_fma_f32 v[50:51], v[102:103], v[150:151], v[50:51] op_sel:[0,1,0] op_sel_hi:[1,1,1]
	v_pk_fma_f32 v[48:49], v[104:105], v[188:189], v[48:49] op_sel:[0,0,0] op_sel_hi:[1,0,1]
	v_pk_fma_f32 v[50:51], v[104:105], v[152:153], v[50:51] op_sel:[0,0,0] op_sel_hi:[1,0,1]
	v_pk_fma_f32 v[48:49], v[106:107], v[188:189], v[48:49] op_sel:[0,1,0] op_sel_hi:[1,1,1]
	v_pk_fma_f32 v[50:51], v[106:107], v[152:153], v[50:51] op_sel:[0,1,0] op_sel_hi:[1,1,1]
	v_pk_fma_f32 v[48:49], v[108:109], v[190:191], v[48:49] op_sel:[0,0,0] op_sel_hi:[1,0,1]
	v_pk_fma_f32 v[50:51], v[108:109], v[154:155], v[50:51] op_sel:[0,0,0] op_sel_hi:[1,0,1]
	v_pk_fma_f32 v[48:49], v[110:111], v[190:191], v[48:49] op_sel:[0,1,0] op_sel_hi:[1,1,1]
	v_pk_fma_f32 v[50:51], v[110:111], v[154:155], v[50:51] op_sel:[0,1,0] op_sel_hi:[1,1,1]
	s_waitcnt lgkmcnt(11)
; #define LAS __attribute__((address_space(3)))
; __device__ __forceinline__ float red8(float x) { x += dpp_mov<0xB1>(x); x += dpp_mov<0x4E>(x); x += dpp_mov<0x141>(x); return x; }
; __device__ __forceinline__ void scan_phase(const KP& P, LAS unsigned char* lds, const int tid, const int bx, const int G) {
;     ...
;             for (int s = 0; s < 32; ++s) {
;                 const LAS float* p = cb + s * 384;
;                 const f32x4 w0 = *(const LAS f32x4*)(p), w1 = *(const LAS f32x4*)(p + 4);
;                 const f32x4 k0 = *(const LAS f32x4*)(p + 64), k1 = *(const LAS f32x4*)(p + 68);
;                 const f32x4 a0 = *(const LAS f32x4*)(p + 128), a1 = *(const LAS f32x4*)(p + 132);
;                 const f32x4 b0 = *(const LAS f32x4*)(p + 192), b1 = *(const LAS f32x4*)(p + 196);
;                 const f32x4 r0 = *(const LAS f32x4*)(p + 256), r1 = *(const LAS f32x4*)(p + 260);
;                 const float vv = buf[(c & 1) * 12288 + s * 384 + 320 + v];
;                 f32x2 sa2 = S[0] * (f32x2){a0.x, a0.y};
;                 sa2 += S[1] * (f32x2){a0.z, a0.w}; sa2 += S[2] * (f32x2){a1.x, a1.y}; sa2 += S[3] * (f32x2){a1.z, a1.w};
;                 const float sa = red8(sa2.x + sa2.y);
;                 const f32x2 sav = {sa, sa}, vv2 = {vv, vv};
;                 S[0] = S[0] * (f32x2){w0.x, w0.y} + sav * (f32x2){b0.x, b0.y} + vv2 * (f32x2){k0.x, k0.y};
;                 S[1] = S[1] * (f32x2){w0.z, w0.w} + sav * (f32x2){b0.z, b0.w} + vv2 * (f32x2){k0.z, k0.w};
;                 S[2] = S[2] * (f32x2){w1.x, w1.y} + sav * (f32x2){b1.x, b1.y} + vv2 * (f32x2){k1.x, k1.y};
;                 S[3] = S[3] * (f32x2){w1.z, w1.w} + sav * (f32x2){b1.z, b1.w} + vv2 * (f32x2){k1.z, k1.w};
;                 f32x2 y2 = S[0] * (f32x2){r0.x, r0.y};
;                 y2 += S[1] * (f32x2){r0.z, r0.w}; y2 += S[2] * (f32x2){r1.x, r1.y}; y2 += S[3] * (f32x2){r1.z, r1.w};
;                 const float y = red8(y2.x + y2.y);
;                 if (kc == 0) ybuf[s * 64 + v] = y;
	ds_read_b128 v[168:171], v44 offset:26368
	ds_read_b128 v[172:175], v44 offset:26384
	ds_read_b128 v[176:179], v44 offset:26880
	ds_read_b128 v[180:183], v44 offset:26896
	ds_read_b128 v[184:187], v44 offset:27136
	ds_read_b128 v[188:191], v44 offset:27152
	ds_read_b64 v[192:193], v46 offset:26112
	ds_read_b128 v[148:151], v44 offset:28160
	ds_read_b128 v[152:155], v44 offset:28176
	v_add_f32_dpp v48, v48, v48 quad_perm:[1,0,3,2] row_mask:0xf bank_mask:0xf bound_ctrl:1
	v_add_f32_dpp v49, v49, v49 quad_perm:[1,0,3,2] row_mask:0xf bank_mask:0xf bound_ctrl:1
	v_add_f32_dpp v50, v50, v50 quad_perm:[1,0,3,2] row_mask:0xf bank_mask:0xf bound_ctrl:1
	v_add_f32_dpp v51, v51, v51 quad_perm:[1,0,3,2] row_mask:0xf bank_mask:0xf bound_ctrl:1
	v_pk_fma_f32 v[96:97], v[144:145], v[120:121], v[96:97] op_sel:[0,0,0] op_sel_hi:[1,0,1]
	v_pk_fma_f32 v[98:99], v[144:145], v[120:121], v[98:99] op_sel:[0,1,0] op_sel_hi:[1,1,1]
	v_pk_fma_f32 v[100:101], v[144:145], v[122:123], v[100:101] op_sel:[0,0,0] op_sel_hi:[1,0,1]
	v_add_f32_dpp v48, v48, v48 quad_perm:[2,3,0,1] row_mask:0xf bank_mask:0xf bound_ctrl:1
	v_add_f32_dpp v49, v49, v49 quad_perm:[2,3,0,1] row_mask:0xf bank_mask:0xf bound_ctrl:1
	v_add_f32_dpp v50, v50, v50 quad_perm:[2,3,0,1] row_mask:0xf bank_mask:0xf bound_ctrl:1
	v_add_f32_dpp v51, v51, v51 quad_perm:[2,3,0,1] row_mask:0xf bank_mask:0xf bound_ctrl:1
	v_pk_fma_f32 v[102:103], v[144:145], v[122:123], v[102:103] op_sel:[0,1,0] op_sel_hi:[1,1,1]
	v_pk_fma_f32 v[104:105], v[144:145], v[124:125], v[104:105] op_sel:[0,0,0] op_sel_hi:[1,0,1]
	v_pk_fma_f32 v[106:107], v[144:145], v[124:125], v[106:107] op_sel:[0,1,0] op_sel_hi:[1,1,1]
	v_add_f32_dpp v48, v48, v48 row_half_mirror row_mask:0xf bank_mask:0xf bound_ctrl:1
	v_add_f32_dpp v49, v49, v49 row_half_mirror row_mask:0xf bank_mask:0xf bound_ctrl:1
	v_add_f32_dpp v50, v50, v50 row_half_mirror row_mask:0xf bank_mask:0xf bound_ctrl:1
	v_add_f32_dpp v51, v51, v51 row_half_mirror row_mask:0xf bank_mask:0xf bound_ctrl:1
	v_pk_fma_f32 v[108:109], v[144:145], v[126:127], v[108:109] op_sel:[0,0,0] op_sel_hi:[1,0,1]
	s_mov_b64 exec, s[10:11]
	ds_write_b64 v45, v[48:49] offset:3584
	s_mov_b64 exec, s[0:1]
	v_pk_fma_f32 v[110:111], v[144:145], v[126:127], v[110:111] op_sel:[0,1,0] op_sel_hi:[1,1,1]
	s_nop 0
	v_pk_fma_f32 v[96:97], v[50:51], v[128:129], v[96:97] op_sel:[0,0,0] op_sel_hi:[1,0,1]
	v_pk_fma_f32 v[98:99], v[50:51], v[128:129], v[98:99] op_sel:[0,1,0] op_sel_hi:[1,1,1]
	v_pk_fma_f32 v[100:101], v[50:51], v[130:131], v[100:101] op_sel:[0,0,0] op_sel_hi:[1,0,1]
	v_pk_fma_f32 v[102:103], v[50:51], v[130:131], v[102:103] op_sel:[0,1,0] op_sel_hi:[1,1,1]
	v_pk_fma_f32 v[104:105], v[50:51], v[132:133], v[104:105] op_sel:[0,0,0] op_sel_hi:[1,0,1]
	v_pk_fma_f32 v[106:107], v[50:51], v[132:133], v[106:107] op_sel:[0,1,0] op_sel_hi:[1,1,1]
	v_pk_fma_f32 v[108:109], v[50:51], v[134:135], v[108:109] op_sel:[0,0,0] op_sel_hi:[1,0,1]
	v_pk_fma_f32 v[110:111], v[50:51], v[134:135], v[110:111] op_sel:[0,1,0] op_sel_hi:[1,1,1]
	v_pk_mul_f32 v[48:49], v[96:97], v[136:137] op_sel:[0,0] op_sel_hi:[1,0]
	v_pk_mul_f32 v[50:51], v[96:97], v[156:157] op_sel:[0,0] op_sel_hi:[1,0]
	v_pk_fma_f32 v[48:49], v[98:99], v[136:137], v[48:49] op_sel:[0,1,0] op_sel_hi:[1,1,1]
	v_pk_fma_f32 v[50:51], v[98:99], v[156:157], v[50:51] op_sel:[0,1,0] op_sel_hi:[1,1,1]
	v_pk_fma_f32 v[48:49], v[100:101], v[138:139], v[48:49] op_sel:[0,0,0] op_sel_hi:[1,0,1]
	v_pk_fma_f32 v[50:51], v[100:101], v[158:159], v[50:51] op_sel:[0,0,0] op_sel_hi:[1,0,1]
	v_pk_fma_f32 v[48:49], v[102:103], v[138:139], v[48:49] op_sel:[0,1,0] op_sel_hi:[1,1,1]
	v_pk_fma_f32 v[50:51], v[102:103], v[158:159], v[50:51] op_sel:[0,1,0] op_sel_hi:[1,1,1]
	v_pk_fma_f32 v[48:49], v[104:105], v[140:141], v[48:49] op_sel:[0,0,0] op_sel_hi:[1,0,1]
	v_pk_fma_f32 v[50:51], v[104:105], v[160:161], v[50:51] op_sel:[0,0,0] op_sel_hi:[1,0,1]
	v_pk_fma_f32 v[48:49], v[106:107], v[140:141], v[48:49] op_sel:[0,1,0] op_sel_hi:[1,1,1]
	v_pk_fma_f32 v[50:51], v[106:107], v[160:161], v[50:51] op_sel:[0,1,0] op_sel_hi:[1,1,1]
	v_pk_fma_f32 v[48:49], v[108:109], v[142:143], v[48:49] op_sel:[0,0,0] op_sel_hi:[1,0,1]
	v_pk_fma_f32 v[50:51], v[108:109], v[162:163], v[50:51] op_sel:[0,0,0] op_sel_hi:[1,0,1]
	v_pk_fma_f32 v[48:49], v[110:111], v[142:143], v[48:49] op_sel:[0,1,0] op_sel_hi:[1,1,1]
	v_pk_fma_f32 v[50:51], v[110:111], v[162:163], v[50:51] op_sel:[0,1,0] op_sel_hi:[1,1,1]
	s_waitcnt lgkmcnt(11)
; #define LAS __attribute__((address_space(3)))
; __device__ __forceinline__ float red8(float x) { x += dpp_mov<0xB1>(x); x += dpp_mov<0x4E>(x); x += dpp_mov<0x141>(x); return x; }
; __device__ __forceinline__ void scan_phase(const KP& P, LAS unsigned char* lds, const int tid, const int bx, const int G) {
;     ...
;             for (int s = 0; s < 32; ++s) {
;                 const LAS float* p = cb + s * 384;
;                 const f32x4 w0 = *(const LAS f32x4*)(p), w1 = *(const LAS f32x4*)(p + 4);
;                 const f32x4 k0 = *(const LAS f32x4*)(p + 64), k1 = *(const LAS f32x4*)(p + 68);
;                 const f32x4 a0 = *(const LAS f32x4*)(p + 128), a1 = *(const LAS f32x4*)(p + 132);
;                 const f32x4 b0 = *(const LAS f32x4*)(p + 192), b1 = *(const LAS f32x4*)(p + 196);
;                 const f32x4 r0 = *(const LAS f32x4*)(p + 256), r1 = *(const LAS f32x4*)(p + 260);
;                 const float vv = buf[(c & 1) * 12288 + s * 384 + 320 + v];
;                 f32x2 sa2 = S[0] * (f32x2){a0.x, a0.y};
;                 sa2 += S[1] * (f32x2){a0.z, a0.w}; sa2 += S[2] * (f32x2){a1.x, a1.y}; sa2 += S[3] * (f32x2){a1.z, a1.w};
;                 const float sa = red8(sa2.x + sa2.y);
;                 const f32x2 sav = {sa, sa}, vv2 = {vv, vv};
;                 S[0] = S[0] * (f32x2){w0.x, w0.y} + sav * (f32x2){b0.x, b0.y} + vv2 * (f32x2){k0.x, k0.y};
;                 S[1] = S[1] * (f32x2){w0.z, w0.w} + sav * (f32x2){b0.z, b0.w} + vv2 * (f32x2){k0.z, k0.w};
;                 S[2] = S[2] * (f32x2){w1.x, w1.y} + sav * (f32x2){b1.x, b1.y} + vv2 * (f32x2){k1.x, k1.y};
;                 S[3] = S[3] * (f32x2){w1.z, w1.w} + sav * (f32x2){b1.z, b1.w} + vv2 * (f32x2){k1.z, k1.w};
;                 f32x2 y2 = S[0] * (f32x2){r0.x, r0.y};
;                 y2 += S[1] * (f32x2){r0.z, r0.w}; y2 += S[2] * (f32x2){r1.x, r1.y}; y2 += S[3] * (f32x2){r1.z, r1.w};
;                 const float y = red8(y2.x + y2.y);
;                 if (kc == 0) ybuf[s * 64 + v] = y;
	ds_read_b128 v[120:123], v44 offset:27904
	ds_read_b128 v[124:127], v44 offset:27920
	ds_read_b128 v[128:131], v44 offset:28416
	ds_read_b128 v[132:135], v44 offset:28432
	ds_read_b128 v[136:139], v44 offset:28672
	ds_read_b128 v[140:143], v44 offset:28688
	ds_read_b64 v[144:145], v46 offset:27648
	ds_read_b128 v[156:159], v44 offset:29696
	ds_read_b128 v[160:163], v44 offset:29712
	v_add_f32_dpp v48, v48, v48 quad_perm:[1,0,3,2] row_mask:0xf bank_mask:0xf bound_ctrl:1
	v_add_f32_dpp v49, v49, v49 quad_perm:[1,0,3,2] row_mask:0xf bank_mask:0xf bound_ctrl:1
	v_add_f32_dpp v50, v50, v50 quad_perm:[1,0,3,2] row_mask:0xf bank_mask:0xf bound_ctrl:1
	v_add_f32_dpp v51, v51, v51 quad_perm:[1,0,3,2] row_mask:0xf bank_mask:0xf bound_ctrl:1
	v_pk_fma_f32 v[96:97], v[146:147], v[70:71], v[96:97] op_sel:[0,0,0] op_sel_hi:[1,0,1]
	v_pk_fma_f32 v[98:99], v[146:147], v[70:71], v[98:99] op_sel:[0,1,0] op_sel_hi:[1,1,1]
	v_pk_fma_f32 v[100:101], v[146:147], v[72:73], v[100:101] op_sel:[0,0,0] op_sel_hi:[1,0,1]
	v_add_f32_dpp v48, v48, v48 quad_perm:[2,3,0,1] row_mask:0xf bank_mask:0xf bound_ctrl:1
	v_add_f32_dpp v49, v49, v49 quad_perm:[2,3,0,1] row_mask:0xf bank_mask:0xf bound_ctrl:1
	v_add_f32_dpp v50, v50, v50 quad_perm:[2,3,0,1] row_mask:0xf bank_mask:0xf bound_ctrl:1
	v_add_f32_dpp v51, v51, v51 quad_perm:[2,3,0,1] row_mask:0xf bank_mask:0xf bound_ctrl:1
	v_pk_fma_f32 v[102:103], v[146:147], v[72:73], v[102:103] op_sel:[0,1,0] op_sel_hi:[1,1,1]
	v_pk_fma_f32 v[104:105], v[146:147], v[74:75], v[104:105] op_sel:[0,0,0] op_sel_hi:[1,0,1]
	v_pk_fma_f32 v[106:107], v[146:147], v[74:75], v[106:107] op_sel:[0,1,0] op_sel_hi:[1,1,1]
	v_add_f32_dpp v48, v48, v48 row_half_mirror row_mask:0xf bank_mask:0xf bound_ctrl:1
	v_add_f32_dpp v49, v49, v49 row_half_mirror row_mask:0xf bank_mask:0xf bound_ctrl:1
	v_add_f32_dpp v50, v50, v50 row_half_mirror row_mask:0xf bank_mask:0xf bound_ctrl:1
	v_add_f32_dpp v51, v51, v51 row_half_mirror row_mask:0xf bank_mask:0xf bound_ctrl:1
	v_pk_fma_f32 v[108:109], v[146:147], v[76:77], v[108:109] op_sel:[0,0,0] op_sel_hi:[1,0,1]
	s_mov_b64 exec, s[10:11]
	ds_write_b64 v45, v[48:49] offset:3840
	s_mov_b64 exec, s[0:1]
	v_pk_fma_f32 v[110:111], v[146:147], v[76:77], v[110:111] op_sel:[0,1,0] op_sel_hi:[1,1,1]
	s_nop 0
	v_pk_fma_f32 v[96:97], v[50:51], v[78:79], v[96:97] op_sel:[0,0,0] op_sel_hi:[1,0,1]
	v_pk_fma_f32 v[98:99], v[50:51], v[78:79], v[98:99] op_sel:[0,1,0] op_sel_hi:[1,1,1]
	v_pk_fma_f32 v[100:101], v[50:51], v[80:81], v[100:101] op_sel:[0,0,0] op_sel_hi:[1,0,1]
	v_pk_fma_f32 v[102:103], v[50:51], v[80:81], v[102:103] op_sel:[0,1,0] op_sel_hi:[1,1,1]
	v_pk_fma_f32 v[104:105], v[50:51], v[82:83], v[104:105] op_sel:[0,0,0] op_sel_hi:[1,0,1]
	v_pk_fma_f32 v[106:107], v[50:51], v[82:83], v[106:107] op_sel:[0,1,0] op_sel_hi:[1,1,1]
	v_pk_fma_f32 v[108:109], v[50:51], v[84:85], v[108:109] op_sel:[0,0,0] op_sel_hi:[1,0,1]
	v_pk_fma_f32 v[110:111], v[50:51], v[84:85], v[110:111] op_sel:[0,1,0] op_sel_hi:[1,1,1]
	v_pk_mul_f32 v[48:49], v[96:97], v[86:87] op_sel:[0,0] op_sel_hi:[1,0]
	v_pk_mul_f32 v[50:51], v[96:97], v[62:63] op_sel:[0,0] op_sel_hi:[1,0]
	v_pk_fma_f32 v[48:49], v[98:99], v[86:87], v[48:49] op_sel:[0,1,0] op_sel_hi:[1,1,1]
	v_pk_fma_f32 v[50:51], v[98:99], v[62:63], v[50:51] op_sel:[0,1,0] op_sel_hi:[1,1,1]
	v_pk_fma_f32 v[48:49], v[100:101], v[88:89], v[48:49] op_sel:[0,0,0] op_sel_hi:[1,0,1]
	v_pk_fma_f32 v[50:51], v[100:101], v[64:65], v[50:51] op_sel:[0,0,0] op_sel_hi:[1,0,1]
	v_pk_fma_f32 v[48:49], v[102:103], v[88:89], v[48:49] op_sel:[0,1,0] op_sel_hi:[1,1,1]
	v_pk_fma_f32 v[50:51], v[102:103], v[64:65], v[50:51] op_sel:[0,1,0] op_sel_hi:[1,1,1]
	v_pk_fma_f32 v[48:49], v[104:105], v[90:91], v[48:49] op_sel:[0,0,0] op_sel_hi:[1,0,1]
	v_pk_fma_f32 v[50:51], v[104:105], v[66:67], v[50:51] op_sel:[0,0,0] op_sel_hi:[1,0,1]
	v_pk_fma_f32 v[48:49], v[106:107], v[90:91], v[48:49] op_sel:[0,1,0] op_sel_hi:[1,1,1]
	v_pk_fma_f32 v[50:51], v[106:107], v[66:67], v[50:51] op_sel:[0,1,0] op_sel_hi:[1,1,1]
	v_pk_fma_f32 v[48:49], v[108:109], v[92:93], v[48:49] op_sel:[0,0,0] op_sel_hi:[1,0,1]
	v_pk_fma_f32 v[50:51], v[108:109], v[68:69], v[50:51] op_sel:[0,0,0] op_sel_hi:[1,0,1]
	v_pk_fma_f32 v[48:49], v[110:111], v[92:93], v[48:49] op_sel:[0,1,0] op_sel_hi:[1,1,1]
	v_pk_fma_f32 v[50:51], v[110:111], v[68:69], v[50:51] op_sel:[0,1,0] op_sel_hi:[1,1,1]
	s_waitcnt lgkmcnt(11)
; #define LAS __attribute__((address_space(3)))
; __device__ __forceinline__ float red8(float x) { x += dpp_mov<0xB1>(x); x += dpp_mov<0x4E>(x); x += dpp_mov<0x141>(x); return x; }
; __device__ __forceinline__ void scan_phase(const KP& P, LAS unsigned char* lds, const int tid, const int bx, const int G) {
;     ...
;             for (int s = 0; s < 32; ++s) {
;                 const LAS float* p = cb + s * 384;
;                 const f32x4 w0 = *(const LAS f32x4*)(p), w1 = *(const LAS f32x4*)(p + 4);
;                 const f32x4 k0 = *(const LAS f32x4*)(p + 64), k1 = *(const LAS f32x4*)(p + 68);
;                 const f32x4 a0 = *(const LAS f32x4*)(p + 128), a1 = *(const LAS f32x4*)(p + 132);
;                 const f32x4 b0 = *(const LAS f32x4*)(p + 192), b1 = *(const LAS f32x4*)(p + 196);
;                 const f32x4 r0 = *(const LAS f32x4*)(p + 256), r1 = *(const LAS f32x4*)(p + 260);
;                 const float vv = buf[(c & 1) * 12288 + s * 384 + 320 + v];
;                 f32x2 sa2 = S[0] * (f32x2){a0.x, a0.y};
;                 sa2 += S[1] * (f32x2){a0.z, a0.w}; sa2 += S[2] * (f32x2){a1.x, a1.y}; sa2 += S[3] * (f32x2){a1.z, a1.w};
;                 const float sa = red8(sa2.x + sa2.y);
;                 const f32x2 sav = {sa, sa}, vv2 = {vv, vv};
;                 S[0] = S[0] * (f32x2){w0.x, w0.y} + sav * (f32x2){b0.x, b0.y} + vv2 * (f32x2){k0.x, k0.y};
;                 S[1] = S[1] * (f32x2){w0.z, w0.w} + sav * (f32x2){b0.z, b0.w} + vv2 * (f32x2){k0.z, k0.w};
;                 S[2] = S[2] * (f32x2){w1.x, w1.y} + sav * (f32x2){b1.x, b1.y} + vv2 * (f32x2){k1.x, k1.y};
;                 S[3] = S[3] * (f32x2){w1.z, w1.w} + sav * (f32x2){b1.z, b1.w} + vv2 * (f32x2){k1.z, k1.w};
;                 f32x2 y2 = S[0] * (f32x2){r0.x, r0.y};
;                 y2 += S[1] * (f32x2){r0.z, r0.w}; y2 += S[2] * (f32x2){r1.x, r1.y}; y2 += S[3] * (f32x2){r1.z, r1.w};
;                 const float y = red8(y2.x + y2.y);
;                 if (kc == 0) ybuf[s * 64 + v] = y;
	ds_read_b128 v[70:73], v44 offset:29440
	ds_read_b128 v[74:77], v44 offset:29456
	ds_read_b128 v[78:81], v44 offset:29952
	ds_read_b128 v[82:85], v44 offset:29968
	ds_read_b128 v[86:89], v44 offset:30208
	ds_read_b128 v[90:93], v44 offset:30224
	ds_read_b64 v[146:147], v46 offset:29184
	ds_read_b128 v[62:65], v44 offset:31232
	ds_read_b128 v[66:69], v44 offset:31248
	v_add_f32_dpp v48, v48, v48 quad_perm:[1,0,3,2] row_mask:0xf bank_mask:0xf bound_ctrl:1
	v_add_f32_dpp v49, v49, v49 quad_perm:[1,0,3,2] row_mask:0xf bank_mask:0xf bound_ctrl:1
	v_add_f32_dpp v50, v50, v50 quad_perm:[1,0,3,2] row_mask:0xf bank_mask:0xf bound_ctrl:1
	v_add_f32_dpp v51, v51, v51 quad_perm:[1,0,3,2] row_mask:0xf bank_mask:0xf bound_ctrl:1
	v_pk_fma_f32 v[96:97], v[192:193], v[168:169], v[96:97] op_sel:[0,0,0] op_sel_hi:[1,0,1]
	v_pk_fma_f32 v[98:99], v[192:193], v[168:169], v[98:99] op_sel:[0,1,0] op_sel_hi:[1,1,1]
	v_pk_fma_f32 v[100:101], v[192:193], v[170:171], v[100:101] op_sel:[0,0,0] op_sel_hi:[1,0,1]
	v_add_f32_dpp v48, v48, v48 quad_perm:[2,3,0,1] row_mask:0xf bank_mask:0xf bound_ctrl:1
	v_add_f32_dpp v49, v49, v49 quad_perm:[2,3,0,1] row_mask:0xf bank_mask:0xf bound_ctrl:1
	v_add_f32_dpp v50, v50, v50 quad_perm:[2,3,0,1] row_mask:0xf bank_mask:0xf bound_ctrl:1
	v_add_f32_dpp v51, v51, v51 quad_perm:[2,3,0,1] row_mask:0xf bank_mask:0xf bound_ctrl:1
	v_pk_fma_f32 v[102:103], v[192:193], v[170:171], v[102:103] op_sel:[0,1,0] op_sel_hi:[1,1,1]
	v_pk_fma_f32 v[104:105], v[192:193], v[172:173], v[104:105] op_sel:[0,0,0] op_sel_hi:[1,0,1]
	v_pk_fma_f32 v[106:107], v[192:193], v[172:173], v[106:107] op_sel:[0,1,0] op_sel_hi:[1,1,1]
	v_add_f32_dpp v48, v48, v48 row_half_mirror row_mask:0xf bank_mask:0xf bound_ctrl:1
	v_add_f32_dpp v49, v49, v49 row_half_mirror row_mask:0xf bank_mask:0xf bound_ctrl:1
	v_add_f32_dpp v50, v50, v50 row_half_mirror row_mask:0xf bank_mask:0xf bound_ctrl:1
	v_add_f32_dpp v51, v51, v51 row_half_mirror row_mask:0xf bank_mask:0xf bound_ctrl:1
	v_pk_fma_f32 v[108:109], v[192:193], v[174:175], v[108:109] op_sel:[0,0,0] op_sel_hi:[1,0,1]
	s_mov_b64 exec, s[10:11]
	ds_write_b64 v45, v[48:49] offset:4096
	s_mov_b64 exec, s[0:1]
	v_pk_fma_f32 v[110:111], v[192:193], v[174:175], v[110:111] op_sel:[0,1,0] op_sel_hi:[1,1,1]
	s_nop 0
	v_pk_fma_f32 v[96:97], v[50:51], v[176:177], v[96:97] op_sel:[0,0,0] op_sel_hi:[1,0,1]
	v_pk_fma_f32 v[98:99], v[50:51], v[176:177], v[98:99] op_sel:[0,1,0] op_sel_hi:[1,1,1]
	v_pk_fma_f32 v[100:101], v[50:51], v[178:179], v[100:101] op_sel:[0,0,0] op_sel_hi:[1,0,1]
	v_pk_fma_f32 v[102:103], v[50:51], v[178:179], v[102:103] op_sel:[0,1,0] op_sel_hi:[1,1,1]
	v_pk_fma_f32 v[104:105], v[50:51], v[180:181], v[104:105] op_sel:[0,0,0] op_sel_hi:[1,0,1]
	v_pk_fma_f32 v[106:107], v[50:51], v[180:181], v[106:107] op_sel:[0,1,0] op_sel_hi:[1,1,1]
	v_pk_fma_f32 v[108:109], v[50:51], v[182:183], v[108:109] op_sel:[0,0,0] op_sel_hi:[1,0,1]
	v_pk_fma_f32 v[110:111], v[50:51], v[182:183], v[110:111] op_sel:[0,1,0] op_sel_hi:[1,1,1]
	v_pk_mul_f32 v[48:49], v[96:97], v[184:185] op_sel:[0,0] op_sel_hi:[1,0]
	v_pk_mul_f32 v[50:51], v[96:97], v[148:149] op_sel:[0,0] op_sel_hi:[1,0]
	v_pk_fma_f32 v[48:49], v[98:99], v[184:185], v[48:49] op_sel:[0,1,0] op_sel_hi:[1,1,1]
	v_pk_fma_f32 v[50:51], v[98:99], v[148:149], v[50:51] op_sel:[0,1,0] op_sel_hi:[1,1,1]
	v_pk_fma_f32 v[48:49], v[100:101], v[186:187], v[48:49] op_sel:[0,0,0] op_sel_hi:[1,0,1]
	v_pk_fma_f32 v[50:51], v[100:101], v[150:151], v[50:51] op_sel:[0,0,0] op_sel_hi:[1,0,1]
	v_pk_fma_f32 v[48:49], v[102:103], v[186:187], v[48:49] op_sel:[0,1,0] op_sel_hi:[1,1,1]
	v_pk_fma_f32 v[50:51], v[102:103], v[150:151], v[50:51] op_sel:[0,1,0] op_sel_hi:[1,1,1]
	v_pk_fma_f32 v[48:49], v[104:105], v[188:189], v[48:49] op_sel:[0,0,0] op_sel_hi:[1,0,1]
	v_pk_fma_f32 v[50:51], v[104:105], v[152:153], v[50:51] op_sel:[0,0,0] op_sel_hi:[1,0,1]
	v_pk_fma_f32 v[48:49], v[106:107], v[188:189], v[48:49] op_sel:[0,1,0] op_sel_hi:[1,1,1]
	v_pk_fma_f32 v[50:51], v[106:107], v[152:153], v[50:51] op_sel:[0,1,0] op_sel_hi:[1,1,1]
	v_pk_fma_f32 v[48:49], v[108:109], v[190:191], v[48:49] op_sel:[0,0,0] op_sel_hi:[1,0,1]
	v_pk_fma_f32 v[50:51], v[108:109], v[154:155], v[50:51] op_sel:[0,0,0] op_sel_hi:[1,0,1]
	v_pk_fma_f32 v[48:49], v[110:111], v[190:191], v[48:49] op_sel:[0,1,0] op_sel_hi:[1,1,1]
	v_pk_fma_f32 v[50:51], v[110:111], v[154:155], v[50:51] op_sel:[0,1,0] op_sel_hi:[1,1,1]
	s_waitcnt lgkmcnt(11)
; #define LAS __attribute__((address_space(3)))
; __device__ __forceinline__ float red8(float x) { x += dpp_mov<0xB1>(x); x += dpp_mov<0x4E>(x); x += dpp_mov<0x141>(x); return x; }
; __device__ __forceinline__ void scan_phase(const KP& P, LAS unsigned char* lds, const int tid, const int bx, const int G) {
;     ...
;             for (int s = 0; s < 32; ++s) {
;                 const LAS float* p = cb + s * 384;
;                 const f32x4 w0 = *(const LAS f32x4*)(p), w1 = *(const LAS f32x4*)(p + 4);
;                 const f32x4 k0 = *(const LAS f32x4*)(p + 64), k1 = *(const LAS f32x4*)(p + 68);
;                 const f32x4 a0 = *(const LAS f32x4*)(p + 128), a1 = *(const LAS f32x4*)(p + 132);
;                 const f32x4 b0 = *(const LAS f32x4*)(p + 192), b1 = *(const LAS f32x4*)(p + 196);
;                 const f32x4 r0 = *(const LAS f32x4*)(p + 256), r1 = *(const LAS f32x4*)(p + 260);
;                 const float vv = buf[(c & 1) * 12288 + s * 384 + 320 + v];
;                 f32x2 sa2 = S[0] * (f32x2){a0.x, a0.y};
;                 sa2 += S[1] * (f32x2){a0.z, a0.w}; sa2 += S[2] * (f32x2){a1.x, a1.y}; sa2 += S[3] * (f32x2){a1.z, a1.w};
;                 const float sa = red8(sa2.x + sa2.y);
;                 const f32x2 sav = {sa, sa}, vv2 = {vv, vv};
;                 S[0] = S[0] * (f32x2){w0.x, w0.y} + sav * (f32x2){b0.x, b0.y} + vv2 * (f32x2){k0.x, k0.y};
;                 S[1] = S[1] * (f32x2){w0.z, w0.w} + sav * (f32x2){b0.z, b0.w} + vv2 * (f32x2){k0.z, k0.w};
;                 S[2] = S[2] * (f32x2){w1.x, w1.y} + sav * (f32x2){b1.x, b1.y} + vv2 * (f32x2){k1.x, k1.y};
;                 S[3] = S[3] * (f32x2){w1.z, w1.w} + sav * (f32x2){b1.z, b1.w} + vv2 * (f32x2){k1.z, k1.w};
;                 f32x2 y2 = S[0] * (f32x2){r0.x, r0.y};
;                 y2 += S[1] * (f32x2){r0.z, r0.w}; y2 += S[2] * (f32x2){r1.x, r1.y}; y2 += S[3] * (f32x2){r1.z, r1.w};
;                 const float y = red8(y2.x + y2.y);
;                 if (kc == 0) ybuf[s * 64 + v] = y;
	ds_read_b128 v[168:171], v44 offset:30976
	ds_read_b128 v[172:175], v44 offset:30992
	ds_read_b128 v[176:179], v44 offset:31488
	ds_read_b128 v[180:183], v44 offset:31504
	ds_read_b128 v[184:187], v44 offset:31744
	ds_read_b128 v[188:191], v44 offset:31760
	ds_read_b64 v[192:193], v46 offset:30720
	ds_read_b128 v[148:151], v44 offset:32768
	ds_read_b128 v[152:155], v44 offset:32784
	v_add_f32_dpp v48, v48, v48 quad_perm:[1,0,3,2] row_mask:0xf bank_mask:0xf bound_ctrl:1
	v_add_f32_dpp v49, v49, v49 quad_perm:[1,0,3,2] row_mask:0xf bank_mask:0xf bound_ctrl:1
	v_add_f32_dpp v50, v50, v50 quad_perm:[1,0,3,2] row_mask:0xf bank_mask:0xf bound_ctrl:1
	v_add_f32_dpp v51, v51, v51 quad_perm:[1,0,3,2] row_mask:0xf bank_mask:0xf bound_ctrl:1
	v_pk_fma_f32 v[96:97], v[144:145], v[120:121], v[96:97] op_sel:[0,0,0] op_sel_hi:[1,0,1]
	v_pk_fma_f32 v[98:99], v[144:145], v[120:121], v[98:99] op_sel:[0,1,0] op_sel_hi:[1,1,1]
	v_pk_fma_f32 v[100:101], v[144:145], v[122:123], v[100:101] op_sel:[0,0,0] op_sel_hi:[1,0,1]
	v_add_f32_dpp v48, v48, v48 quad_perm:[2,3,0,1] row_mask:0xf bank_mask:0xf bound_ctrl:1
	v_add_f32_dpp v49, v49, v49 quad_perm:[2,3,0,1] row_mask:0xf bank_mask:0xf bound_ctrl:1
	v_add_f32_dpp v50, v50, v50 quad_perm:[2,3,0,1] row_mask:0xf bank_mask:0xf bound_ctrl:1
	v_add_f32_dpp v51, v51, v51 quad_perm:[2,3,0,1] row_mask:0xf bank_mask:0xf bound_ctrl:1
	v_pk_fma_f32 v[102:103], v[144:145], v[122:123], v[102:103] op_sel:[0,1,0] op_sel_hi:[1,1,1]
	v_pk_fma_f32 v[104:105], v[144:145], v[124:125], v[104:105] op_sel:[0,0,0] op_sel_hi:[1,0,1]
	v_pk_fma_f32 v[106:107], v[144:145], v[124:125], v[106:107] op_sel:[0,1,0] op_sel_hi:[1,1,1]
	v_add_f32_dpp v48, v48, v48 row_half_mirror row_mask:0xf bank_mask:0xf bound_ctrl:1
	v_add_f32_dpp v49, v49, v49 row_half_mirror row_mask:0xf bank_mask:0xf bound_ctrl:1
	v_add_f32_dpp v50, v50, v50 row_half_mirror row_mask:0xf bank_mask:0xf bound_ctrl:1
	v_add_f32_dpp v51, v51, v51 row_half_mirror row_mask:0xf bank_mask:0xf bound_ctrl:1
	v_pk_fma_f32 v[108:109], v[144:145], v[126:127], v[108:109] op_sel:[0,0,0] op_sel_hi:[1,0,1]
	s_mov_b64 exec, s[10:11]
	ds_write_b64 v45, v[48:49] offset:4352
	s_mov_b64 exec, s[0:1]
	v_pk_fma_f32 v[110:111], v[144:145], v[126:127], v[110:111] op_sel:[0,1,0] op_sel_hi:[1,1,1]
	s_nop 0
	v_pk_fma_f32 v[96:97], v[50:51], v[128:129], v[96:97] op_sel:[0,0,0] op_sel_hi:[1,0,1]
	v_pk_fma_f32 v[98:99], v[50:51], v[128:129], v[98:99] op_sel:[0,1,0] op_sel_hi:[1,1,1]
	v_pk_fma_f32 v[100:101], v[50:51], v[130:131], v[100:101] op_sel:[0,0,0] op_sel_hi:[1,0,1]
	v_pk_fma_f32 v[102:103], v[50:51], v[130:131], v[102:103] op_sel:[0,1,0] op_sel_hi:[1,1,1]
	v_pk_fma_f32 v[104:105], v[50:51], v[132:133], v[104:105] op_sel:[0,0,0] op_sel_hi:[1,0,1]
	v_pk_fma_f32 v[106:107], v[50:51], v[132:133], v[106:107] op_sel:[0,1,0] op_sel_hi:[1,1,1]
	v_pk_fma_f32 v[108:109], v[50:51], v[134:135], v[108:109] op_sel:[0,0,0] op_sel_hi:[1,0,1]
	v_pk_fma_f32 v[110:111], v[50:51], v[134:135], v[110:111] op_sel:[0,1,0] op_sel_hi:[1,1,1]
	v_pk_mul_f32 v[48:49], v[96:97], v[136:137] op_sel:[0,0] op_sel_hi:[1,0]
	v_pk_mul_f32 v[50:51], v[96:97], v[156:157] op_sel:[0,0] op_sel_hi:[1,0]
	v_pk_fma_f32 v[48:49], v[98:99], v[136:137], v[48:49] op_sel:[0,1,0] op_sel_hi:[1,1,1]
	v_pk_fma_f32 v[50:51], v[98:99], v[156:157], v[50:51] op_sel:[0,1,0] op_sel_hi:[1,1,1]
	v_pk_fma_f32 v[48:49], v[100:101], v[138:139], v[48:49] op_sel:[0,0,0] op_sel_hi:[1,0,1]
	v_pk_fma_f32 v[50:51], v[100:101], v[158:159], v[50:51] op_sel:[0,0,0] op_sel_hi:[1,0,1]
	v_pk_fma_f32 v[48:49], v[102:103], v[138:139], v[48:49] op_sel:[0,1,0] op_sel_hi:[1,1,1]
	v_pk_fma_f32 v[50:51], v[102:103], v[158:159], v[50:51] op_sel:[0,1,0] op_sel_hi:[1,1,1]
	v_pk_fma_f32 v[48:49], v[104:105], v[140:141], v[48:49] op_sel:[0,0,0] op_sel_hi:[1,0,1]
	v_pk_fma_f32 v[50:51], v[104:105], v[160:161], v[50:51] op_sel:[0,0,0] op_sel_hi:[1,0,1]
	v_pk_fma_f32 v[48:49], v[106:107], v[140:141], v[48:49] op_sel:[0,1,0] op_sel_hi:[1,1,1]
	v_pk_fma_f32 v[50:51], v[106:107], v[160:161], v[50:51] op_sel:[0,1,0] op_sel_hi:[1,1,1]
	v_pk_fma_f32 v[48:49], v[108:109], v[142:143], v[48:49] op_sel:[0,0,0] op_sel_hi:[1,0,1]
	v_pk_fma_f32 v[50:51], v[108:109], v[162:163], v[50:51] op_sel:[0,0,0] op_sel_hi:[1,0,1]
	v_pk_fma_f32 v[48:49], v[110:111], v[142:143], v[48:49] op_sel:[0,1,0] op_sel_hi:[1,1,1]
	v_pk_fma_f32 v[50:51], v[110:111], v[162:163], v[50:51] op_sel:[0,1,0] op_sel_hi:[1,1,1]
	s_waitcnt lgkmcnt(11)
; #define LAS __attribute__((address_space(3)))
; __device__ __forceinline__ float red8(float x) { x += dpp_mov<0xB1>(x); x += dpp_mov<0x4E>(x); x += dpp_mov<0x141>(x); return x; }
; __device__ __forceinline__ void scan_phase(const KP& P, LAS unsigned char* lds, const int tid, const int bx, const int G) {
;     ...
;             for (int s = 0; s < 32; ++s) {
;                 const LAS float* p = cb + s * 384;
;                 const f32x4 w0 = *(const LAS f32x4*)(p), w1 = *(const LAS f32x4*)(p + 4);
;                 const f32x4 k0 = *(const LAS f32x4*)(p + 64), k1 = *(const LAS f32x4*)(p + 68);
;                 const f32x4 a0 = *(const LAS f32x4*)(p + 128), a1 = *(const LAS f32x4*)(p + 132);
;                 const f32x4 b0 = *(const LAS f32x4*)(p + 192), b1 = *(const LAS f32x4*)(p + 196);
;                 const f32x4 r0 = *(const LAS f32x4*)(p + 256), r1 = *(const LAS f32x4*)(p + 260);
;                 const float vv = buf[(c & 1) * 12288 + s * 384 + 320 + v];
;                 f32x2 sa2 = S[0] * (f32x2){a0.x, a0.y};
;                 sa2 += S[1] * (f32x2){a0.z, a0.w}; sa2 += S[2] * (f32x2){a1.x, a1.y}; sa2 += S[3] * (f32x2){a1.z, a1.w};
;                 const float sa = red8(sa2.x + sa2.y);
;                 const f32x2 sav = {sa, sa}, vv2 = {vv, vv};
;                 S[0] = S[0] * (f32x2){w0.x, w0.y} + sav * (f32x2){b0.x, b0.y} + vv2 * (f32x2){k0.x, k0.y};
;                 S[1] = S[1] * (f32x2){w0.z, w0.w} + sav * (f32x2){b0.z, b0.w} + vv2 * (f32x2){k0.z, k0.w};
;                 S[2] = S[2] * (f32x2){w1.x, w1.y} + sav * (f32x2){b1.x, b1.y} + vv2 * (f32x2){k1.x, k1.y};
;                 S[3] = S[3] * (f32x2){w1.z, w1.w} + sav * (f32x2){b1.z, b1.w} + vv2 * (f32x2){k1.z, k1.w};
;                 f32x2 y2 = S[0] * (f32x2){r0.x, r0.y};
;                 y2 += S[1] * (f32x2){r0.z, r0.w}; y2 += S[2] * (f32x2){r1.x, r1.y}; y2 += S[3] * (f32x2){r1.z, r1.w};
;                 const float y = red8(y2.x + y2.y);
;                 if (kc == 0) ybuf[s * 64 + v] = y;
	ds_read_b128 v[120:123], v44 offset:32512
	ds_read_b128 v[124:127], v44 offset:32528
	ds_read_b128 v[128:131], v44 offset:33024
	ds_read_b128 v[132:135], v44 offset:33040
	ds_read_b128 v[136:139], v44 offset:33280
	ds_read_b128 v[140:143], v44 offset:33296
	ds_read_b64 v[144:145], v46 offset:32256
	ds_read_b128 v[156:159], v44 offset:34304
	ds_read_b128 v[160:163], v44 offset:34320
	v_add_f32_dpp v48, v48, v48 quad_perm:[1,0,3,2] row_mask:0xf bank_mask:0xf bound_ctrl:1
	v_add_f32_dpp v49, v49, v49 quad_perm:[1,0,3,2] row_mask:0xf bank_mask:0xf bound_ctrl:1
	v_add_f32_dpp v50, v50, v50 quad_perm:[1,0,3,2] row_mask:0xf bank_mask:0xf bound_ctrl:1
	v_add_f32_dpp v51, v51, v51 quad_perm:[1,0,3,2] row_mask:0xf bank_mask:0xf bound_ctrl:1
	v_pk_fma_f32 v[96:97], v[146:147], v[70:71], v[96:97] op_sel:[0,0,0] op_sel_hi:[1,0,1]
	v_pk_fma_f32 v[98:99], v[146:147], v[70:71], v[98:99] op_sel:[0,1,0] op_sel_hi:[1,1,1]
	v_pk_fma_f32 v[100:101], v[146:147], v[72:73], v[100:101] op_sel:[0,0,0] op_sel_hi:[1,0,1]
	v_add_f32_dpp v48, v48, v48 quad_perm:[2,3,0,1] row_mask:0xf bank_mask:0xf bound_ctrl:1
	v_add_f32_dpp v49, v49, v49 quad_perm:[2,3,0,1] row_mask:0xf bank_mask:0xf bound_ctrl:1
	v_add_f32_dpp v50, v50, v50 quad_perm:[2,3,0,1] row_mask:0xf bank_mask:0xf bound_ctrl:1
	v_add_f32_dpp v51, v51, v51 quad_perm:[2,3,0,1] row_mask:0xf bank_mask:0xf bound_ctrl:1
	v_pk_fma_f32 v[102:103], v[146:147], v[72:73], v[102:103] op_sel:[0,1,0] op_sel_hi:[1,1,1]
	v_pk_fma_f32 v[104:105], v[146:147], v[74:75], v[104:105] op_sel:[0,0,0] op_sel_hi:[1,0,1]
	v_pk_fma_f32 v[106:107], v[146:147], v[74:75], v[106:107] op_sel:[0,1,0] op_sel_hi:[1,1,1]
	v_add_f32_dpp v48, v48, v48 row_half_mirror row_mask:0xf bank_mask:0xf bound_ctrl:1
	v_add_f32_dpp v49, v49, v49 row_half_mirror row_mask:0xf bank_mask:0xf bound_ctrl:1
	v_add_f32_dpp v50, v50, v50 row_half_mirror row_mask:0xf bank_mask:0xf bound_ctrl:1
	v_add_f32_dpp v51, v51, v51 row_half_mirror row_mask:0xf bank_mask:0xf bound_ctrl:1
	v_pk_fma_f32 v[108:109], v[146:147], v[76:77], v[108:109] op_sel:[0,0,0] op_sel_hi:[1,0,1]
	s_mov_b64 exec, s[10:11]
	ds_write_b64 v45, v[48:49] offset:4608
	s_mov_b64 exec, s[0:1]
	v_pk_fma_f32 v[110:111], v[146:147], v[76:77], v[110:111] op_sel:[0,1,0] op_sel_hi:[1,1,1]
	s_nop 0
	v_pk_fma_f32 v[96:97], v[50:51], v[78:79], v[96:97] op_sel:[0,0,0] op_sel_hi:[1,0,1]
	v_pk_fma_f32 v[98:99], v[50:51], v[78:79], v[98:99] op_sel:[0,1,0] op_sel_hi:[1,1,1]
	v_pk_fma_f32 v[100:101], v[50:51], v[80:81], v[100:101] op_sel:[0,0,0] op_sel_hi:[1,0,1]
	v_pk_fma_f32 v[102:103], v[50:51], v[80:81], v[102:103] op_sel:[0,1,0] op_sel_hi:[1,1,1]
	v_pk_fma_f32 v[104:105], v[50:51], v[82:83], v[104:105] op_sel:[0,0,0] op_sel_hi:[1,0,1]
	v_pk_fma_f32 v[106:107], v[50:51], v[82:83], v[106:107] op_sel:[0,1,0] op_sel_hi:[1,1,1]
	v_pk_fma_f32 v[108:109], v[50:51], v[84:85], v[108:109] op_sel:[0,0,0] op_sel_hi:[1,0,1]
	v_pk_fma_f32 v[110:111], v[50:51], v[84:85], v[110:111] op_sel:[0,1,0] op_sel_hi:[1,1,1]
	v_pk_mul_f32 v[48:49], v[96:97], v[86:87] op_sel:[0,0] op_sel_hi:[1,0]
	v_pk_mul_f32 v[50:51], v[96:97], v[62:63] op_sel:[0,0] op_sel_hi:[1,0]
	v_pk_fma_f32 v[48:49], v[98:99], v[86:87], v[48:49] op_sel:[0,1,0] op_sel_hi:[1,1,1]
	v_pk_fma_f32 v[50:51], v[98:99], v[62:63], v[50:51] op_sel:[0,1,0] op_sel_hi:[1,1,1]
	v_pk_fma_f32 v[48:49], v[100:101], v[88:89], v[48:49] op_sel:[0,0,0] op_sel_hi:[1,0,1]
	v_pk_fma_f32 v[50:51], v[100:101], v[64:65], v[50:51] op_sel:[0,0,0] op_sel_hi:[1,0,1]
	v_pk_fma_f32 v[48:49], v[102:103], v[88:89], v[48:49] op_sel:[0,1,0] op_sel_hi:[1,1,1]
	v_pk_fma_f32 v[50:51], v[102:103], v[64:65], v[50:51] op_sel:[0,1,0] op_sel_hi:[1,1,1]
	v_pk_fma_f32 v[48:49], v[104:105], v[90:91], v[48:49] op_sel:[0,0,0] op_sel_hi:[1,0,1]
	v_pk_fma_f32 v[50:51], v[104:105], v[66:67], v[50:51] op_sel:[0,0,0] op_sel_hi:[1,0,1]
	v_pk_fma_f32 v[48:49], v[106:107], v[90:91], v[48:49] op_sel:[0,1,0] op_sel_hi:[1,1,1]
	v_pk_fma_f32 v[50:51], v[106:107], v[66:67], v[50:51] op_sel:[0,1,0] op_sel_hi:[1,1,1]
	v_pk_fma_f32 v[48:49], v[108:109], v[92:93], v[48:49] op_sel:[0,0,0] op_sel_hi:[1,0,1]
	v_pk_fma_f32 v[50:51], v[108:109], v[68:69], v[50:51] op_sel:[0,0,0] op_sel_hi:[1,0,1]
	v_pk_fma_f32 v[48:49], v[110:111], v[92:93], v[48:49] op_sel:[0,1,0] op_sel_hi:[1,1,1]
	v_pk_fma_f32 v[50:51], v[110:111], v[68:69], v[50:51] op_sel:[0,1,0] op_sel_hi:[1,1,1]
	s_waitcnt lgkmcnt(11)
; #define LAS __attribute__((address_space(3)))
; __device__ __forceinline__ float red8(float x) { x += dpp_mov<0xB1>(x); x += dpp_mov<0x4E>(x); x += dpp_mov<0x141>(x); return x; }
; __device__ __forceinline__ void scan_phase(const KP& P, LAS unsigned char* lds, const int tid, const int bx, const int G) {
;     ...
;             for (int s = 0; s < 32; ++s) {
;                 const LAS float* p = cb + s * 384;
;                 const f32x4 w0 = *(const LAS f32x4*)(p), w1 = *(const LAS f32x4*)(p + 4);
;                 const f32x4 k0 = *(const LAS f32x4*)(p + 64), k1 = *(const LAS f32x4*)(p + 68);
;                 const f32x4 a0 = *(const LAS f32x4*)(p + 128), a1 = *(const LAS f32x4*)(p + 132);
;                 const f32x4 b0 = *(const LAS f32x4*)(p + 192), b1 = *(const LAS f32x4*)(p + 196);
;                 const f32x4 r0 = *(const LAS f32x4*)(p + 256), r1 = *(const LAS f32x4*)(p + 260);
;                 const float vv = buf[(c & 1) * 12288 + s * 384 + 320 + v];
;                 f32x2 sa2 = S[0] * (f32x2){a0.x, a0.y};
;                 sa2 += S[1] * (f32x2){a0.z, a0.w}; sa2 += S[2] * (f32x2){a1.x, a1.y}; sa2 += S[3] * (f32x2){a1.z, a1.w};
;                 const float sa = red8(sa2.x + sa2.y);
;                 const f32x2 sav = {sa, sa}, vv2 = {vv, vv};
;                 S[0] = S[0] * (f32x2){w0.x, w0.y} + sav * (f32x2){b0.x, b0.y} + vv2 * (f32x2){k0.x, k0.y};
;                 S[1] = S[1] * (f32x2){w0.z, w0.w} + sav * (f32x2){b0.z, b0.w} + vv2 * (f32x2){k0.z, k0.w};
;                 S[2] = S[2] * (f32x2){w1.x, w1.y} + sav * (f32x2){b1.x, b1.y} + vv2 * (f32x2){k1.x, k1.y};
;                 S[3] = S[3] * (f32x2){w1.z, w1.w} + sav * (f32x2){b1.z, b1.w} + vv2 * (f32x2){k1.z, k1.w};
;                 f32x2 y2 = S[0] * (f32x2){r0.x, r0.y};
;                 y2 += S[1] * (f32x2){r0.z, r0.w}; y2 += S[2] * (f32x2){r1.x, r1.y}; y2 += S[3] * (f32x2){r1.z, r1.w};
;                 const float y = red8(y2.x + y2.y);
;                 if (kc == 0) ybuf[s * 64 + v] = y;
	ds_read_b128 v[70:73], v44 offset:34048
	ds_read_b128 v[74:77], v44 offset:34064
	ds_read_b128 v[78:81], v44 offset:34560
	ds_read_b128 v[82:85], v44 offset:34576
	ds_read_b128 v[86:89], v44 offset:34816
	ds_read_b128 v[90:93], v44 offset:34832
	ds_read_b64 v[146:147], v46 offset:33792
	ds_read_b128 v[62:65], v44 offset:35840
	ds_read_b128 v[66:69], v44 offset:35856
	v_add_f32_dpp v48, v48, v48 quad_perm:[1,0,3,2] row_mask:0xf bank_mask:0xf bound_ctrl:1
	v_add_f32_dpp v49, v49, v49 quad_perm:[1,0,3,2] row_mask:0xf bank_mask:0xf bound_ctrl:1
	v_add_f32_dpp v50, v50, v50 quad_perm:[1,0,3,2] row_mask:0xf bank_mask:0xf bound_ctrl:1
	v_add_f32_dpp v51, v51, v51 quad_perm:[1,0,3,2] row_mask:0xf bank_mask:0xf bound_ctrl:1
	v_pk_fma_f32 v[96:97], v[192:193], v[168:169], v[96:97] op_sel:[0,0,0] op_sel_hi:[1,0,1]
	v_pk_fma_f32 v[98:99], v[192:193], v[168:169], v[98:99] op_sel:[0,1,0] op_sel_hi:[1,1,1]
	v_pk_fma_f32 v[100:101], v[192:193], v[170:171], v[100:101] op_sel:[0,0,0] op_sel_hi:[1,0,1]
	v_add_f32_dpp v48, v48, v48 quad_perm:[2,3,0,1] row_mask:0xf bank_mask:0xf bound_ctrl:1
	v_add_f32_dpp v49, v49, v49 quad_perm:[2,3,0,1] row_mask:0xf bank_mask:0xf bound_ctrl:1
	v_add_f32_dpp v50, v50, v50 quad_perm:[2,3,0,1] row_mask:0xf bank_mask:0xf bound_ctrl:1
	v_add_f32_dpp v51, v51, v51 quad_perm:[2,3,0,1] row_mask:0xf bank_mask:0xf bound_ctrl:1
	v_pk_fma_f32 v[102:103], v[192:193], v[170:171], v[102:103] op_sel:[0,1,0] op_sel_hi:[1,1,1]
	v_pk_fma_f32 v[104:105], v[192:193], v[172:173], v[104:105] op_sel:[0,0,0] op_sel_hi:[1,0,1]
	v_pk_fma_f32 v[106:107], v[192:193], v[172:173], v[106:107] op_sel:[0,1,0] op_sel_hi:[1,1,1]
	v_add_f32_dpp v48, v48, v48 row_half_mirror row_mask:0xf bank_mask:0xf bound_ctrl:1
	v_add_f32_dpp v49, v49, v49 row_half_mirror row_mask:0xf bank_mask:0xf bound_ctrl:1
	v_add_f32_dpp v50, v50, v50 row_half_mirror row_mask:0xf bank_mask:0xf bound_ctrl:1
	v_add_f32_dpp v51, v51, v51 row_half_mirror row_mask:0xf bank_mask:0xf bound_ctrl:1
	v_pk_fma_f32 v[108:109], v[192:193], v[174:175], v[108:109] op_sel:[0,0,0] op_sel_hi:[1,0,1]
	s_mov_b64 exec, s[10:11]
	ds_write_b64 v45, v[48:49] offset:4864
	s_mov_b64 exec, s[0:1]
	v_pk_fma_f32 v[110:111], v[192:193], v[174:175], v[110:111] op_sel:[0,1,0] op_sel_hi:[1,1,1]
	s_nop 0
	v_pk_fma_f32 v[96:97], v[50:51], v[176:177], v[96:97] op_sel:[0,0,0] op_sel_hi:[1,0,1]
	v_pk_fma_f32 v[98:99], v[50:51], v[176:177], v[98:99] op_sel:[0,1,0] op_sel_hi:[1,1,1]
	v_pk_fma_f32 v[100:101], v[50:51], v[178:179], v[100:101] op_sel:[0,0,0] op_sel_hi:[1,0,1]
	v_pk_fma_f32 v[102:103], v[50:51], v[178:179], v[102:103] op_sel:[0,1,0] op_sel_hi:[1,1,1]
	v_pk_fma_f32 v[104:105], v[50:51], v[180:181], v[104:105] op_sel:[0,0,0] op_sel_hi:[1,0,1]
	v_pk_fma_f32 v[106:107], v[50:51], v[180:181], v[106:107] op_sel:[0,1,0] op_sel_hi:[1,1,1]
	v_pk_fma_f32 v[108:109], v[50:51], v[182:183], v[108:109] op_sel:[0,0,0] op_sel_hi:[1,0,1]
	v_pk_fma_f32 v[110:111], v[50:51], v[182:183], v[110:111] op_sel:[0,1,0] op_sel_hi:[1,1,1]
	v_pk_mul_f32 v[48:49], v[96:97], v[184:185] op_sel:[0,0] op_sel_hi:[1,0]
	v_pk_mul_f32 v[50:51], v[96:97], v[148:149] op_sel:[0,0] op_sel_hi:[1,0]
	v_pk_fma_f32 v[48:49], v[98:99], v[184:185], v[48:49] op_sel:[0,1,0] op_sel_hi:[1,1,1]
	v_pk_fma_f32 v[50:51], v[98:99], v[148:149], v[50:51] op_sel:[0,1,0] op_sel_hi:[1,1,1]
	v_pk_fma_f32 v[48:49], v[100:101], v[186:187], v[48:49] op_sel:[0,0,0] op_sel_hi:[1,0,1]
	v_pk_fma_f32 v[50:51], v[100:101], v[150:151], v[50:51] op_sel:[0,0,0] op_sel_hi:[1,0,1]
	v_pk_fma_f32 v[48:49], v[102:103], v[186:187], v[48:49] op_sel:[0,1,0] op_sel_hi:[1,1,1]
	v_pk_fma_f32 v[50:51], v[102:103], v[150:151], v[50:51] op_sel:[0,1,0] op_sel_hi:[1,1,1]
	v_pk_fma_f32 v[48:49], v[104:105], v[188:189], v[48:49] op_sel:[0,0,0] op_sel_hi:[1,0,1]
	v_pk_fma_f32 v[50:51], v[104:105], v[152:153], v[50:51] op_sel:[0,0,0] op_sel_hi:[1,0,1]
	v_pk_fma_f32 v[48:49], v[106:107], v[188:189], v[48:49] op_sel:[0,1,0] op_sel_hi:[1,1,1]
	v_pk_fma_f32 v[50:51], v[106:107], v[152:153], v[50:51] op_sel:[0,1,0] op_sel_hi:[1,1,1]
	v_pk_fma_f32 v[48:49], v[108:109], v[190:191], v[48:49] op_sel:[0,0,0] op_sel_hi:[1,0,1]
	v_pk_fma_f32 v[50:51], v[108:109], v[154:155], v[50:51] op_sel:[0,0,0] op_sel_hi:[1,0,1]
	v_pk_fma_f32 v[48:49], v[110:111], v[190:191], v[48:49] op_sel:[0,1,0] op_sel_hi:[1,1,1]
	v_pk_fma_f32 v[50:51], v[110:111], v[154:155], v[50:51] op_sel:[0,1,0] op_sel_hi:[1,1,1]
	s_waitcnt lgkmcnt(11)
; #define LAS __attribute__((address_space(3)))
; __device__ __forceinline__ float red8(float x) { x += dpp_mov<0xB1>(x); x += dpp_mov<0x4E>(x); x += dpp_mov<0x141>(x); return x; }
; __device__ __forceinline__ void scan_phase(const KP& P, LAS unsigned char* lds, const int tid, const int bx, const int G) {
;     ...
;             for (int s = 0; s < 32; ++s) {
;                 const LAS float* p = cb + s * 384;
;                 const f32x4 w0 = *(const LAS f32x4*)(p), w1 = *(const LAS f32x4*)(p + 4);
;                 const f32x4 k0 = *(const LAS f32x4*)(p + 64), k1 = *(const LAS f32x4*)(p + 68);
;                 const f32x4 a0 = *(const LAS f32x4*)(p + 128), a1 = *(const LAS f32x4*)(p + 132);
;                 const f32x4 b0 = *(const LAS f32x4*)(p + 192), b1 = *(const LAS f32x4*)(p + 196);
;                 const f32x4 r0 = *(const LAS f32x4*)(p + 256), r1 = *(const LAS f32x4*)(p + 260);
;                 const float vv = buf[(c & 1) * 12288 + s * 384 + 320 + v];
;                 f32x2 sa2 = S[0] * (f32x2){a0.x, a0.y};
;                 sa2 += S[1] * (f32x2){a0.z, a0.w}; sa2 += S[2] * (f32x2){a1.x, a1.y}; sa2 += S[3] * (f32x2){a1.z, a1.w};
;                 const float sa = red8(sa2.x + sa2.y);
;                 const f32x2 sav = {sa, sa}, vv2 = {vv, vv};
;                 S[0] = S[0] * (f32x2){w0.x, w0.y} + sav * (f32x2){b0.x, b0.y} + vv2 * (f32x2){k0.x, k0.y};
;                 S[1] = S[1] * (f32x2){w0.z, w0.w} + sav * (f32x2){b0.z, b0.w} + vv2 * (f32x2){k0.z, k0.w};
;                 S[2] = S[2] * (f32x2){w1.x, w1.y} + sav * (f32x2){b1.x, b1.y} + vv2 * (f32x2){k1.x, k1.y};
;                 S[3] = S[3] * (f32x2){w1.z, w1.w} + sav * (f32x2){b1.z, b1.w} + vv2 * (f32x2){k1.z, k1.w};
;                 f32x2 y2 = S[0] * (f32x2){r0.x, r0.y};
;                 y2 += S[1] * (f32x2){r0.z, r0.w}; y2 += S[2] * (f32x2){r1.x, r1.y}; y2 += S[3] * (f32x2){r1.z, r1.w};
;                 const float y = red8(y2.x + y2.y);
;                 if (kc == 0) ybuf[s * 64 + v] = y;
	ds_read_b128 v[168:171], v44 offset:35584
	ds_read_b128 v[172:175], v44 offset:35600
	ds_read_b128 v[176:179], v44 offset:36096
	ds_read_b128 v[180:183], v44 offset:36112
	ds_read_b128 v[184:187], v44 offset:36352
	ds_read_b128 v[188:191], v44 offset:36368
	ds_read_b64 v[192:193], v46 offset:35328
	ds_read_b128 v[148:151], v44 offset:37376
	ds_read_b128 v[152:155], v44 offset:37392
	v_add_f32_dpp v48, v48, v48 quad_perm:[1,0,3,2] row_mask:0xf bank_mask:0xf bound_ctrl:1
	v_add_f32_dpp v49, v49, v49 quad_perm:[1,0,3,2] row_mask:0xf bank_mask:0xf bound_ctrl:1
	v_add_f32_dpp v50, v50, v50 quad_perm:[1,0,3,2] row_mask:0xf bank_mask:0xf bound_ctrl:1
	v_add_f32_dpp v51, v51, v51 quad_perm:[1,0,3,2] row_mask:0xf bank_mask:0xf bound_ctrl:1
	v_pk_fma_f32 v[96:97], v[144:145], v[120:121], v[96:97] op_sel:[0,0,0] op_sel_hi:[1,0,1]
	v_pk_fma_f32 v[98:99], v[144:145], v[120:121], v[98:99] op_sel:[0,1,0] op_sel_hi:[1,1,1]
	v_pk_fma_f32 v[100:101], v[144:145], v[122:123], v[100:101] op_sel:[0,0,0] op_sel_hi:[1,0,1]
	v_add_f32_dpp v48, v48, v48 quad_perm:[2,3,0,1] row_mask:0xf bank_mask:0xf bound_ctrl:1
	v_add_f32_dpp v49, v49, v49 quad_perm:[2,3,0,1] row_mask:0xf bank_mask:0xf bound_ctrl:1
	v_add_f32_dpp v50, v50, v50 quad_perm:[2,3,0,1] row_mask:0xf bank_mask:0xf bound_ctrl:1
	v_add_f32_dpp v51, v51, v51 quad_perm:[2,3,0,1] row_mask:0xf bank_mask:0xf bound_ctrl:1
	v_pk_fma_f32 v[102:103], v[144:145], v[122:123], v[102:103] op_sel:[0,1,0] op_sel_hi:[1,1,1]
	v_pk_fma_f32 v[104:105], v[144:145], v[124:125], v[104:105] op_sel:[0,0,0] op_sel_hi:[1,0,1]
	v_pk_fma_f32 v[106:107], v[144:145], v[124:125], v[106:107] op_sel:[0,1,0] op_sel_hi:[1,1,1]
	v_add_f32_dpp v48, v48, v48 row_half_mirror row_mask:0xf bank_mask:0xf bound_ctrl:1
	v_add_f32_dpp v49, v49, v49 row_half_mirror row_mask:0xf bank_mask:0xf bound_ctrl:1
	v_add_f32_dpp v50, v50, v50 row_half_mirror row_mask:0xf bank_mask:0xf bound_ctrl:1
	v_add_f32_dpp v51, v51, v51 row_half_mirror row_mask:0xf bank_mask:0xf bound_ctrl:1
	v_pk_fma_f32 v[108:109], v[144:145], v[126:127], v[108:109] op_sel:[0,0,0] op_sel_hi:[1,0,1]
	s_mov_b64 exec, s[10:11]
	ds_write_b64 v45, v[48:49] offset:5120
	s_mov_b64 exec, s[0:1]
	v_pk_fma_f32 v[110:111], v[144:145], v[126:127], v[110:111] op_sel:[0,1,0] op_sel_hi:[1,1,1]
	s_nop 0
	v_pk_fma_f32 v[96:97], v[50:51], v[128:129], v[96:97] op_sel:[0,0,0] op_sel_hi:[1,0,1]
	v_pk_fma_f32 v[98:99], v[50:51], v[128:129], v[98:99] op_sel:[0,1,0] op_sel_hi:[1,1,1]
	v_pk_fma_f32 v[100:101], v[50:51], v[130:131], v[100:101] op_sel:[0,0,0] op_sel_hi:[1,0,1]
	v_pk_fma_f32 v[102:103], v[50:51], v[130:131], v[102:103] op_sel:[0,1,0] op_sel_hi:[1,1,1]
	v_pk_fma_f32 v[104:105], v[50:51], v[132:133], v[104:105] op_sel:[0,0,0] op_sel_hi:[1,0,1]
	v_pk_fma_f32 v[106:107], v[50:51], v[132:133], v[106:107] op_sel:[0,1,0] op_sel_hi:[1,1,1]
	v_pk_fma_f32 v[108:109], v[50:51], v[134:135], v[108:109] op_sel:[0,0,0] op_sel_hi:[1,0,1]
	v_pk_fma_f32 v[110:111], v[50:51], v[134:135], v[110:111] op_sel:[0,1,0] op_sel_hi:[1,1,1]
	v_pk_mul_f32 v[48:49], v[96:97], v[136:137] op_sel:[0,0] op_sel_hi:[1,0]
	v_pk_mul_f32 v[50:51], v[96:97], v[156:157] op_sel:[0,0] op_sel_hi:[1,0]
	v_pk_fma_f32 v[48:49], v[98:99], v[136:137], v[48:49] op_sel:[0,1,0] op_sel_hi:[1,1,1]
	v_pk_fma_f32 v[50:51], v[98:99], v[156:157], v[50:51] op_sel:[0,1,0] op_sel_hi:[1,1,1]
	v_pk_fma_f32 v[48:49], v[100:101], v[138:139], v[48:49] op_sel:[0,0,0] op_sel_hi:[1,0,1]
	v_pk_fma_f32 v[50:51], v[100:101], v[158:159], v[50:51] op_sel:[0,0,0] op_sel_hi:[1,0,1]
	v_pk_fma_f32 v[48:49], v[102:103], v[138:139], v[48:49] op_sel:[0,1,0] op_sel_hi:[1,1,1]
	v_pk_fma_f32 v[50:51], v[102:103], v[158:159], v[50:51] op_sel:[0,1,0] op_sel_hi:[1,1,1]
	v_pk_fma_f32 v[48:49], v[104:105], v[140:141], v[48:49] op_sel:[0,0,0] op_sel_hi:[1,0,1]
	v_pk_fma_f32 v[50:51], v[104:105], v[160:161], v[50:51] op_sel:[0,0,0] op_sel_hi:[1,0,1]
	v_pk_fma_f32 v[48:49], v[106:107], v[140:141], v[48:49] op_sel:[0,1,0] op_sel_hi:[1,1,1]
	v_pk_fma_f32 v[50:51], v[106:107], v[160:161], v[50:51] op_sel:[0,1,0] op_sel_hi:[1,1,1]
	v_pk_fma_f32 v[48:49], v[108:109], v[142:143], v[48:49] op_sel:[0,0,0] op_sel_hi:[1,0,1]
	v_pk_fma_f32 v[50:51], v[108:109], v[162:163], v[50:51] op_sel:[0,0,0] op_sel_hi:[1,0,1]
	v_pk_fma_f32 v[48:49], v[110:111], v[142:143], v[48:49] op_sel:[0,1,0] op_sel_hi:[1,1,1]
	v_pk_fma_f32 v[50:51], v[110:111], v[162:163], v[50:51] op_sel:[0,1,0] op_sel_hi:[1,1,1]
	s_waitcnt lgkmcnt(11)
; #define LAS __attribute__((address_space(3)))
; __device__ __forceinline__ float red8(float x) { x += dpp_mov<0xB1>(x); x += dpp_mov<0x4E>(x); x += dpp_mov<0x141>(x); return x; }
; __device__ __forceinline__ void scan_phase(const KP& P, LAS unsigned char* lds, const int tid, const int bx, const int G) {
;     ...
;             for (int s = 0; s < 32; ++s) {
;                 const LAS float* p = cb + s * 384;
;                 const f32x4 w0 = *(const LAS f32x4*)(p), w1 = *(const LAS f32x4*)(p + 4);
;                 const f32x4 k0 = *(const LAS f32x4*)(p + 64), k1 = *(const LAS f32x4*)(p + 68);
;                 const f32x4 a0 = *(const LAS f32x4*)(p + 128), a1 = *(const LAS f32x4*)(p + 132);
;                 const f32x4 b0 = *(const LAS f32x4*)(p + 192), b1 = *(const LAS f32x4*)(p + 196);
;                 const f32x4 r0 = *(const LAS f32x4*)(p + 256), r1 = *(const LAS f32x4*)(p + 260);
;                 const float vv = buf[(c & 1) * 12288 + s * 384 + 320 + v];
;                 f32x2 sa2 = S[0] * (f32x2){a0.x, a0.y};
;                 sa2 += S[1] * (f32x2){a0.z, a0.w}; sa2 += S[2] * (f32x2){a1.x, a1.y}; sa2 += S[3] * (f32x2){a1.z, a1.w};
;                 const float sa = red8(sa2.x + sa2.y);
;                 const f32x2 sav = {sa, sa}, vv2 = {vv, vv};
;                 S[0] = S[0] * (f32x2){w0.x, w0.y} + sav * (f32x2){b0.x, b0.y} + vv2 * (f32x2){k0.x, k0.y};
;                 S[1] = S[1] * (f32x2){w0.z, w0.w} + sav * (f32x2){b0.z, b0.w} + vv2 * (f32x2){k0.z, k0.w};
;                 S[2] = S[2] * (f32x2){w1.x, w1.y} + sav * (f32x2){b1.x, b1.y} + vv2 * (f32x2){k1.x, k1.y};
;                 S[3] = S[3] * (f32x2){w1.z, w1.w} + sav * (f32x2){b1.z, b1.w} + vv2 * (f32x2){k1.z, k1.w};
;                 f32x2 y2 = S[0] * (f32x2){r0.x, r0.y};
;                 y2 += S[1] * (f32x2){r0.z, r0.w}; y2 += S[2] * (f32x2){r1.x, r1.y}; y2 += S[3] * (f32x2){r1.z, r1.w};
;                 const float y = red8(y2.x + y2.y);
;                 if (kc == 0) ybuf[s * 64 + v] = y;
	ds_read_b128 v[120:123], v44 offset:37120
	ds_read_b128 v[124:127], v44 offset:37136
	ds_read_b128 v[128:131], v44 offset:37632
	ds_read_b128 v[132:135], v44 offset:37648
	ds_read_b128 v[136:139], v44 offset:37888
	ds_read_b128 v[140:143], v44 offset:37904
	ds_read_b64 v[144:145], v46 offset:36864
	ds_read_b128 v[156:159], v44 offset:38912
	ds_read_b128 v[160:163], v44 offset:38928
	v_add_f32_dpp v48, v48, v48 quad_perm:[1,0,3,2] row_mask:0xf bank_mask:0xf bound_ctrl:1
	v_add_f32_dpp v49, v49, v49 quad_perm:[1,0,3,2] row_mask:0xf bank_mask:0xf bound_ctrl:1
	v_add_f32_dpp v50, v50, v50 quad_perm:[1,0,3,2] row_mask:0xf bank_mask:0xf bound_ctrl:1
	v_add_f32_dpp v51, v51, v51 quad_perm:[1,0,3,2] row_mask:0xf bank_mask:0xf bound_ctrl:1
	v_pk_fma_f32 v[96:97], v[146:147], v[70:71], v[96:97] op_sel:[0,0,0] op_sel_hi:[1,0,1]
	v_pk_fma_f32 v[98:99], v[146:147], v[70:71], v[98:99] op_sel:[0,1,0] op_sel_hi:[1,1,1]
	v_pk_fma_f32 v[100:101], v[146:147], v[72:73], v[100:101] op_sel:[0,0,0] op_sel_hi:[1,0,1]
	v_add_f32_dpp v48, v48, v48 quad_perm:[2,3,0,1] row_mask:0xf bank_mask:0xf bound_ctrl:1
	v_add_f32_dpp v49, v49, v49 quad_perm:[2,3,0,1] row_mask:0xf bank_mask:0xf bound_ctrl:1
	v_add_f32_dpp v50, v50, v50 quad_perm:[2,3,0,1] row_mask:0xf bank_mask:0xf bound_ctrl:1
	v_add_f32_dpp v51, v51, v51 quad_perm:[2,3,0,1] row_mask:0xf bank_mask:0xf bound_ctrl:1
	v_pk_fma_f32 v[102:103], v[146:147], v[72:73], v[102:103] op_sel:[0,1,0] op_sel_hi:[1,1,1]
	v_pk_fma_f32 v[104:105], v[146:147], v[74:75], v[104:105] op_sel:[0,0,0] op_sel_hi:[1,0,1]
	v_pk_fma_f32 v[106:107], v[146:147], v[74:75], v[106:107] op_sel:[0,1,0] op_sel_hi:[1,1,1]
	v_add_f32_dpp v48, v48, v48 row_half_mirror row_mask:0xf bank_mask:0xf bound_ctrl:1
	v_add_f32_dpp v49, v49, v49 row_half_mirror row_mask:0xf bank_mask:0xf bound_ctrl:1
	v_add_f32_dpp v50, v50, v50 row_half_mirror row_mask:0xf bank_mask:0xf bound_ctrl:1
	v_add_f32_dpp v51, v51, v51 row_half_mirror row_mask:0xf bank_mask:0xf bound_ctrl:1
	v_pk_fma_f32 v[108:109], v[146:147], v[76:77], v[108:109] op_sel:[0,0,0] op_sel_hi:[1,0,1]
	s_mov_b64 exec, s[10:11]
	ds_write_b64 v45, v[48:49] offset:5376
	s_mov_b64 exec, s[0:1]
	v_pk_fma_f32 v[110:111], v[146:147], v[76:77], v[110:111] op_sel:[0,1,0] op_sel_hi:[1,1,1]
	s_nop 0
	v_pk_fma_f32 v[96:97], v[50:51], v[78:79], v[96:97] op_sel:[0,0,0] op_sel_hi:[1,0,1]
	v_pk_fma_f32 v[98:99], v[50:51], v[78:79], v[98:99] op_sel:[0,1,0] op_sel_hi:[1,1,1]
	v_pk_fma_f32 v[100:101], v[50:51], v[80:81], v[100:101] op_sel:[0,0,0] op_sel_hi:[1,0,1]
	v_pk_fma_f32 v[102:103], v[50:51], v[80:81], v[102:103] op_sel:[0,1,0] op_sel_hi:[1,1,1]
	v_pk_fma_f32 v[104:105], v[50:51], v[82:83], v[104:105] op_sel:[0,0,0] op_sel_hi:[1,0,1]
	v_pk_fma_f32 v[106:107], v[50:51], v[82:83], v[106:107] op_sel:[0,1,0] op_sel_hi:[1,1,1]
	v_pk_fma_f32 v[108:109], v[50:51], v[84:85], v[108:109] op_sel:[0,0,0] op_sel_hi:[1,0,1]
	v_pk_fma_f32 v[110:111], v[50:51], v[84:85], v[110:111] op_sel:[0,1,0] op_sel_hi:[1,1,1]
	v_pk_mul_f32 v[48:49], v[96:97], v[86:87] op_sel:[0,0] op_sel_hi:[1,0]
	v_pk_mul_f32 v[50:51], v[96:97], v[62:63] op_sel:[0,0] op_sel_hi:[1,0]
	v_pk_fma_f32 v[48:49], v[98:99], v[86:87], v[48:49] op_sel:[0,1,0] op_sel_hi:[1,1,1]
	v_pk_fma_f32 v[50:51], v[98:99], v[62:63], v[50:51] op_sel:[0,1,0] op_sel_hi:[1,1,1]
	v_pk_fma_f32 v[48:49], v[100:101], v[88:89], v[48:49] op_sel:[0,0,0] op_sel_hi:[1,0,1]
	v_pk_fma_f32 v[50:51], v[100:101], v[64:65], v[50:51] op_sel:[0,0,0] op_sel_hi:[1,0,1]
	v_pk_fma_f32 v[48:49], v[102:103], v[88:89], v[48:49] op_sel:[0,1,0] op_sel_hi:[1,1,1]
	v_pk_fma_f32 v[50:51], v[102:103], v[64:65], v[50:51] op_sel:[0,1,0] op_sel_hi:[1,1,1]
	v_pk_fma_f32 v[48:49], v[104:105], v[90:91], v[48:49] op_sel:[0,0,0] op_sel_hi:[1,0,1]
	v_pk_fma_f32 v[50:51], v[104:105], v[66:67], v[50:51] op_sel:[0,0,0] op_sel_hi:[1,0,1]
	v_pk_fma_f32 v[48:49], v[106:107], v[90:91], v[48:49] op_sel:[0,1,0] op_sel_hi:[1,1,1]
	v_pk_fma_f32 v[50:51], v[106:107], v[66:67], v[50:51] op_sel:[0,1,0] op_sel_hi:[1,1,1]
	v_pk_fma_f32 v[48:49], v[108:109], v[92:93], v[48:49] op_sel:[0,0,0] op_sel_hi:[1,0,1]
	v_pk_fma_f32 v[50:51], v[108:109], v[68:69], v[50:51] op_sel:[0,0,0] op_sel_hi:[1,0,1]
	v_pk_fma_f32 v[48:49], v[110:111], v[92:93], v[48:49] op_sel:[0,1,0] op_sel_hi:[1,1,1]
	v_pk_fma_f32 v[50:51], v[110:111], v[68:69], v[50:51] op_sel:[0,1,0] op_sel_hi:[1,1,1]
	s_waitcnt lgkmcnt(11)
; #define LAS __attribute__((address_space(3)))
; __device__ __forceinline__ float red8(float x) { x += dpp_mov<0xB1>(x); x += dpp_mov<0x4E>(x); x += dpp_mov<0x141>(x); return x; }
; __device__ __forceinline__ void scan_phase(const KP& P, LAS unsigned char* lds, const int tid, const int bx, const int G) {
;     ...
;             for (int s = 0; s < 32; ++s) {
;                 const LAS float* p = cb + s * 384;
;                 const f32x4 w0 = *(const LAS f32x4*)(p), w1 = *(const LAS f32x4*)(p + 4);
;                 const f32x4 k0 = *(const LAS f32x4*)(p + 64), k1 = *(const LAS f32x4*)(p + 68);
;                 const f32x4 a0 = *(const LAS f32x4*)(p + 128), a1 = *(const LAS f32x4*)(p + 132);
;                 const f32x4 b0 = *(const LAS f32x4*)(p + 192), b1 = *(const LAS f32x4*)(p + 196);
;                 const f32x4 r0 = *(const LAS f32x4*)(p + 256), r1 = *(const LAS f32x4*)(p + 260);
;                 const float vv = buf[(c & 1) * 12288 + s * 384 + 320 + v];
;                 f32x2 sa2 = S[0] * (f32x2){a0.x, a0.y};
;                 sa2 += S[1] * (f32x2){a0.z, a0.w}; sa2 += S[2] * (f32x2){a1.x, a1.y}; sa2 += S[3] * (f32x2){a1.z, a1.w};
;                 const float sa = red8(sa2.x + sa2.y);
;                 const f32x2 sav = {sa, sa}, vv2 = {vv, vv};
;                 S[0] = S[0] * (f32x2){w0.x, w0.y} + sav * (f32x2){b0.x, b0.y} + vv2 * (f32x2){k0.x, k0.y};
;                 S[1] = S[1] * (f32x2){w0.z, w0.w} + sav * (f32x2){b0.z, b0.w} + vv2 * (f32x2){k0.z, k0.w};
;                 S[2] = S[2] * (f32x2){w1.x, w1.y} + sav * (f32x2){b1.x, b1.y} + vv2 * (f32x2){k1.x, k1.y};
;                 S[3] = S[3] * (f32x2){w1.z, w1.w} + sav * (f32x2){b1.z, b1.w} + vv2 * (f32x2){k1.z, k1.w};
;                 f32x2 y2 = S[0] * (f32x2){r0.x, r0.y};
;                 y2 += S[1] * (f32x2){r0.z, r0.w}; y2 += S[2] * (f32x2){r1.x, r1.y}; y2 += S[3] * (f32x2){r1.z, r1.w};
;                 const float y = red8(y2.x + y2.y);
;                 if (kc == 0) ybuf[s * 64 + v] = y;
	ds_read_b128 v[70:73], v44 offset:38656
	ds_read_b128 v[74:77], v44 offset:38672
	ds_read_b128 v[78:81], v44 offset:39168
	ds_read_b128 v[82:85], v44 offset:39184
	ds_read_b128 v[86:89], v44 offset:39424
	ds_read_b128 v[90:93], v44 offset:39440
	ds_read_b64 v[146:147], v46 offset:38400
	ds_read_b128 v[62:65], v44 offset:40448
	ds_read_b128 v[66:69], v44 offset:40464
	v_add_f32_dpp v48, v48, v48 quad_perm:[1,0,3,2] row_mask:0xf bank_mask:0xf bound_ctrl:1
	v_add_f32_dpp v49, v49, v49 quad_perm:[1,0,3,2] row_mask:0xf bank_mask:0xf bound_ctrl:1
	v_add_f32_dpp v50, v50, v50 quad_perm:[1,0,3,2] row_mask:0xf bank_mask:0xf bound_ctrl:1
	v_add_f32_dpp v51, v51, v51 quad_perm:[1,0,3,2] row_mask:0xf bank_mask:0xf bound_ctrl:1
	v_pk_fma_f32 v[96:97], v[192:193], v[168:169], v[96:97] op_sel:[0,0,0] op_sel_hi:[1,0,1]
	v_pk_fma_f32 v[98:99], v[192:193], v[168:169], v[98:99] op_sel:[0,1,0] op_sel_hi:[1,1,1]
	v_pk_fma_f32 v[100:101], v[192:193], v[170:171], v[100:101] op_sel:[0,0,0] op_sel_hi:[1,0,1]
	v_add_f32_dpp v48, v48, v48 quad_perm:[2,3,0,1] row_mask:0xf bank_mask:0xf bound_ctrl:1
	v_add_f32_dpp v49, v49, v49 quad_perm:[2,3,0,1] row_mask:0xf bank_mask:0xf bound_ctrl:1
	v_add_f32_dpp v50, v50, v50 quad_perm:[2,3,0,1] row_mask:0xf bank_mask:0xf bound_ctrl:1
	v_add_f32_dpp v51, v51, v51 quad_perm:[2,3,0,1] row_mask:0xf bank_mask:0xf bound_ctrl:1
	v_pk_fma_f32 v[102:103], v[192:193], v[170:171], v[102:103] op_sel:[0,1,0] op_sel_hi:[1,1,1]
	v_pk_fma_f32 v[104:105], v[192:193], v[172:173], v[104:105] op_sel:[0,0,0] op_sel_hi:[1,0,1]
	v_pk_fma_f32 v[106:107], v[192:193], v[172:173], v[106:107] op_sel:[0,1,0] op_sel_hi:[1,1,1]
	v_add_f32_dpp v48, v48, v48 row_half_mirror row_mask:0xf bank_mask:0xf bound_ctrl:1
	v_add_f32_dpp v49, v49, v49 row_half_mirror row_mask:0xf bank_mask:0xf bound_ctrl:1
	v_add_f32_dpp v50, v50, v50 row_half_mirror row_mask:0xf bank_mask:0xf bound_ctrl:1
	v_add_f32_dpp v51, v51, v51 row_half_mirror row_mask:0xf bank_mask:0xf bound_ctrl:1
	v_pk_fma_f32 v[108:109], v[192:193], v[174:175], v[108:109] op_sel:[0,0,0] op_sel_hi:[1,0,1]
	s_mov_b64 exec, s[10:11]
	ds_write_b64 v45, v[48:49] offset:5632
	s_mov_b64 exec, s[0:1]
	v_pk_fma_f32 v[110:111], v[192:193], v[174:175], v[110:111] op_sel:[0,1,0] op_sel_hi:[1,1,1]
	s_nop 0
	v_pk_fma_f32 v[96:97], v[50:51], v[176:177], v[96:97] op_sel:[0,0,0] op_sel_hi:[1,0,1]
	v_pk_fma_f32 v[98:99], v[50:51], v[176:177], v[98:99] op_sel:[0,1,0] op_sel_hi:[1,1,1]
	v_pk_fma_f32 v[100:101], v[50:51], v[178:179], v[100:101] op_sel:[0,0,0] op_sel_hi:[1,0,1]
	v_pk_fma_f32 v[102:103], v[50:51], v[178:179], v[102:103] op_sel:[0,1,0] op_sel_hi:[1,1,1]
	v_pk_fma_f32 v[104:105], v[50:51], v[180:181], v[104:105] op_sel:[0,0,0] op_sel_hi:[1,0,1]
	v_pk_fma_f32 v[106:107], v[50:51], v[180:181], v[106:107] op_sel:[0,1,0] op_sel_hi:[1,1,1]
	v_pk_fma_f32 v[108:109], v[50:51], v[182:183], v[108:109] op_sel:[0,0,0] op_sel_hi:[1,0,1]
	v_pk_fma_f32 v[110:111], v[50:51], v[182:183], v[110:111] op_sel:[0,1,0] op_sel_hi:[1,1,1]
	v_pk_mul_f32 v[48:49], v[96:97], v[184:185] op_sel:[0,0] op_sel_hi:[1,0]
	v_pk_mul_f32 v[50:51], v[96:97], v[148:149] op_sel:[0,0] op_sel_hi:[1,0]
	v_pk_fma_f32 v[48:49], v[98:99], v[184:185], v[48:49] op_sel:[0,1,0] op_sel_hi:[1,1,1]
	v_pk_fma_f32 v[50:51], v[98:99], v[148:149], v[50:51] op_sel:[0,1,0] op_sel_hi:[1,1,1]
	v_pk_fma_f32 v[48:49], v[100:101], v[186:187], v[48:49] op_sel:[0,0,0] op_sel_hi:[1,0,1]
	v_pk_fma_f32 v[50:51], v[100:101], v[150:151], v[50:51] op_sel:[0,0,0] op_sel_hi:[1,0,1]
	v_pk_fma_f32 v[48:49], v[102:103], v[186:187], v[48:49] op_sel:[0,1,0] op_sel_hi:[1,1,1]
	v_pk_fma_f32 v[50:51], v[102:103], v[150:151], v[50:51] op_sel:[0,1,0] op_sel_hi:[1,1,1]
	v_pk_fma_f32 v[48:49], v[104:105], v[188:189], v[48:49] op_sel:[0,0,0] op_sel_hi:[1,0,1]
	v_pk_fma_f32 v[50:51], v[104:105], v[152:153], v[50:51] op_sel:[0,0,0] op_sel_hi:[1,0,1]
	v_pk_fma_f32 v[48:49], v[106:107], v[188:189], v[48:49] op_sel:[0,1,0] op_sel_hi:[1,1,1]
	v_pk_fma_f32 v[50:51], v[106:107], v[152:153], v[50:51] op_sel:[0,1,0] op_sel_hi:[1,1,1]
	v_pk_fma_f32 v[48:49], v[108:109], v[190:191], v[48:49] op_sel:[0,0,0] op_sel_hi:[1,0,1]
	v_pk_fma_f32 v[50:51], v[108:109], v[154:155], v[50:51] op_sel:[0,0,0] op_sel_hi:[1,0,1]
	v_pk_fma_f32 v[48:49], v[110:111], v[190:191], v[48:49] op_sel:[0,1,0] op_sel_hi:[1,1,1]
	v_pk_fma_f32 v[50:51], v[110:111], v[154:155], v[50:51] op_sel:[0,1,0] op_sel_hi:[1,1,1]
	s_waitcnt lgkmcnt(11)
; #define LAS __attribute__((address_space(3)))
; __device__ __forceinline__ float red8(float x) { x += dpp_mov<0xB1>(x); x += dpp_mov<0x4E>(x); x += dpp_mov<0x141>(x); return x; }
; __device__ __forceinline__ void scan_phase(const KP& P, LAS unsigned char* lds, const int tid, const int bx, const int G) {
;     ...
;             for (int s = 0; s < 32; ++s) {
;                 const LAS float* p = cb + s * 384;
;                 const f32x4 w0 = *(const LAS f32x4*)(p), w1 = *(const LAS f32x4*)(p + 4);
;                 const f32x4 k0 = *(const LAS f32x4*)(p + 64), k1 = *(const LAS f32x4*)(p + 68);
;                 const f32x4 a0 = *(const LAS f32x4*)(p + 128), a1 = *(const LAS f32x4*)(p + 132);
;                 const f32x4 b0 = *(const LAS f32x4*)(p + 192), b1 = *(const LAS f32x4*)(p + 196);
;                 const f32x4 r0 = *(const LAS f32x4*)(p + 256), r1 = *(const LAS f32x4*)(p + 260);
;                 const float vv = buf[(c & 1) * 12288 + s * 384 + 320 + v];
;                 f32x2 sa2 = S[0] * (f32x2){a0.x, a0.y};
;                 sa2 += S[1] * (f32x2){a0.z, a0.w}; sa2 += S[2] * (f32x2){a1.x, a1.y}; sa2 += S[3] * (f32x2){a1.z, a1.w};
;                 const float sa = red8(sa2.x + sa2.y);
;                 const f32x2 sav = {sa, sa}, vv2 = {vv, vv};
;                 S[0] = S[0] * (f32x2){w0.x, w0.y} + sav * (f32x2){b0.x, b0.y} + vv2 * (f32x2){k0.x, k0.y};
;                 S[1] = S[1] * (f32x2){w0.z, w0.w} + sav * (f32x2){b0.z, b0.w} + vv2 * (f32x2){k0.z, k0.w};
;                 S[2] = S[2] * (f32x2){w1.x, w1.y} + sav * (f32x2){b1.x, b1.y} + vv2 * (f32x2){k1.x, k1.y};
;                 S[3] = S[3] * (f32x2){w1.z, w1.w} + sav * (f32x2){b1.z, b1.w} + vv2 * (f32x2){k1.z, k1.w};
;                 f32x2 y2 = S[0] * (f32x2){r0.x, r0.y};
;                 y2 += S[1] * (f32x2){r0.z, r0.w}; y2 += S[2] * (f32x2){r1.x, r1.y}; y2 += S[3] * (f32x2){r1.z, r1.w};
;                 const float y = red8(y2.x + y2.y);
;                 if (kc == 0) ybuf[s * 64 + v] = y;
	ds_read_b128 v[168:171], v44 offset:40192
	ds_read_b128 v[172:175], v44 offset:40208
	ds_read_b128 v[176:179], v44 offset:40704
	ds_read_b128 v[180:183], v44 offset:40720
	ds_read_b128 v[184:187], v44 offset:40960
	ds_read_b128 v[188:191], v44 offset:40976
	ds_read_b64 v[192:193], v46 offset:39936
	ds_read_b128 v[148:151], v44 offset:41984
	ds_read_b128 v[152:155], v44 offset:42000
	v_add_f32_dpp v48, v48, v48 quad_perm:[1,0,3,2] row_mask:0xf bank_mask:0xf bound_ctrl:1
	v_add_f32_dpp v49, v49, v49 quad_perm:[1,0,3,2] row_mask:0xf bank_mask:0xf bound_ctrl:1
	v_add_f32_dpp v50, v50, v50 quad_perm:[1,0,3,2] row_mask:0xf bank_mask:0xf bound_ctrl:1
	v_add_f32_dpp v51, v51, v51 quad_perm:[1,0,3,2] row_mask:0xf bank_mask:0xf bound_ctrl:1
	v_pk_fma_f32 v[96:97], v[144:145], v[120:121], v[96:97] op_sel:[0,0,0] op_sel_hi:[1,0,1]
	v_pk_fma_f32 v[98:99], v[144:145], v[120:121], v[98:99] op_sel:[0,1,0] op_sel_hi:[1,1,1]
	v_pk_fma_f32 v[100:101], v[144:145], v[122:123], v[100:101] op_sel:[0,0,0] op_sel_hi:[1,0,1]
	v_add_f32_dpp v48, v48, v48 quad_perm:[2,3,0,1] row_mask:0xf bank_mask:0xf bound_ctrl:1
	v_add_f32_dpp v49, v49, v49 quad_perm:[2,3,0,1] row_mask:0xf bank_mask:0xf bound_ctrl:1
	v_add_f32_dpp v50, v50, v50 quad_perm:[2,3,0,1] row_mask:0xf bank_mask:0xf bound_ctrl:1
	v_add_f32_dpp v51, v51, v51 quad_perm:[2,3,0,1] row_mask:0xf bank_mask:0xf bound_ctrl:1
	v_pk_fma_f32 v[102:103], v[144:145], v[122:123], v[102:103] op_sel:[0,1,0] op_sel_hi:[1,1,1]
	v_pk_fma_f32 v[104:105], v[144:145], v[124:125], v[104:105] op_sel:[0,0,0] op_sel_hi:[1,0,1]
	v_pk_fma_f32 v[106:107], v[144:145], v[124:125], v[106:107] op_sel:[0,1,0] op_sel_hi:[1,1,1]
	v_add_f32_dpp v48, v48, v48 row_half_mirror row_mask:0xf bank_mask:0xf bound_ctrl:1
	v_add_f32_dpp v49, v49, v49 row_half_mirror row_mask:0xf bank_mask:0xf bound_ctrl:1
	v_add_f32_dpp v50, v50, v50 row_half_mirror row_mask:0xf bank_mask:0xf bound_ctrl:1
	v_add_f32_dpp v51, v51, v51 row_half_mirror row_mask:0xf bank_mask:0xf bound_ctrl:1
	v_pk_fma_f32 v[108:109], v[144:145], v[126:127], v[108:109] op_sel:[0,0,0] op_sel_hi:[1,0,1]
	s_mov_b64 exec, s[10:11]
	ds_write_b64 v45, v[48:49] offset:5888
	s_mov_b64 exec, s[0:1]
	v_pk_fma_f32 v[110:111], v[144:145], v[126:127], v[110:111] op_sel:[0,1,0] op_sel_hi:[1,1,1]
	s_nop 0
	v_pk_fma_f32 v[96:97], v[50:51], v[128:129], v[96:97] op_sel:[0,0,0] op_sel_hi:[1,0,1]
	v_pk_fma_f32 v[98:99], v[50:51], v[128:129], v[98:99] op_sel:[0,1,0] op_sel_hi:[1,1,1]
	v_pk_fma_f32 v[100:101], v[50:51], v[130:131], v[100:101] op_sel:[0,0,0] op_sel_hi:[1,0,1]
	v_pk_fma_f32 v[102:103], v[50:51], v[130:131], v[102:103] op_sel:[0,1,0] op_sel_hi:[1,1,1]
	v_pk_fma_f32 v[104:105], v[50:51], v[132:133], v[104:105] op_sel:[0,0,0] op_sel_hi:[1,0,1]
	v_pk_fma_f32 v[106:107], v[50:51], v[132:133], v[106:107] op_sel:[0,1,0] op_sel_hi:[1,1,1]
	v_pk_fma_f32 v[108:109], v[50:51], v[134:135], v[108:109] op_sel:[0,0,0] op_sel_hi:[1,0,1]
	v_pk_fma_f32 v[110:111], v[50:51], v[134:135], v[110:111] op_sel:[0,1,0] op_sel_hi:[1,1,1]
	v_pk_mul_f32 v[48:49], v[96:97], v[136:137] op_sel:[0,0] op_sel_hi:[1,0]
	v_pk_mul_f32 v[50:51], v[96:97], v[156:157] op_sel:[0,0] op_sel_hi:[1,0]
	v_pk_fma_f32 v[48:49], v[98:99], v[136:137], v[48:49] op_sel:[0,1,0] op_sel_hi:[1,1,1]
	v_pk_fma_f32 v[50:51], v[98:99], v[156:157], v[50:51] op_sel:[0,1,0] op_sel_hi:[1,1,1]
	v_pk_fma_f32 v[48:49], v[100:101], v[138:139], v[48:49] op_sel:[0,0,0] op_sel_hi:[1,0,1]
	v_pk_fma_f32 v[50:51], v[100:101], v[158:159], v[50:51] op_sel:[0,0,0] op_sel_hi:[1,0,1]
	v_pk_fma_f32 v[48:49], v[102:103], v[138:139], v[48:49] op_sel:[0,1,0] op_sel_hi:[1,1,1]
	v_pk_fma_f32 v[50:51], v[102:103], v[158:159], v[50:51] op_sel:[0,1,0] op_sel_hi:[1,1,1]
	v_pk_fma_f32 v[48:49], v[104:105], v[140:141], v[48:49] op_sel:[0,0,0] op_sel_hi:[1,0,1]
	v_pk_fma_f32 v[50:51], v[104:105], v[160:161], v[50:51] op_sel:[0,0,0] op_sel_hi:[1,0,1]
	v_pk_fma_f32 v[48:49], v[106:107], v[140:141], v[48:49] op_sel:[0,1,0] op_sel_hi:[1,1,1]
	v_pk_fma_f32 v[50:51], v[106:107], v[160:161], v[50:51] op_sel:[0,1,0] op_sel_hi:[1,1,1]
	v_pk_fma_f32 v[48:49], v[108:109], v[142:143], v[48:49] op_sel:[0,0,0] op_sel_hi:[1,0,1]
	v_pk_fma_f32 v[50:51], v[108:109], v[162:163], v[50:51] op_sel:[0,0,0] op_sel_hi:[1,0,1]
	v_pk_fma_f32 v[48:49], v[110:111], v[142:143], v[48:49] op_sel:[0,1,0] op_sel_hi:[1,1,1]
	v_pk_fma_f32 v[50:51], v[110:111], v[162:163], v[50:51] op_sel:[0,1,0] op_sel_hi:[1,1,1]
	s_waitcnt lgkmcnt(11)
; #define LAS __attribute__((address_space(3)))
; __device__ __forceinline__ float red8(float x) { x += dpp_mov<0xB1>(x); x += dpp_mov<0x4E>(x); x += dpp_mov<0x141>(x); return x; }
; __device__ __forceinline__ void scan_phase(const KP& P, LAS unsigned char* lds, const int tid, const int bx, const int G) {
;     ...
;             for (int s = 0; s < 32; ++s) {
;                 const LAS float* p = cb + s * 384;
;                 const f32x4 w0 = *(const LAS f32x4*)(p), w1 = *(const LAS f32x4*)(p + 4);
;                 const f32x4 k0 = *(const LAS f32x4*)(p + 64), k1 = *(const LAS f32x4*)(p + 68);
;                 const f32x4 a0 = *(const LAS f32x4*)(p + 128), a1 = *(const LAS f32x4*)(p + 132);
;                 const f32x4 b0 = *(const LAS f32x4*)(p + 192), b1 = *(const LAS f32x4*)(p + 196);
;                 const f32x4 r0 = *(const LAS f32x4*)(p + 256), r1 = *(const LAS f32x4*)(p + 260);
;                 const float vv = buf[(c & 1) * 12288 + s * 384 + 320 + v];
;                 f32x2 sa2 = S[0] * (f32x2){a0.x, a0.y};
;                 sa2 += S[1] * (f32x2){a0.z, a0.w}; sa2 += S[2] * (f32x2){a1.x, a1.y}; sa2 += S[3] * (f32x2){a1.z, a1.w};
;                 const float sa = red8(sa2.x + sa2.y);
;                 const f32x2 sav = {sa, sa}, vv2 = {vv, vv};
;                 S[0] = S[0] * (f32x2){w0.x, w0.y} + sav * (f32x2){b0.x, b0.y} + vv2 * (f32x2){k0.x, k0.y};
;                 S[1] = S[1] * (f32x2){w0.z, w0.w} + sav * (f32x2){b0.z, b0.w} + vv2 * (f32x2){k0.z, k0.w};
;                 S[2] = S[2] * (f32x2){w1.x, w1.y} + sav * (f32x2){b1.x, b1.y} + vv2 * (f32x2){k1.x, k1.y};
;                 S[3] = S[3] * (f32x2){w1.z, w1.w} + sav * (f32x2){b1.z, b1.w} + vv2 * (f32x2){k1.z, k1.w};
;                 f32x2 y2 = S[0] * (f32x2){r0.x, r0.y};
;                 y2 += S[1] * (f32x2){r0.z, r0.w}; y2 += S[2] * (f32x2){r1.x, r1.y}; y2 += S[3] * (f32x2){r1.z, r1.w};
;                 const float y = red8(y2.x + y2.y);
;                 if (kc == 0) ybuf[s * 64 + v] = y;
	ds_read_b128 v[120:123], v44 offset:41728
	ds_read_b128 v[124:127], v44 offset:41744
	ds_read_b128 v[128:131], v44 offset:42240
	ds_read_b128 v[132:135], v44 offset:42256
	ds_read_b128 v[136:139], v44 offset:42496
	ds_read_b128 v[140:143], v44 offset:42512
	ds_read_b64 v[144:145], v46 offset:41472
	ds_read_b128 v[156:159], v44 offset:43520
	ds_read_b128 v[160:163], v44 offset:43536
	v_add_f32_dpp v48, v48, v48 quad_perm:[1,0,3,2] row_mask:0xf bank_mask:0xf bound_ctrl:1
	v_add_f32_dpp v49, v49, v49 quad_perm:[1,0,3,2] row_mask:0xf bank_mask:0xf bound_ctrl:1
	v_add_f32_dpp v50, v50, v50 quad_perm:[1,0,3,2] row_mask:0xf bank_mask:0xf bound_ctrl:1
	v_add_f32_dpp v51, v51, v51 quad_perm:[1,0,3,2] row_mask:0xf bank_mask:0xf bound_ctrl:1
	v_pk_fma_f32 v[96:97], v[146:147], v[70:71], v[96:97] op_sel:[0,0,0] op_sel_hi:[1,0,1]
	v_pk_fma_f32 v[98:99], v[146:147], v[70:71], v[98:99] op_sel:[0,1,0] op_sel_hi:[1,1,1]
	v_pk_fma_f32 v[100:101], v[146:147], v[72:73], v[100:101] op_sel:[0,0,0] op_sel_hi:[1,0,1]
	v_add_f32_dpp v48, v48, v48 quad_perm:[2,3,0,1] row_mask:0xf bank_mask:0xf bound_ctrl:1
	v_add_f32_dpp v49, v49, v49 quad_perm:[2,3,0,1] row_mask:0xf bank_mask:0xf bound_ctrl:1
	v_add_f32_dpp v50, v50, v50 quad_perm:[2,3,0,1] row_mask:0xf bank_mask:0xf bound_ctrl:1
	v_add_f32_dpp v51, v51, v51 quad_perm:[2,3,0,1] row_mask:0xf bank_mask:0xf bound_ctrl:1
	v_pk_fma_f32 v[102:103], v[146:147], v[72:73], v[102:103] op_sel:[0,1,0] op_sel_hi:[1,1,1]
	v_pk_fma_f32 v[104:105], v[146:147], v[74:75], v[104:105] op_sel:[0,0,0] op_sel_hi:[1,0,1]
	v_pk_fma_f32 v[106:107], v[146:147], v[74:75], v[106:107] op_sel:[0,1,0] op_sel_hi:[1,1,1]
	v_add_f32_dpp v48, v48, v48 row_half_mirror row_mask:0xf bank_mask:0xf bound_ctrl:1
	v_add_f32_dpp v49, v49, v49 row_half_mirror row_mask:0xf bank_mask:0xf bound_ctrl:1
	v_add_f32_dpp v50, v50, v50 row_half_mirror row_mask:0xf bank_mask:0xf bound_ctrl:1
	v_add_f32_dpp v51, v51, v51 row_half_mirror row_mask:0xf bank_mask:0xf bound_ctrl:1
	v_pk_fma_f32 v[108:109], v[146:147], v[76:77], v[108:109] op_sel:[0,0,0] op_sel_hi:[1,0,1]
	s_mov_b64 exec, s[10:11]
	ds_write_b64 v45, v[48:49] offset:6144
	s_mov_b64 exec, s[0:1]
	v_pk_fma_f32 v[110:111], v[146:147], v[76:77], v[110:111] op_sel:[0,1,0] op_sel_hi:[1,1,1]
	s_nop 0
	v_pk_fma_f32 v[96:97], v[50:51], v[78:79], v[96:97] op_sel:[0,0,0] op_sel_hi:[1,0,1]
	v_pk_fma_f32 v[98:99], v[50:51], v[78:79], v[98:99] op_sel:[0,1,0] op_sel_hi:[1,1,1]
	v_pk_fma_f32 v[100:101], v[50:51], v[80:81], v[100:101] op_sel:[0,0,0] op_sel_hi:[1,0,1]
	v_pk_fma_f32 v[102:103], v[50:51], v[80:81], v[102:103] op_sel:[0,1,0] op_sel_hi:[1,1,1]
	v_pk_fma_f32 v[104:105], v[50:51], v[82:83], v[104:105] op_sel:[0,0,0] op_sel_hi:[1,0,1]
	v_pk_fma_f32 v[106:107], v[50:51], v[82:83], v[106:107] op_sel:[0,1,0] op_sel_hi:[1,1,1]
	v_pk_fma_f32 v[108:109], v[50:51], v[84:85], v[108:109] op_sel:[0,0,0] op_sel_hi:[1,0,1]
	v_pk_fma_f32 v[110:111], v[50:51], v[84:85], v[110:111] op_sel:[0,1,0] op_sel_hi:[1,1,1]
	v_pk_mul_f32 v[48:49], v[96:97], v[86:87] op_sel:[0,0] op_sel_hi:[1,0]
	v_pk_mul_f32 v[50:51], v[96:97], v[62:63] op_sel:[0,0] op_sel_hi:[1,0]
	v_pk_fma_f32 v[48:49], v[98:99], v[86:87], v[48:49] op_sel:[0,1,0] op_sel_hi:[1,1,1]
	v_pk_fma_f32 v[50:51], v[98:99], v[62:63], v[50:51] op_sel:[0,1,0] op_sel_hi:[1,1,1]
	v_pk_fma_f32 v[48:49], v[100:101], v[88:89], v[48:49] op_sel:[0,0,0] op_sel_hi:[1,0,1]
	v_pk_fma_f32 v[50:51], v[100:101], v[64:65], v[50:51] op_sel:[0,0,0] op_sel_hi:[1,0,1]
	v_pk_fma_f32 v[48:49], v[102:103], v[88:89], v[48:49] op_sel:[0,1,0] op_sel_hi:[1,1,1]
	v_pk_fma_f32 v[50:51], v[102:103], v[64:65], v[50:51] op_sel:[0,1,0] op_sel_hi:[1,1,1]
	v_pk_fma_f32 v[48:49], v[104:105], v[90:91], v[48:49] op_sel:[0,0,0] op_sel_hi:[1,0,1]
	v_pk_fma_f32 v[50:51], v[104:105], v[66:67], v[50:51] op_sel:[0,0,0] op_sel_hi:[1,0,1]
	v_pk_fma_f32 v[48:49], v[106:107], v[90:91], v[48:49] op_sel:[0,1,0] op_sel_hi:[1,1,1]
	v_pk_fma_f32 v[50:51], v[106:107], v[66:67], v[50:51] op_sel:[0,1,0] op_sel_hi:[1,1,1]
	v_pk_fma_f32 v[48:49], v[108:109], v[92:93], v[48:49] op_sel:[0,0,0] op_sel_hi:[1,0,1]
	v_pk_fma_f32 v[50:51], v[108:109], v[68:69], v[50:51] op_sel:[0,0,0] op_sel_hi:[1,0,1]
	v_pk_fma_f32 v[48:49], v[110:111], v[92:93], v[48:49] op_sel:[0,1,0] op_sel_hi:[1,1,1]
	v_pk_fma_f32 v[50:51], v[110:111], v[68:69], v[50:51] op_sel:[0,1,0] op_sel_hi:[1,1,1]
	s_waitcnt lgkmcnt(11)
; #define LAS __attribute__((address_space(3)))
; __device__ __forceinline__ float red8(float x) { x += dpp_mov<0xB1>(x); x += dpp_mov<0x4E>(x); x += dpp_mov<0x141>(x); return x; }
; __device__ __forceinline__ void scan_phase(const KP& P, LAS unsigned char* lds, const int tid, const int bx, const int G) {
;     ...
;             for (int s = 0; s < 32; ++s) {
;                 const LAS float* p = cb + s * 384;
;                 const f32x4 w0 = *(const LAS f32x4*)(p), w1 = *(const LAS f32x4*)(p + 4);
;                 const f32x4 k0 = *(const LAS f32x4*)(p + 64), k1 = *(const LAS f32x4*)(p + 68);
;                 const f32x4 a0 = *(const LAS f32x4*)(p + 128), a1 = *(const LAS f32x4*)(p + 132);
;                 const f32x4 b0 = *(const LAS f32x4*)(p + 192), b1 = *(const LAS f32x4*)(p + 196);
;                 const f32x4 r0 = *(const LAS f32x4*)(p + 256), r1 = *(const LAS f32x4*)(p + 260);
;                 const float vv = buf[(c & 1) * 12288 + s * 384 + 320 + v];
;                 f32x2 sa2 = S[0] * (f32x2){a0.x, a0.y};
;                 sa2 += S[1] * (f32x2){a0.z, a0.w}; sa2 += S[2] * (f32x2){a1.x, a1.y}; sa2 += S[3] * (f32x2){a1.z, a1.w};
;                 const float sa = red8(sa2.x + sa2.y);
;                 const f32x2 sav = {sa, sa}, vv2 = {vv, vv};
;                 S[0] = S[0] * (f32x2){w0.x, w0.y} + sav * (f32x2){b0.x, b0.y} + vv2 * (f32x2){k0.x, k0.y};
;                 S[1] = S[1] * (f32x2){w0.z, w0.w} + sav * (f32x2){b0.z, b0.w} + vv2 * (f32x2){k0.z, k0.w};
;                 S[2] = S[2] * (f32x2){w1.x, w1.y} + sav * (f32x2){b1.x, b1.y} + vv2 * (f32x2){k1.x, k1.y};
;                 S[3] = S[3] * (f32x2){w1.z, w1.w} + sav * (f32x2){b1.z, b1.w} + vv2 * (f32x2){k1.z, k1.w};
;                 f32x2 y2 = S[0] * (f32x2){r0.x, r0.y};
;                 y2 += S[1] * (f32x2){r0.z, r0.w}; y2 += S[2] * (f32x2){r1.x, r1.y}; y2 += S[3] * (f32x2){r1.z, r1.w};
;                 const float y = red8(y2.x + y2.y);
;                 if (kc == 0) ybuf[s * 64 + v] = y;
	ds_read_b128 v[70:73], v44 offset:43264
	ds_read_b128 v[74:77], v44 offset:43280
	ds_read_b128 v[78:81], v44 offset:43776
	ds_read_b128 v[82:85], v44 offset:43792
	ds_read_b128 v[86:89], v44 offset:44032
	ds_read_b128 v[90:93], v44 offset:44048
	ds_read_b64 v[146:147], v46 offset:43008
	ds_read_b128 v[62:65], v44 offset:45056
	ds_read_b128 v[66:69], v44 offset:45072
	v_add_f32_dpp v48, v48, v48 quad_perm:[1,0,3,2] row_mask:0xf bank_mask:0xf bound_ctrl:1
	v_add_f32_dpp v49, v49, v49 quad_perm:[1,0,3,2] row_mask:0xf bank_mask:0xf bound_ctrl:1
	v_add_f32_dpp v50, v50, v50 quad_perm:[1,0,3,2] row_mask:0xf bank_mask:0xf bound_ctrl:1
	v_add_f32_dpp v51, v51, v51 quad_perm:[1,0,3,2] row_mask:0xf bank_mask:0xf bound_ctrl:1
	v_pk_fma_f32 v[96:97], v[192:193], v[168:169], v[96:97] op_sel:[0,0,0] op_sel_hi:[1,0,1]
	v_pk_fma_f32 v[98:99], v[192:193], v[168:169], v[98:99] op_sel:[0,1,0] op_sel_hi:[1,1,1]
	v_pk_fma_f32 v[100:101], v[192:193], v[170:171], v[100:101] op_sel:[0,0,0] op_sel_hi:[1,0,1]
	v_add_f32_dpp v48, v48, v48 quad_perm:[2,3,0,1] row_mask:0xf bank_mask:0xf bound_ctrl:1
	v_add_f32_dpp v49, v49, v49 quad_perm:[2,3,0,1] row_mask:0xf bank_mask:0xf bound_ctrl:1
	v_add_f32_dpp v50, v50, v50 quad_perm:[2,3,0,1] row_mask:0xf bank_mask:0xf bound_ctrl:1
	v_add_f32_dpp v51, v51, v51 quad_perm:[2,3,0,1] row_mask:0xf bank_mask:0xf bound_ctrl:1
	v_pk_fma_f32 v[102:103], v[192:193], v[170:171], v[102:103] op_sel:[0,1,0] op_sel_hi:[1,1,1]
	v_pk_fma_f32 v[104:105], v[192:193], v[172:173], v[104:105] op_sel:[0,0,0] op_sel_hi:[1,0,1]
	v_pk_fma_f32 v[106:107], v[192:193], v[172:173], v[106:107] op_sel:[0,1,0] op_sel_hi:[1,1,1]
	v_add_f32_dpp v48, v48, v48 row_half_mirror row_mask:0xf bank_mask:0xf bound_ctrl:1
	v_add_f32_dpp v49, v49, v49 row_half_mirror row_mask:0xf bank_mask:0xf bound_ctrl:1
	v_add_f32_dpp v50, v50, v50 row_half_mirror row_mask:0xf bank_mask:0xf bound_ctrl:1
	v_add_f32_dpp v51, v51, v51 row_half_mirror row_mask:0xf bank_mask:0xf bound_ctrl:1
	v_pk_fma_f32 v[108:109], v[192:193], v[174:175], v[108:109] op_sel:[0,0,0] op_sel_hi:[1,0,1]
	s_mov_b64 exec, s[10:11]
	ds_write_b64 v45, v[48:49] offset:6400
	s_mov_b64 exec, s[0:1]
	v_pk_fma_f32 v[110:111], v[192:193], v[174:175], v[110:111] op_sel:[0,1,0] op_sel_hi:[1,1,1]
	s_nop 0
	v_pk_fma_f32 v[96:97], v[50:51], v[176:177], v[96:97] op_sel:[0,0,0] op_sel_hi:[1,0,1]
	v_pk_fma_f32 v[98:99], v[50:51], v[176:177], v[98:99] op_sel:[0,1,0] op_sel_hi:[1,1,1]
	v_pk_fma_f32 v[100:101], v[50:51], v[178:179], v[100:101] op_sel:[0,0,0] op_sel_hi:[1,0,1]
	v_pk_fma_f32 v[102:103], v[50:51], v[178:179], v[102:103] op_sel:[0,1,0] op_sel_hi:[1,1,1]
	v_pk_fma_f32 v[104:105], v[50:51], v[180:181], v[104:105] op_sel:[0,0,0] op_sel_hi:[1,0,1]
	v_pk_fma_f32 v[106:107], v[50:51], v[180:181], v[106:107] op_sel:[0,1,0] op_sel_hi:[1,1,1]
	v_pk_fma_f32 v[108:109], v[50:51], v[182:183], v[108:109] op_sel:[0,0,0] op_sel_hi:[1,0,1]
	v_pk_fma_f32 v[110:111], v[50:51], v[182:183], v[110:111] op_sel:[0,1,0] op_sel_hi:[1,1,1]
	v_pk_mul_f32 v[48:49], v[96:97], v[184:185] op_sel:[0,0] op_sel_hi:[1,0]
	v_pk_mul_f32 v[50:51], v[96:97], v[148:149] op_sel:[0,0] op_sel_hi:[1,0]
	v_pk_fma_f32 v[48:49], v[98:99], v[184:185], v[48:49] op_sel:[0,1,0] op_sel_hi:[1,1,1]
	v_pk_fma_f32 v[50:51], v[98:99], v[148:149], v[50:51] op_sel:[0,1,0] op_sel_hi:[1,1,1]
	v_pk_fma_f32 v[48:49], v[100:101], v[186:187], v[48:49] op_sel:[0,0,0] op_sel_hi:[1,0,1]
	v_pk_fma_f32 v[50:51], v[100:101], v[150:151], v[50:51] op_sel:[0,0,0] op_sel_hi:[1,0,1]
	v_pk_fma_f32 v[48:49], v[102:103], v[186:187], v[48:49] op_sel:[0,1,0] op_sel_hi:[1,1,1]
	v_pk_fma_f32 v[50:51], v[102:103], v[150:151], v[50:51] op_sel:[0,1,0] op_sel_hi:[1,1,1]
	v_pk_fma_f32 v[48:49], v[104:105], v[188:189], v[48:49] op_sel:[0,0,0] op_sel_hi:[1,0,1]
	v_pk_fma_f32 v[50:51], v[104:105], v[152:153], v[50:51] op_sel:[0,0,0] op_sel_hi:[1,0,1]
	v_pk_fma_f32 v[48:49], v[106:107], v[188:189], v[48:49] op_sel:[0,1,0] op_sel_hi:[1,1,1]
	v_pk_fma_f32 v[50:51], v[106:107], v[152:153], v[50:51] op_sel:[0,1,0] op_sel_hi:[1,1,1]
	v_pk_fma_f32 v[48:49], v[108:109], v[190:191], v[48:49] op_sel:[0,0,0] op_sel_hi:[1,0,1]
	v_pk_fma_f32 v[50:51], v[108:109], v[154:155], v[50:51] op_sel:[0,0,0] op_sel_hi:[1,0,1]
	v_pk_fma_f32 v[48:49], v[110:111], v[190:191], v[48:49] op_sel:[0,1,0] op_sel_hi:[1,1,1]
	v_pk_fma_f32 v[50:51], v[110:111], v[154:155], v[50:51] op_sel:[0,1,0] op_sel_hi:[1,1,1]
	s_waitcnt lgkmcnt(11)
; #define LAS __attribute__((address_space(3)))
; __device__ __forceinline__ float red8(float x) { x += dpp_mov<0xB1>(x); x += dpp_mov<0x4E>(x); x += dpp_mov<0x141>(x); return x; }
; __device__ __forceinline__ void scan_phase(const KP& P, LAS unsigned char* lds, const int tid, const int bx, const int G) {
;     ...
;             for (int s = 0; s < 32; ++s) {
;                 const LAS float* p = cb + s * 384;
;                 const f32x4 w0 = *(const LAS f32x4*)(p), w1 = *(const LAS f32x4*)(p + 4);
;                 const f32x4 k0 = *(const LAS f32x4*)(p + 64), k1 = *(const LAS f32x4*)(p + 68);
;                 const f32x4 a0 = *(const LAS f32x4*)(p + 128), a1 = *(const LAS f32x4*)(p + 132);
;                 const f32x4 b0 = *(const LAS f32x4*)(p + 192), b1 = *(const LAS f32x4*)(p + 196);
;                 const f32x4 r0 = *(const LAS f32x4*)(p + 256), r1 = *(const LAS f32x4*)(p + 260);
;                 const float vv = buf[(c & 1) * 12288 + s * 384 + 320 + v];
;                 f32x2 sa2 = S[0] * (f32x2){a0.x, a0.y};
;                 sa2 += S[1] * (f32x2){a0.z, a0.w}; sa2 += S[2] * (f32x2){a1.x, a1.y}; sa2 += S[3] * (f32x2){a1.z, a1.w};
;                 const float sa = red8(sa2.x + sa2.y);
;                 const f32x2 sav = {sa, sa}, vv2 = {vv, vv};
;                 S[0] = S[0] * (f32x2){w0.x, w0.y} + sav * (f32x2){b0.x, b0.y} + vv2 * (f32x2){k0.x, k0.y};
;                 S[1] = S[1] * (f32x2){w0.z, w0.w} + sav * (f32x2){b0.z, b0.w} + vv2 * (f32x2){k0.z, k0.w};
;                 S[2] = S[2] * (f32x2){w1.x, w1.y} + sav * (f32x2){b1.x, b1.y} + vv2 * (f32x2){k1.x, k1.y};
;                 S[3] = S[3] * (f32x2){w1.z, w1.w} + sav * (f32x2){b1.z, b1.w} + vv2 * (f32x2){k1.z, k1.w};
;                 f32x2 y2 = S[0] * (f32x2){r0.x, r0.y};
;                 y2 += S[1] * (f32x2){r0.z, r0.w}; y2 += S[2] * (f32x2){r1.x, r1.y}; y2 += S[3] * (f32x2){r1.z, r1.w};
;                 const float y = red8(y2.x + y2.y);
;                 if (kc == 0) ybuf[s * 64 + v] = y;
	ds_read_b128 v[168:171], v44 offset:44800
	ds_read_b128 v[172:175], v44 offset:44816
	ds_read_b128 v[176:179], v44 offset:45312
	ds_read_b128 v[180:183], v44 offset:45328
	ds_read_b128 v[184:187], v44 offset:45568
	ds_read_b128 v[188:191], v44 offset:45584
	ds_read_b64 v[192:193], v46 offset:44544
	ds_read_b128 v[148:151], v44 offset:46592
	ds_read_b128 v[152:155], v44 offset:46608
	v_add_f32_dpp v48, v48, v48 quad_perm:[1,0,3,2] row_mask:0xf bank_mask:0xf bound_ctrl:1
	v_add_f32_dpp v49, v49, v49 quad_perm:[1,0,3,2] row_mask:0xf bank_mask:0xf bound_ctrl:1
	v_add_f32_dpp v50, v50, v50 quad_perm:[1,0,3,2] row_mask:0xf bank_mask:0xf bound_ctrl:1
	v_add_f32_dpp v51, v51, v51 quad_perm:[1,0,3,2] row_mask:0xf bank_mask:0xf bound_ctrl:1
	v_pk_fma_f32 v[96:97], v[144:145], v[120:121], v[96:97] op_sel:[0,0,0] op_sel_hi:[1,0,1]
	v_pk_fma_f32 v[98:99], v[144:145], v[120:121], v[98:99] op_sel:[0,1,0] op_sel_hi:[1,1,1]
	v_pk_fma_f32 v[100:101], v[144:145], v[122:123], v[100:101] op_sel:[0,0,0] op_sel_hi:[1,0,1]
	v_add_f32_dpp v48, v48, v48 quad_perm:[2,3,0,1] row_mask:0xf bank_mask:0xf bound_ctrl:1
	v_add_f32_dpp v49, v49, v49 quad_perm:[2,3,0,1] row_mask:0xf bank_mask:0xf bound_ctrl:1
	v_add_f32_dpp v50, v50, v50 quad_perm:[2,3,0,1] row_mask:0xf bank_mask:0xf bound_ctrl:1
	v_add_f32_dpp v51, v51, v51 quad_perm:[2,3,0,1] row_mask:0xf bank_mask:0xf bound_ctrl:1
	v_pk_fma_f32 v[102:103], v[144:145], v[122:123], v[102:103] op_sel:[0,1,0] op_sel_hi:[1,1,1]
	v_pk_fma_f32 v[104:105], v[144:145], v[124:125], v[104:105] op_sel:[0,0,0] op_sel_hi:[1,0,1]
	v_pk_fma_f32 v[106:107], v[144:145], v[124:125], v[106:107] op_sel:[0,1,0] op_sel_hi:[1,1,1]
	v_add_f32_dpp v48, v48, v48 row_half_mirror row_mask:0xf bank_mask:0xf bound_ctrl:1
	v_add_f32_dpp v49, v49, v49 row_half_mirror row_mask:0xf bank_mask:0xf bound_ctrl:1
	v_add_f32_dpp v50, v50, v50 row_half_mirror row_mask:0xf bank_mask:0xf bound_ctrl:1
	v_add_f32_dpp v51, v51, v51 row_half_mirror row_mask:0xf bank_mask:0xf bound_ctrl:1
	v_pk_fma_f32 v[108:109], v[144:145], v[126:127], v[108:109] op_sel:[0,0,0] op_sel_hi:[1,0,1]
	s_mov_b64 exec, s[10:11]
	ds_write_b64 v45, v[48:49] offset:6656
	s_mov_b64 exec, s[0:1]
	v_pk_fma_f32 v[110:111], v[144:145], v[126:127], v[110:111] op_sel:[0,1,0] op_sel_hi:[1,1,1]
	s_nop 0
	v_pk_fma_f32 v[96:97], v[50:51], v[128:129], v[96:97] op_sel:[0,0,0] op_sel_hi:[1,0,1]
	v_pk_fma_f32 v[98:99], v[50:51], v[128:129], v[98:99] op_sel:[0,1,0] op_sel_hi:[1,1,1]
	v_pk_fma_f32 v[100:101], v[50:51], v[130:131], v[100:101] op_sel:[0,0,0] op_sel_hi:[1,0,1]
	v_pk_fma_f32 v[102:103], v[50:51], v[130:131], v[102:103] op_sel:[0,1,0] op_sel_hi:[1,1,1]
	v_pk_fma_f32 v[104:105], v[50:51], v[132:133], v[104:105] op_sel:[0,0,0] op_sel_hi:[1,0,1]
	v_pk_fma_f32 v[106:107], v[50:51], v[132:133], v[106:107] op_sel:[0,1,0] op_sel_hi:[1,1,1]
	v_pk_fma_f32 v[108:109], v[50:51], v[134:135], v[108:109] op_sel:[0,0,0] op_sel_hi:[1,0,1]
	v_pk_fma_f32 v[110:111], v[50:51], v[134:135], v[110:111] op_sel:[0,1,0] op_sel_hi:[1,1,1]
	v_pk_mul_f32 v[48:49], v[96:97], v[136:137] op_sel:[0,0] op_sel_hi:[1,0]
	v_pk_mul_f32 v[50:51], v[96:97], v[156:157] op_sel:[0,0] op_sel_hi:[1,0]
	v_pk_fma_f32 v[48:49], v[98:99], v[136:137], v[48:49] op_sel:[0,1,0] op_sel_hi:[1,1,1]
	v_pk_fma_f32 v[50:51], v[98:99], v[156:157], v[50:51] op_sel:[0,1,0] op_sel_hi:[1,1,1]
	v_pk_fma_f32 v[48:49], v[100:101], v[138:139], v[48:49] op_sel:[0,0,0] op_sel_hi:[1,0,1]
	v_pk_fma_f32 v[50:51], v[100:101], v[158:159], v[50:51] op_sel:[0,0,0] op_sel_hi:[1,0,1]
	v_pk_fma_f32 v[48:49], v[102:103], v[138:139], v[48:49] op_sel:[0,1,0] op_sel_hi:[1,1,1]
	v_pk_fma_f32 v[50:51], v[102:103], v[158:159], v[50:51] op_sel:[0,1,0] op_sel_hi:[1,1,1]
	v_pk_fma_f32 v[48:49], v[104:105], v[140:141], v[48:49] op_sel:[0,0,0] op_sel_hi:[1,0,1]
	v_pk_fma_f32 v[50:51], v[104:105], v[160:161], v[50:51] op_sel:[0,0,0] op_sel_hi:[1,0,1]
	v_pk_fma_f32 v[48:49], v[106:107], v[140:141], v[48:49] op_sel:[0,1,0] op_sel_hi:[1,1,1]
	v_pk_fma_f32 v[50:51], v[106:107], v[160:161], v[50:51] op_sel:[0,1,0] op_sel_hi:[1,1,1]
	v_pk_fma_f32 v[48:49], v[108:109], v[142:143], v[48:49] op_sel:[0,0,0] op_sel_hi:[1,0,1]
	v_pk_fma_f32 v[50:51], v[108:109], v[162:163], v[50:51] op_sel:[0,0,0] op_sel_hi:[1,0,1]
	v_pk_fma_f32 v[48:49], v[110:111], v[142:143], v[48:49] op_sel:[0,1,0] op_sel_hi:[1,1,1]
	v_pk_fma_f32 v[50:51], v[110:111], v[162:163], v[50:51] op_sel:[0,1,0] op_sel_hi:[1,1,1]
	s_waitcnt lgkmcnt(11)
; #define LAS __attribute__((address_space(3)))
; __device__ __forceinline__ float red8(float x) { x += dpp_mov<0xB1>(x); x += dpp_mov<0x4E>(x); x += dpp_mov<0x141>(x); return x; }
; __device__ __forceinline__ void scan_phase(const KP& P, LAS unsigned char* lds, const int tid, const int bx, const int G) {
;     ...
;             for (int s = 0; s < 32; ++s) {
;                 const LAS float* p = cb + s * 384;
;                 const f32x4 w0 = *(const LAS f32x4*)(p), w1 = *(const LAS f32x4*)(p + 4);
;                 const f32x4 k0 = *(const LAS f32x4*)(p + 64), k1 = *(const LAS f32x4*)(p + 68);
;                 const f32x4 a0 = *(const LAS f32x4*)(p + 128), a1 = *(const LAS f32x4*)(p + 132);
;                 const f32x4 b0 = *(const LAS f32x4*)(p + 192), b1 = *(const LAS f32x4*)(p + 196);
;                 const f32x4 r0 = *(const LAS f32x4*)(p + 256), r1 = *(const LAS f32x4*)(p + 260);
;                 const float vv = buf[(c & 1) * 12288 + s * 384 + 320 + v];
;                 f32x2 sa2 = S[0] * (f32x2){a0.x, a0.y};
;                 sa2 += S[1] * (f32x2){a0.z, a0.w}; sa2 += S[2] * (f32x2){a1.x, a1.y}; sa2 += S[3] * (f32x2){a1.z, a1.w};
;                 const float sa = red8(sa2.x + sa2.y);
;                 const f32x2 sav = {sa, sa}, vv2 = {vv, vv};
;                 S[0] = S[0] * (f32x2){w0.x, w0.y} + sav * (f32x2){b0.x, b0.y} + vv2 * (f32x2){k0.x, k0.y};
;                 S[1] = S[1] * (f32x2){w0.z, w0.w} + sav * (f32x2){b0.z, b0.w} + vv2 * (f32x2){k0.z, k0.w};
;                 S[2] = S[2] * (f32x2){w1.x, w1.y} + sav * (f32x2){b1.x, b1.y} + vv2 * (f32x2){k1.x, k1.y};
;                 S[3] = S[3] * (f32x2){w1.z, w1.w} + sav * (f32x2){b1.z, b1.w} + vv2 * (f32x2){k1.z, k1.w};
;                 f32x2 y2 = S[0] * (f32x2){r0.x, r0.y};
;                 y2 += S[1] * (f32x2){r0.z, r0.w}; y2 += S[2] * (f32x2){r1.x, r1.y}; y2 += S[3] * (f32x2){r1.z, r1.w};
;                 const float y = red8(y2.x + y2.y);
;                 if (kc == 0) ybuf[s * 64 + v] = y;
	ds_read_b128 v[120:123], v44 offset:46336
	ds_read_b128 v[124:127], v44 offset:46352
	ds_read_b128 v[128:131], v44 offset:46848
	ds_read_b128 v[132:135], v44 offset:46864
	ds_read_b128 v[136:139], v44 offset:47104
	ds_read_b128 v[140:143], v44 offset:47120
	ds_read_b64 v[144:145], v46 offset:46080
	ds_read_b128 v[156:159], v44 offset:48128
	ds_read_b128 v[160:163], v44 offset:48144
	v_add_f32_dpp v48, v48, v48 quad_perm:[1,0,3,2] row_mask:0xf bank_mask:0xf bound_ctrl:1
	v_add_f32_dpp v49, v49, v49 quad_perm:[1,0,3,2] row_mask:0xf bank_mask:0xf bound_ctrl:1
	v_add_f32_dpp v50, v50, v50 quad_perm:[1,0,3,2] row_mask:0xf bank_mask:0xf bound_ctrl:1
	v_add_f32_dpp v51, v51, v51 quad_perm:[1,0,3,2] row_mask:0xf bank_mask:0xf bound_ctrl:1
	v_pk_fma_f32 v[96:97], v[146:147], v[70:71], v[96:97] op_sel:[0,0,0] op_sel_hi:[1,0,1]
	v_pk_fma_f32 v[98:99], v[146:147], v[70:71], v[98:99] op_sel:[0,1,0] op_sel_hi:[1,1,1]
	v_pk_fma_f32 v[100:101], v[146:147], v[72:73], v[100:101] op_sel:[0,0,0] op_sel_hi:[1,0,1]
	v_add_f32_dpp v48, v48, v48 quad_perm:[2,3,0,1] row_mask:0xf bank_mask:0xf bound_ctrl:1
	v_add_f32_dpp v49, v49, v49 quad_perm:[2,3,0,1] row_mask:0xf bank_mask:0xf bound_ctrl:1
	v_add_f32_dpp v50, v50, v50 quad_perm:[2,3,0,1] row_mask:0xf bank_mask:0xf bound_ctrl:1
	v_add_f32_dpp v51, v51, v51 quad_perm:[2,3,0,1] row_mask:0xf bank_mask:0xf bound_ctrl:1
	v_pk_fma_f32 v[102:103], v[146:147], v[72:73], v[102:103] op_sel:[0,1,0] op_sel_hi:[1,1,1]
	v_pk_fma_f32 v[104:105], v[146:147], v[74:75], v[104:105] op_sel:[0,0,0] op_sel_hi:[1,0,1]
	v_pk_fma_f32 v[106:107], v[146:147], v[74:75], v[106:107] op_sel:[0,1,0] op_sel_hi:[1,1,1]
	v_add_f32_dpp v48, v48, v48 row_half_mirror row_mask:0xf bank_mask:0xf bound_ctrl:1
	v_add_f32_dpp v49, v49, v49 row_half_mirror row_mask:0xf bank_mask:0xf bound_ctrl:1
	v_add_f32_dpp v50, v50, v50 row_half_mirror row_mask:0xf bank_mask:0xf bound_ctrl:1
	v_add_f32_dpp v51, v51, v51 row_half_mirror row_mask:0xf bank_mask:0xf bound_ctrl:1
	v_pk_fma_f32 v[108:109], v[146:147], v[76:77], v[108:109] op_sel:[0,0,0] op_sel_hi:[1,0,1]
	s_mov_b64 exec, s[10:11]
	ds_write_b64 v45, v[48:49] offset:6912
	s_mov_b64 exec, s[0:1]
	v_pk_fma_f32 v[110:111], v[146:147], v[76:77], v[110:111] op_sel:[0,1,0] op_sel_hi:[1,1,1]
	s_nop 0
	v_pk_fma_f32 v[96:97], v[50:51], v[78:79], v[96:97] op_sel:[0,0,0] op_sel_hi:[1,0,1]
	v_pk_fma_f32 v[98:99], v[50:51], v[78:79], v[98:99] op_sel:[0,1,0] op_sel_hi:[1,1,1]
	v_pk_fma_f32 v[100:101], v[50:51], v[80:81], v[100:101] op_sel:[0,0,0] op_sel_hi:[1,0,1]
	v_pk_fma_f32 v[102:103], v[50:51], v[80:81], v[102:103] op_sel:[0,1,0] op_sel_hi:[1,1,1]
	v_pk_fma_f32 v[104:105], v[50:51], v[82:83], v[104:105] op_sel:[0,0,0] op_sel_hi:[1,0,1]
	v_pk_fma_f32 v[106:107], v[50:51], v[82:83], v[106:107] op_sel:[0,1,0] op_sel_hi:[1,1,1]
	v_pk_fma_f32 v[108:109], v[50:51], v[84:85], v[108:109] op_sel:[0,0,0] op_sel_hi:[1,0,1]
	v_pk_fma_f32 v[110:111], v[50:51], v[84:85], v[110:111] op_sel:[0,1,0] op_sel_hi:[1,1,1]
	v_pk_mul_f32 v[48:49], v[96:97], v[86:87] op_sel:[0,0] op_sel_hi:[1,0]
	v_pk_mul_f32 v[50:51], v[96:97], v[62:63] op_sel:[0,0] op_sel_hi:[1,0]
	v_pk_fma_f32 v[48:49], v[98:99], v[86:87], v[48:49] op_sel:[0,1,0] op_sel_hi:[1,1,1]
	v_pk_fma_f32 v[50:51], v[98:99], v[62:63], v[50:51] op_sel:[0,1,0] op_sel_hi:[1,1,1]
	v_pk_fma_f32 v[48:49], v[100:101], v[88:89], v[48:49] op_sel:[0,0,0] op_sel_hi:[1,0,1]
	v_pk_fma_f32 v[50:51], v[100:101], v[64:65], v[50:51] op_sel:[0,0,0] op_sel_hi:[1,0,1]
	v_pk_fma_f32 v[48:49], v[102:103], v[88:89], v[48:49] op_sel:[0,1,0] op_sel_hi:[1,1,1]
	v_pk_fma_f32 v[50:51], v[102:103], v[64:65], v[50:51] op_sel:[0,1,0] op_sel_hi:[1,1,1]
	v_pk_fma_f32 v[48:49], v[104:105], v[90:91], v[48:49] op_sel:[0,0,0] op_sel_hi:[1,0,1]
	v_pk_fma_f32 v[50:51], v[104:105], v[66:67], v[50:51] op_sel:[0,0,0] op_sel_hi:[1,0,1]
	v_pk_fma_f32 v[48:49], v[106:107], v[90:91], v[48:49] op_sel:[0,1,0] op_sel_hi:[1,1,1]
	v_pk_fma_f32 v[50:51], v[106:107], v[66:67], v[50:51] op_sel:[0,1,0] op_sel_hi:[1,1,1]
	v_pk_fma_f32 v[48:49], v[108:109], v[92:93], v[48:49] op_sel:[0,0,0] op_sel_hi:[1,0,1]
	v_pk_fma_f32 v[50:51], v[108:109], v[68:69], v[50:51] op_sel:[0,0,0] op_sel_hi:[1,0,1]
	v_pk_fma_f32 v[48:49], v[110:111], v[92:93], v[48:49] op_sel:[0,1,0] op_sel_hi:[1,1,1]
	v_pk_fma_f32 v[50:51], v[110:111], v[68:69], v[50:51] op_sel:[0,1,0] op_sel_hi:[1,1,1]
	s_waitcnt lgkmcnt(11)
; #define LAS __attribute__((address_space(3)))
; __device__ __forceinline__ float red8(float x) { x += dpp_mov<0xB1>(x); x += dpp_mov<0x4E>(x); x += dpp_mov<0x141>(x); return x; }
; __device__ __forceinline__ void scan_phase(const KP& P, LAS unsigned char* lds, const int tid, const int bx, const int G) {
;     ...
;             for (int s = 0; s < 32; ++s) {
;                 const LAS float* p = cb + s * 384;
;                 const f32x4 w0 = *(const LAS f32x4*)(p), w1 = *(const LAS f32x4*)(p + 4);
;                 const f32x4 k0 = *(const LAS f32x4*)(p + 64), k1 = *(const LAS f32x4*)(p + 68);
;                 const f32x4 a0 = *(const LAS f32x4*)(p + 128), a1 = *(const LAS f32x4*)(p + 132);
;                 const f32x4 b0 = *(const LAS f32x4*)(p + 192), b1 = *(const LAS f32x4*)(p + 196);
;                 const f32x4 r0 = *(const LAS f32x4*)(p + 256), r1 = *(const LAS f32x4*)(p + 260);
;                 const float vv = buf[(c & 1) * 12288 + s * 384 + 320 + v];
;                 f32x2 sa2 = S[0] * (f32x2){a0.x, a0.y};
;                 sa2 += S[1] * (f32x2){a0.z, a0.w}; sa2 += S[2] * (f32x2){a1.x, a1.y}; sa2 += S[3] * (f32x2){a1.z, a1.w};
;                 const float sa = red8(sa2.x + sa2.y);
;                 const f32x2 sav = {sa, sa}, vv2 = {vv, vv};
;                 S[0] = S[0] * (f32x2){w0.x, w0.y} + sav * (f32x2){b0.x, b0.y} + vv2 * (f32x2){k0.x, k0.y};
;                 S[1] = S[1] * (f32x2){w0.z, w0.w} + sav * (f32x2){b0.z, b0.w} + vv2 * (f32x2){k0.z, k0.w};
;                 S[2] = S[2] * (f32x2){w1.x, w1.y} + sav * (f32x2){b1.x, b1.y} + vv2 * (f32x2){k1.x, k1.y};
;                 S[3] = S[3] * (f32x2){w1.z, w1.w} + sav * (f32x2){b1.z, b1.w} + vv2 * (f32x2){k1.z, k1.w};
;                 f32x2 y2 = S[0] * (f32x2){r0.x, r0.y};
;                 y2 += S[1] * (f32x2){r0.z, r0.w}; y2 += S[2] * (f32x2){r1.x, r1.y}; y2 += S[3] * (f32x2){r1.z, r1.w};
;                 const float y = red8(y2.x + y2.y);
;                 if (kc == 0) ybuf[s * 64 + v] = y;
	ds_read_b128 v[70:73], v44 offset:47872
	ds_read_b128 v[74:77], v44 offset:47888
	ds_read_b128 v[78:81], v44 offset:48384
	ds_read_b128 v[82:85], v44 offset:48400
	ds_read_b128 v[86:89], v44 offset:48640
	ds_read_b128 v[90:93], v44 offset:48656
	ds_read_b64 v[146:147], v46 offset:47616
	v_add_f32_dpp v48, v48, v48 quad_perm:[1,0,3,2] row_mask:0xf bank_mask:0xf bound_ctrl:1
	v_add_f32_dpp v49, v49, v49 quad_perm:[1,0,3,2] row_mask:0xf bank_mask:0xf bound_ctrl:1
	v_add_f32_dpp v50, v50, v50 quad_perm:[1,0,3,2] row_mask:0xf bank_mask:0xf bound_ctrl:1
	v_add_f32_dpp v51, v51, v51 quad_perm:[1,0,3,2] row_mask:0xf bank_mask:0xf bound_ctrl:1
	v_pk_fma_f32 v[96:97], v[192:193], v[168:169], v[96:97] op_sel:[0,0,0] op_sel_hi:[1,0,1]
	v_pk_fma_f32 v[98:99], v[192:193], v[168:169], v[98:99] op_sel:[0,1,0] op_sel_hi:[1,1,1]
	v_pk_fma_f32 v[100:101], v[192:193], v[170:171], v[100:101] op_sel:[0,0,0] op_sel_hi:[1,0,1]
	v_add_f32_dpp v48, v48, v48 quad_perm:[2,3,0,1] row_mask:0xf bank_mask:0xf bound_ctrl:1
	v_add_f32_dpp v49, v49, v49 quad_perm:[2,3,0,1] row_mask:0xf bank_mask:0xf bound_ctrl:1
	v_add_f32_dpp v50, v50, v50 quad_perm:[2,3,0,1] row_mask:0xf bank_mask:0xf bound_ctrl:1
	v_add_f32_dpp v51, v51, v51 quad_perm:[2,3,0,1] row_mask:0xf bank_mask:0xf bound_ctrl:1
	v_pk_fma_f32 v[102:103], v[192:193], v[170:171], v[102:103] op_sel:[0,1,0] op_sel_hi:[1,1,1]
	v_pk_fma_f32 v[104:105], v[192:193], v[172:173], v[104:105] op_sel:[0,0,0] op_sel_hi:[1,0,1]
	v_pk_fma_f32 v[106:107], v[192:193], v[172:173], v[106:107] op_sel:[0,1,0] op_sel_hi:[1,1,1]
	v_add_f32_dpp v48, v48, v48 row_half_mirror row_mask:0xf bank_mask:0xf bound_ctrl:1
	v_add_f32_dpp v49, v49, v49 row_half_mirror row_mask:0xf bank_mask:0xf bound_ctrl:1
	v_add_f32_dpp v50, v50, v50 row_half_mirror row_mask:0xf bank_mask:0xf bound_ctrl:1
	v_add_f32_dpp v51, v51, v51 row_half_mirror row_mask:0xf bank_mask:0xf bound_ctrl:1
	v_pk_fma_f32 v[108:109], v[192:193], v[174:175], v[108:109] op_sel:[0,0,0] op_sel_hi:[1,0,1]
	s_mov_b64 exec, s[10:11]
	ds_write_b64 v45, v[48:49] offset:7168
	s_mov_b64 exec, s[0:1]
	v_pk_fma_f32 v[110:111], v[192:193], v[174:175], v[110:111] op_sel:[0,1,0] op_sel_hi:[1,1,1]
	s_nop 0
	v_pk_fma_f32 v[96:97], v[50:51], v[176:177], v[96:97] op_sel:[0,0,0] op_sel_hi:[1,0,1]
	v_pk_fma_f32 v[98:99], v[50:51], v[176:177], v[98:99] op_sel:[0,1,0] op_sel_hi:[1,1,1]
	v_pk_fma_f32 v[100:101], v[50:51], v[178:179], v[100:101] op_sel:[0,0,0] op_sel_hi:[1,0,1]
	v_pk_fma_f32 v[102:103], v[50:51], v[178:179], v[102:103] op_sel:[0,1,0] op_sel_hi:[1,1,1]
	v_pk_fma_f32 v[104:105], v[50:51], v[180:181], v[104:105] op_sel:[0,0,0] op_sel_hi:[1,0,1]
	v_pk_fma_f32 v[106:107], v[50:51], v[180:181], v[106:107] op_sel:[0,1,0] op_sel_hi:[1,1,1]
	v_pk_fma_f32 v[108:109], v[50:51], v[182:183], v[108:109] op_sel:[0,0,0] op_sel_hi:[1,0,1]
	v_pk_fma_f32 v[110:111], v[50:51], v[182:183], v[110:111] op_sel:[0,1,0] op_sel_hi:[1,1,1]
	v_pk_mul_f32 v[48:49], v[96:97], v[184:185] op_sel:[0,0] op_sel_hi:[1,0]
	v_pk_mul_f32 v[50:51], v[96:97], v[148:149] op_sel:[0,0] op_sel_hi:[1,0]
	v_pk_fma_f32 v[48:49], v[98:99], v[184:185], v[48:49] op_sel:[0,1,0] op_sel_hi:[1,1,1]
	v_pk_fma_f32 v[50:51], v[98:99], v[148:149], v[50:51] op_sel:[0,1,0] op_sel_hi:[1,1,1]
	v_pk_fma_f32 v[48:49], v[100:101], v[186:187], v[48:49] op_sel:[0,0,0] op_sel_hi:[1,0,1]
	v_pk_fma_f32 v[50:51], v[100:101], v[150:151], v[50:51] op_sel:[0,0,0] op_sel_hi:[1,0,1]
	v_pk_fma_f32 v[48:49], v[102:103], v[186:187], v[48:49] op_sel:[0,1,0] op_sel_hi:[1,1,1]
	v_pk_fma_f32 v[50:51], v[102:103], v[150:151], v[50:51] op_sel:[0,1,0] op_sel_hi:[1,1,1]
	v_pk_fma_f32 v[48:49], v[104:105], v[188:189], v[48:49] op_sel:[0,0,0] op_sel_hi:[1,0,1]
	v_pk_fma_f32 v[50:51], v[104:105], v[152:153], v[50:51] op_sel:[0,0,0] op_sel_hi:[1,0,1]
	v_pk_fma_f32 v[48:49], v[106:107], v[188:189], v[48:49] op_sel:[0,1,0] op_sel_hi:[1,1,1]
	v_pk_fma_f32 v[50:51], v[106:107], v[152:153], v[50:51] op_sel:[0,1,0] op_sel_hi:[1,1,1]
	v_pk_fma_f32 v[48:49], v[108:109], v[190:191], v[48:49] op_sel:[0,0,0] op_sel_hi:[1,0,1]
	v_pk_fma_f32 v[50:51], v[108:109], v[154:155], v[50:51] op_sel:[0,0,0] op_sel_hi:[1,0,1]
	v_pk_fma_f32 v[48:49], v[110:111], v[190:191], v[48:49] op_sel:[0,1,0] op_sel_hi:[1,1,1]
	v_pk_fma_f32 v[50:51], v[110:111], v[154:155], v[50:51] op_sel:[0,1,0] op_sel_hi:[1,1,1]
	s_waitcnt lgkmcnt(9)
; #define LAS __attribute__((address_space(3)))
; __device__ __forceinline__ float red8(float x) { x += dpp_mov<0xB1>(x); x += dpp_mov<0x4E>(x); x += dpp_mov<0x141>(x); return x; }
; __device__ __forceinline__ void scan_phase(const KP& P, LAS unsigned char* lds, const int tid, const int bx, const int G) {
;     ...
;             for (int s = 0; s < 32; ++s) {
;                 const LAS float* p = cb + s * 384;
;                 const f32x4 w0 = *(const LAS f32x4*)(p), w1 = *(const LAS f32x4*)(p + 4);
;                 const f32x4 k0 = *(const LAS f32x4*)(p + 64), k1 = *(const LAS f32x4*)(p + 68);
;                 const f32x4 a0 = *(const LAS f32x4*)(p + 128), a1 = *(const LAS f32x4*)(p + 132);
;                 const f32x4 b0 = *(const LAS f32x4*)(p + 192), b1 = *(const LAS f32x4*)(p + 196);
;                 const f32x4 r0 = *(const LAS f32x4*)(p + 256), r1 = *(const LAS f32x4*)(p + 260);
;                 const float vv = buf[(c & 1) * 12288 + s * 384 + 320 + v];
;                 f32x2 sa2 = S[0] * (f32x2){a0.x, a0.y};
;                 sa2 += S[1] * (f32x2){a0.z, a0.w}; sa2 += S[2] * (f32x2){a1.x, a1.y}; sa2 += S[3] * (f32x2){a1.z, a1.w};
;                 const float sa = red8(sa2.x + sa2.y);
;                 const f32x2 sav = {sa, sa}, vv2 = {vv, vv};
;                 S[0] = S[0] * (f32x2){w0.x, w0.y} + sav * (f32x2){b0.x, b0.y} + vv2 * (f32x2){k0.x, k0.y};
;                 S[1] = S[1] * (f32x2){w0.z, w0.w} + sav * (f32x2){b0.z, b0.w} + vv2 * (f32x2){k0.z, k0.w};
;                 S[2] = S[2] * (f32x2){w1.x, w1.y} + sav * (f32x2){b1.x, b1.y} + vv2 * (f32x2){k1.x, k1.y};
;                 S[3] = S[3] * (f32x2){w1.z, w1.w} + sav * (f32x2){b1.z, b1.w} + vv2 * (f32x2){k1.z, k1.w};
;                 f32x2 y2 = S[0] * (f32x2){r0.x, r0.y};
;                 y2 += S[1] * (f32x2){r0.z, r0.w}; y2 += S[2] * (f32x2){r1.x, r1.y}; y2 += S[3] * (f32x2){r1.z, r1.w};
;                 const float y = red8(y2.x + y2.y);
;                 if (kc == 0) ybuf[s * 64 + v] = y;
	s_nop 1
	v_add_f32_dpp v48, v48, v48 quad_perm:[1,0,3,2] row_mask:0xf bank_mask:0xf bound_ctrl:1
	v_add_f32_dpp v49, v49, v49 quad_perm:[1,0,3,2] row_mask:0xf bank_mask:0xf bound_ctrl:1
	v_add_f32_dpp v50, v50, v50 quad_perm:[1,0,3,2] row_mask:0xf bank_mask:0xf bound_ctrl:1
	v_add_f32_dpp v51, v51, v51 quad_perm:[1,0,3,2] row_mask:0xf bank_mask:0xf bound_ctrl:1
	v_pk_fma_f32 v[96:97], v[144:145], v[120:121], v[96:97] op_sel:[0,0,0] op_sel_hi:[1,0,1]
	v_pk_fma_f32 v[98:99], v[144:145], v[120:121], v[98:99] op_sel:[0,1,0] op_sel_hi:[1,1,1]
	v_pk_fma_f32 v[100:101], v[144:145], v[122:123], v[100:101] op_sel:[0,0,0] op_sel_hi:[1,0,1]
	v_add_f32_dpp v48, v48, v48 quad_perm:[2,3,0,1] row_mask:0xf bank_mask:0xf bound_ctrl:1
	v_add_f32_dpp v49, v49, v49 quad_perm:[2,3,0,1] row_mask:0xf bank_mask:0xf bound_ctrl:1
	v_add_f32_dpp v50, v50, v50 quad_perm:[2,3,0,1] row_mask:0xf bank_mask:0xf bound_ctrl:1
	v_add_f32_dpp v51, v51, v51 quad_perm:[2,3,0,1] row_mask:0xf bank_mask:0xf bound_ctrl:1
	v_pk_fma_f32 v[102:103], v[144:145], v[122:123], v[102:103] op_sel:[0,1,0] op_sel_hi:[1,1,1]
	v_pk_fma_f32 v[104:105], v[144:145], v[124:125], v[104:105] op_sel:[0,0,0] op_sel_hi:[1,0,1]
	v_pk_fma_f32 v[106:107], v[144:145], v[124:125], v[106:107] op_sel:[0,1,0] op_sel_hi:[1,1,1]
	v_add_f32_dpp v48, v48, v48 row_half_mirror row_mask:0xf bank_mask:0xf bound_ctrl:1
	v_add_f32_dpp v49, v49, v49 row_half_mirror row_mask:0xf bank_mask:0xf bound_ctrl:1
	v_add_f32_dpp v50, v50, v50 row_half_mirror row_mask:0xf bank_mask:0xf bound_ctrl:1
	v_add_f32_dpp v51, v51, v51 row_half_mirror row_mask:0xf bank_mask:0xf bound_ctrl:1
	v_pk_fma_f32 v[108:109], v[144:145], v[126:127], v[108:109] op_sel:[0,0,0] op_sel_hi:[1,0,1]
	s_mov_b64 exec, s[10:11]
	ds_write_b64 v45, v[48:49] offset:7424
	s_mov_b64 exec, s[0:1]
	v_pk_fma_f32 v[110:111], v[144:145], v[126:127], v[110:111] op_sel:[0,1,0] op_sel_hi:[1,1,1]
	s_nop 0
	v_pk_fma_f32 v[96:97], v[50:51], v[128:129], v[96:97] op_sel:[0,0,0] op_sel_hi:[1,0,1]
	v_pk_fma_f32 v[98:99], v[50:51], v[128:129], v[98:99] op_sel:[0,1,0] op_sel_hi:[1,1,1]
	v_pk_fma_f32 v[100:101], v[50:51], v[130:131], v[100:101] op_sel:[0,0,0] op_sel_hi:[1,0,1]
	v_pk_fma_f32 v[102:103], v[50:51], v[130:131], v[102:103] op_sel:[0,1,0] op_sel_hi:[1,1,1]
	v_pk_fma_f32 v[104:105], v[50:51], v[132:133], v[104:105] op_sel:[0,0,0] op_sel_hi:[1,0,1]
	v_pk_fma_f32 v[106:107], v[50:51], v[132:133], v[106:107] op_sel:[0,1,0] op_sel_hi:[1,1,1]
	v_pk_fma_f32 v[108:109], v[50:51], v[134:135], v[108:109] op_sel:[0,0,0] op_sel_hi:[1,0,1]
	v_pk_fma_f32 v[110:111], v[50:51], v[134:135], v[110:111] op_sel:[0,1,0] op_sel_hi:[1,1,1]
	v_pk_mul_f32 v[48:49], v[96:97], v[136:137] op_sel:[0,0] op_sel_hi:[1,0]
	v_pk_mul_f32 v[50:51], v[96:97], v[156:157] op_sel:[0,0] op_sel_hi:[1,0]
	v_pk_fma_f32 v[48:49], v[98:99], v[136:137], v[48:49] op_sel:[0,1,0] op_sel_hi:[1,1,1]
	v_pk_fma_f32 v[50:51], v[98:99], v[156:157], v[50:51] op_sel:[0,1,0] op_sel_hi:[1,1,1]
	v_pk_fma_f32 v[48:49], v[100:101], v[138:139], v[48:49] op_sel:[0,0,0] op_sel_hi:[1,0,1]
	v_pk_fma_f32 v[50:51], v[100:101], v[158:159], v[50:51] op_sel:[0,0,0] op_sel_hi:[1,0,1]
	v_pk_fma_f32 v[48:49], v[102:103], v[138:139], v[48:49] op_sel:[0,1,0] op_sel_hi:[1,1,1]
	v_pk_fma_f32 v[50:51], v[102:103], v[158:159], v[50:51] op_sel:[0,1,0] op_sel_hi:[1,1,1]
	v_pk_fma_f32 v[48:49], v[104:105], v[140:141], v[48:49] op_sel:[0,0,0] op_sel_hi:[1,0,1]
	v_pk_fma_f32 v[50:51], v[104:105], v[160:161], v[50:51] op_sel:[0,0,0] op_sel_hi:[1,0,1]
	v_pk_fma_f32 v[48:49], v[106:107], v[140:141], v[48:49] op_sel:[0,1,0] op_sel_hi:[1,1,1]
	v_pk_fma_f32 v[50:51], v[106:107], v[160:161], v[50:51] op_sel:[0,1,0] op_sel_hi:[1,1,1]
	v_pk_fma_f32 v[48:49], v[108:109], v[142:143], v[48:49] op_sel:[0,0,0] op_sel_hi:[1,0,1]
	v_pk_fma_f32 v[50:51], v[108:109], v[162:163], v[50:51] op_sel:[0,0,0] op_sel_hi:[1,0,1]
	v_pk_fma_f32 v[48:49], v[110:111], v[142:143], v[48:49] op_sel:[0,1,0] op_sel_hi:[1,1,1]
	v_pk_fma_f32 v[50:51], v[110:111], v[162:163], v[50:51] op_sel:[0,1,0] op_sel_hi:[1,1,1]
	s_waitcnt lgkmcnt(2)
; #define LAS __attribute__((address_space(3)))
; __device__ __forceinline__ float red8(float x) { x += dpp_mov<0xB1>(x); x += dpp_mov<0x4E>(x); x += dpp_mov<0x141>(x); return x; }
; __device__ __forceinline__ void scan_phase(const KP& P, LAS unsigned char* lds, const int tid, const int bx, const int G) {
;     ...
;             for (int s = 0; s < 32; ++s) {
;                 const LAS float* p = cb + s * 384;
;                 const f32x4 w0 = *(const LAS f32x4*)(p), w1 = *(const LAS f32x4*)(p + 4);
;                 const f32x4 k0 = *(const LAS f32x4*)(p + 64), k1 = *(const LAS f32x4*)(p + 68);
;                 const f32x4 a0 = *(const LAS f32x4*)(p + 128), a1 = *(const LAS f32x4*)(p + 132);
;                 const f32x4 b0 = *(const LAS f32x4*)(p + 192), b1 = *(const LAS f32x4*)(p + 196);
;                 const f32x4 r0 = *(const LAS f32x4*)(p + 256), r1 = *(const LAS f32x4*)(p + 260);
;                 const float vv = buf[(c & 1) * 12288 + s * 384 + 320 + v];
;                 f32x2 sa2 = S[0] * (f32x2){a0.x, a0.y};
;                 sa2 += S[1] * (f32x2){a0.z, a0.w}; sa2 += S[2] * (f32x2){a1.x, a1.y}; sa2 += S[3] * (f32x2){a1.z, a1.w};
;                 const float sa = red8(sa2.x + sa2.y);
;                 const f32x2 sav = {sa, sa}, vv2 = {vv, vv};
;                 S[0] = S[0] * (f32x2){w0.x, w0.y} + sav * (f32x2){b0.x, b0.y} + vv2 * (f32x2){k0.x, k0.y};
;                 S[1] = S[1] * (f32x2){w0.z, w0.w} + sav * (f32x2){b0.z, b0.w} + vv2 * (f32x2){k0.z, k0.w};
;                 S[2] = S[2] * (f32x2){w1.x, w1.y} + sav * (f32x2){b1.x, b1.y} + vv2 * (f32x2){k1.x, k1.y};
;                 S[3] = S[3] * (f32x2){w1.z, w1.w} + sav * (f32x2){b1.z, b1.w} + vv2 * (f32x2){k1.z, k1.w};
;                 f32x2 y2 = S[0] * (f32x2){r0.x, r0.y};
;                 y2 += S[1] * (f32x2){r0.z, r0.w}; y2 += S[2] * (f32x2){r1.x, r1.y}; y2 += S[3] * (f32x2){r1.z, r1.w};
;                 const float y = red8(y2.x + y2.y);
;                 if (kc == 0) ybuf[s * 64 + v] = y;
;             }
	s_nop 1
	v_add_f32_dpp v48, v48, v48 quad_perm:[1,0,3,2] row_mask:0xf bank_mask:0xf bound_ctrl:1
	v_add_f32_dpp v49, v49, v49 quad_perm:[1,0,3,2] row_mask:0xf bank_mask:0xf bound_ctrl:1
	v_add_f32_dpp v50, v50, v50 quad_perm:[1,0,3,2] row_mask:0xf bank_mask:0xf bound_ctrl:1
	v_add_f32_dpp v51, v51, v51 quad_perm:[1,0,3,2] row_mask:0xf bank_mask:0xf bound_ctrl:1
	v_pk_fma_f32 v[96:97], v[146:147], v[70:71], v[96:97] op_sel:[0,0,0] op_sel_hi:[1,0,1]
	v_pk_fma_f32 v[98:99], v[146:147], v[70:71], v[98:99] op_sel:[0,1,0] op_sel_hi:[1,1,1]
	v_pk_fma_f32 v[100:101], v[146:147], v[72:73], v[100:101] op_sel:[0,0,0] op_sel_hi:[1,0,1]
	v_add_f32_dpp v48, v48, v48 quad_perm:[2,3,0,1] row_mask:0xf bank_mask:0xf bound_ctrl:1
	v_add_f32_dpp v49, v49, v49 quad_perm:[2,3,0,1] row_mask:0xf bank_mask:0xf bound_ctrl:1
	v_add_f32_dpp v50, v50, v50 quad_perm:[2,3,0,1] row_mask:0xf bank_mask:0xf bound_ctrl:1
	v_add_f32_dpp v51, v51, v51 quad_perm:[2,3,0,1] row_mask:0xf bank_mask:0xf bound_ctrl:1
	v_pk_fma_f32 v[102:103], v[146:147], v[72:73], v[102:103] op_sel:[0,1,0] op_sel_hi:[1,1,1]
	v_pk_fma_f32 v[104:105], v[146:147], v[74:75], v[104:105] op_sel:[0,0,0] op_sel_hi:[1,0,1]
	v_pk_fma_f32 v[106:107], v[146:147], v[74:75], v[106:107] op_sel:[0,1,0] op_sel_hi:[1,1,1]
	v_add_f32_dpp v48, v48, v48 row_half_mirror row_mask:0xf bank_mask:0xf bound_ctrl:1
	v_add_f32_dpp v49, v49, v49 row_half_mirror row_mask:0xf bank_mask:0xf bound_ctrl:1
	v_add_f32_dpp v50, v50, v50 row_half_mirror row_mask:0xf bank_mask:0xf bound_ctrl:1
	v_add_f32_dpp v51, v51, v51 row_half_mirror row_mask:0xf bank_mask:0xf bound_ctrl:1
	v_pk_fma_f32 v[108:109], v[146:147], v[76:77], v[108:109] op_sel:[0,0,0] op_sel_hi:[1,0,1]
	s_mov_b64 exec, s[10:11]
	ds_write_b64 v45, v[48:49] offset:7680
	s_mov_b64 exec, s[0:1]
	v_pk_fma_f32 v[110:111], v[146:147], v[76:77], v[110:111] op_sel:[0,1,0] op_sel_hi:[1,1,1]
	s_nop 0
	v_pk_fma_f32 v[96:97], v[50:51], v[78:79], v[96:97] op_sel:[0,0,0] op_sel_hi:[1,0,1]
	v_pk_fma_f32 v[98:99], v[50:51], v[78:79], v[98:99] op_sel:[0,1,0] op_sel_hi:[1,1,1]
	v_pk_fma_f32 v[100:101], v[50:51], v[80:81], v[100:101] op_sel:[0,0,0] op_sel_hi:[1,0,1]
	v_pk_fma_f32 v[102:103], v[50:51], v[80:81], v[102:103] op_sel:[0,1,0] op_sel_hi:[1,1,1]
	v_pk_fma_f32 v[104:105], v[50:51], v[82:83], v[104:105] op_sel:[0,0,0] op_sel_hi:[1,0,1]
	v_pk_fma_f32 v[106:107], v[50:51], v[82:83], v[106:107] op_sel:[0,1,0] op_sel_hi:[1,1,1]
	v_pk_fma_f32 v[108:109], v[50:51], v[84:85], v[108:109] op_sel:[0,0,0] op_sel_hi:[1,0,1]
	v_pk_fma_f32 v[110:111], v[50:51], v[84:85], v[110:111] op_sel:[0,1,0] op_sel_hi:[1,1,1]
	v_pk_mul_f32 v[48:49], v[96:97], v[86:87] op_sel:[0,0] op_sel_hi:[1,0]
	s_nop 0
	v_pk_fma_f32 v[48:49], v[98:99], v[86:87], v[48:49] op_sel:[0,1,0] op_sel_hi:[1,1,1]
	s_nop 0
	v_pk_fma_f32 v[48:49], v[100:101], v[88:89], v[48:49] op_sel:[0,0,0] op_sel_hi:[1,0,1]
	s_nop 0
	v_pk_fma_f32 v[48:49], v[102:103], v[88:89], v[48:49] op_sel:[0,1,0] op_sel_hi:[1,1,1]
	s_nop 0
	v_pk_fma_f32 v[48:49], v[104:105], v[90:91], v[48:49] op_sel:[0,0,0] op_sel_hi:[1,0,1]
	s_nop 0
	v_pk_fma_f32 v[48:49], v[106:107], v[90:91], v[48:49] op_sel:[0,1,0] op_sel_hi:[1,1,1]
	s_nop 0
	v_pk_fma_f32 v[48:49], v[108:109], v[92:93], v[48:49] op_sel:[0,0,0] op_sel_hi:[1,0,1]
	s_nop 0
	v_pk_fma_f32 v[48:49], v[110:111], v[92:93], v[48:49] op_sel:[0,1,0] op_sel_hi:[1,1,1]
	s_nop 0
	v_pk_mul_f32 v[96:97], v[96:97], v[112:113] op_sel:[0,0] op_sel_hi:[1,0]
	v_pk_mul_f32 v[98:99], v[98:99], v[112:113] op_sel:[0,1] op_sel_hi:[1,1]
	v_pk_mul_f32 v[100:101], v[100:101], v[114:115] op_sel:[0,0] op_sel_hi:[1,0]
	v_pk_mul_f32 v[102:103], v[102:103], v[114:115] op_sel:[0,1] op_sel_hi:[1,1]
	v_pk_mul_f32 v[104:105], v[104:105], v[116:117] op_sel:[0,0] op_sel_hi:[1,0]
	v_pk_mul_f32 v[106:107], v[106:107], v[116:117] op_sel:[0,1] op_sel_hi:[1,1]
	v_pk_mul_f32 v[108:109], v[108:109], v[118:119] op_sel:[0,0] op_sel_hi:[1,0]
	v_pk_mul_f32 v[110:111], v[110:111], v[118:119] op_sel:[0,1] op_sel_hi:[1,1]
	v_add_f32_dpp v48, v48, v48 quad_perm:[1,0,3,2] row_mask:0xf bank_mask:0xf bound_ctrl:1
	v_add_f32_dpp v49, v49, v49 quad_perm:[1,0,3,2] row_mask:0xf bank_mask:0xf bound_ctrl:1
	s_nop 1
	v_add_f32_dpp v48, v48, v48 quad_perm:[2,3,0,1] row_mask:0xf bank_mask:0xf bound_ctrl:1
	v_add_f32_dpp v49, v49, v49 quad_perm:[2,3,0,1] row_mask:0xf bank_mask:0xf bound_ctrl:1
	s_nop 1
	v_add_f32_dpp v48, v48, v48 row_half_mirror row_mask:0xf bank_mask:0xf bound_ctrl:1
	v_add_f32_dpp v49, v49, v49 row_half_mirror row_mask:0xf bank_mask:0xf bound_ctrl:1
	s_nop 1
	s_mov_b64 exec, s[10:11]
	ds_write_b64 v45, v[48:49] offset:7936
	s_mov_b64 exec, s[0:1]
